# baseline (speedup 1.0000x reference)
.LBB0_477:
	s_ashr_i32 s7, s6, 31
	s_lshl_b64 s[4:5], s[6:7], 18
	v_mov_b32_e32 v119, v170
	s_add_u32 s4, s17, s4
	s_addc_u32 s5, s18, s5
	v_ashrrev_i32_e32 v18, 3, v119
	s_lshl_b32 s6, s16, 7
	v_lshlrev_b32_e32 v24, 3, v119
	v_add_u32_e32 v20, 32, v18
	s_and_b32 s12, s6, 0x180
	v_and_b32_e32 v1, 56, v24
	v_ashrrev_i32_e32 v19, 31, v18
	v_ashrrev_i32_e32 v21, 31, v20
	s_add_u32 s6, s4, s12
	v_lshlrev_b32_e32 v25, 1, v1
	v_lshlrev_b64 v[2:3], 10, v[18:19]
	v_lshlrev_b64 v[6:7], 10, v[20:21]
	s_addc_u32 s7, s5, 0
	s_lshl_b64 s[8:9], s[8:9], 16
	v_or_b32_e32 v2, v2, v25
	v_or_b32_e32 v6, v6, v25
	s_add_u32 s4, s36, s8
	v_lshl_add_u64 v[90:91], s[6:7], 0, v[2:3]
	v_lshl_add_u64 v[14:15], s[6:7], 0, v[6:7]
	v_ashrrev_i32_e32 v136, 1, v119
	flat_load_dwordx4 v[2:5], v[90:91] offset:512
	flat_load_dwordx4 v[6:9], v[14:15] offset:512
	flat_load_dwordx4 v[10:13], v[90:91]
	s_nop 0
	flat_load_dwordx4 v[14:17], v[14:15]
	s_addc_u32 s5, s37, s9
	v_bfi_b32 v22, s1, v136, v119
	s_add_u32 s12, s4, s12
	v_ashrrev_i32_e32 v23, 31, v22
	s_addc_u32 s13, s5, 0
	v_bfe_u32 v1, v119, 5, 1
	v_lshlrev_b64 v[22:23], 9, v[22:23]
	v_lshl_add_u64 v[22:23], s[12:13], 0, v[22:23]
	v_lshlrev_b32_e32 v114, 4, v1
	v_mov_b32_e32 v115, v0
	v_lshl_add_u64 v[22:23], v[22:23], 0, v[114:115]
	flat_load_dwordx4 v[74:77], v[22:23]
	flat_load_dwordx4 v[70:73], v[22:23] offset:32
	flat_load_dwordx4 v[66:69], v[22:23] offset:64
	flat_load_dwordx4 v[78:81], v[22:23] offset:96
	v_and_b32_e32 v19, 0x1fffff0, v18
	v_lshlrev_b32_e32 v21, 1, v18
	v_lshrrev_b32_e32 v26, 1, v18
	v_and_b32_e32 v27, 3, v18
	v_lshlrev_b32_e32 v28, 7, v18
	v_lshlrev_b32_e32 v18, 4, v18
	v_and_or_b32 v19, v21, 8, v19
	v_and_or_b32 v21, v26, 4, v27
	v_and_b32_e32 v26, 0x1fffff0, v20
	v_lshlrev_b32_e32 v27, 1, v20
	v_bfe_u32 v24, v24, 5, 1
	v_and_b32_e32 v18, 0x70, v18
	v_lshlrev_b32_e32 v20, 7, v20
	v_lshrrev_b32_e32 v19, 2, v19
	v_and_or_b32 v26, v27, 8, v26
	v_and_b32_e32 v115, 31, v119
	v_lshlrev_b32_e32 v82, 4, v119
	v_bitop3_b32 v131, v25, v28, v18 bitop3:0xde
	v_bitop3_b32 v132, v25, v20, v18 bitop3:0xde
	v_or_b32_e32 v18, v19, v24
	v_lshrrev_b32_e32 v19, 2, v26
	v_lshlrev_b32_e32 v54, 7, v115
	v_and_b32_e32 v55, 0x70, v82
	v_lshlrev_b32_e32 v21, 6, v21
	v_and_b32_e32 v29, 48, v25
	v_lshlrev_b32_e32 v18, 9, v18
	v_or_b32_e32 v19, v19, v24
	v_bitop3_b32 v124, v114, v54, v55 bitop3:0xde
	v_or3_b32 v133, v18, v21, v29
	v_lshlrev_b32_e32 v18, 9, v19
	v_or3_b32 v134, v18, v21, v29
	s_waitcnt vmcnt(0)
	v_or_b32_e32 v22, 32, v114
	v_bitop3_b32 v125, v22, v54, v55 bitop3:0xde
	s_mov_b32 s6, 0x10000
	v_add_co_u32_e32 v50, vcc, s6, v90
	s_mov_b32 s7, 0x18000
	s_nop 0
	v_addc_co_u32_e32 v51, vcc, 0, v91, vcc
	s_mov_b64 s[4:5], 0x18000
	v_add_co_u32_e32 v52, vcc, s7, v90
	v_lshl_add_u64 v[46:47], v[90:91], 0, s[4:5]
	s_nop 0
	v_addc_co_u32_e32 v53, vcc, 0, v91, vcc
	s_waitcnt vmcnt(0) lgkmcnt(0)
	ds_write_b128 v133, v[2:5]
	ds_write_b128 v134, v[6:9]
	ds_write_b128 v131, v[10:13] offset:16384
	ds_write_b128 v132, v[14:17] offset:16384
	s_waitcnt lgkmcnt(0)
	s_barrier
	ds_read_b128 v[2:5], v124 offset:16384
	ds_read_b128 v[18:21], v124 offset:20480
	ds_read_b128 v[34:37], v125 offset:16384
	ds_read_b128 v[38:41], v125 offset:20480
	s_waitcnt lgkmcnt(3)
	v_mfma_f32_32x32x16_bf16 v[2:17], v[2:5], v[74:77], 0
	s_mov_b32 s4, 0x28000
	v_add_co_u32_e32 v60, vcc, s4, v90
	s_mov_b64 s[4:5], 0x20000
	s_nop 0
	v_addc_co_u32_e32 v61, vcc, 0, v91, vcc
	v_lshl_add_u64 v[62:63], v[90:91], 0, s[4:5]
	s_waitcnt lgkmcnt(2)
	v_mfma_f32_32x32x16_bf16 v[18:33], v[18:21], v[74:77], 0
	s_mov_b32 s4, 0x20000
	v_lshl_add_u64 v[42:43], v[90:91], 0, s[48:49]
	v_add_co_u32_e32 v64, vcc, s4, v90
	v_lshl_add_u64 v[58:59], v[90:91], 0, s[50:51]
	s_nop 0
	v_addc_co_u32_e32 v65, vcc, 0, v91, vcc
	s_waitcnt lgkmcnt(1)
	v_mfma_f32_32x32x16_bf16 v[2:17], v[34:37], v[70:73], v[2:17]
	v_or_b32_e32 v34, 64, v114
	v_bitop3_b32 v130, v34, v54, v55 bitop3:0xde
	ds_read_b128 v[34:37], v130 offset:16384
	v_and_b32_e32 v121, 63, v119
	s_waitcnt lgkmcnt(1)
	v_mfma_f32_32x32x16_bf16 v[18:33], v[38:41], v[70:73], v[18:33]
	ds_read_b128 v[38:41], v130 offset:20480
	flat_load_dwordx4 v[42:45], v[42:43] offset:512
	s_nop 0
	flat_load_dwordx4 v[46:49], v[46:47] offset:512
	s_waitcnt lgkmcnt(0)
	v_mfma_f32_32x32x16_bf16 v[18:33], v[38:41], v[66:69], v[18:33]
	v_or_b32_e32 v38, 0x60, v114
	v_bitop3_b32 v135, v38, v54, v55 bitop3:0xde
	v_mfma_f32_32x32x16_bf16 v[2:17], v[34:37], v[66:69], v[2:17]
	flat_load_dwordx4 v[34:37], v[50:51]
	s_nop 0
	flat_load_dwordx4 v[50:53], v[52:53]
	ds_read_b128 v[38:41], v135 offset:16384
	ds_read_b128 v[54:57], v135 offset:20480
	flat_load_dwordx4 v[98:101], v[60:61]
	flat_load_dwordx4 v[106:109], v[58:59] offset:512
	flat_load_dwordx4 v[102:105], v[64:65]
	flat_load_dwordx4 v[110:113], v[62:63] offset:512
	s_waitcnt vmcnt(4)
	s_waitcnt vmcnt(0)
	ds_write_b128 v133, v[42:45] offset:8192
	ds_write_b128 v134, v[46:49] offset:8192
	s_waitcnt lgkmcnt(0)
	ds_write_b128 v131, v[34:37] offset:24576
	ds_write_b128 v132, v[50:53] offset:24576
	v_mfma_f32_32x32x16_bf16 v[2:17], v[38:41], v[78:81], v[2:17]
	v_lshlrev_b32_e32 v38, 3, v121
	v_and_b32_e32 v39, 0xc0, v82
	v_lshlrev_b32_e32 v40, 1, v119
	v_and_or_b32 v39, v38, 24, v39
	v_and_b32_e32 v40, 32, v40
	v_and_b32_e32 v38, 0x100, v38
	v_or3_b32 v127, v39, v40, v38
	s_nop 4
	v_max_f32_e32 v38, v3, v3
	v_max_f32_e32 v39, v2, v2
	v_mfma_f32_32x32x16_bf16 v[18:33], v[54:57], v[78:81], v[18:33]
	v_max_f32_e32 v38, v39, v38
	v_max3_f32 v38, v38, v4, v5
	v_max3_f32 v38, v38, v6, v7
	v_max3_f32 v38, v38, v8, v9
	v_max3_f32 v38, v38, v10, v11
	v_max3_f32 v38, v38, v12, v13
	v_max3_f32 v38, v38, v14, v15
	v_max3_f32 v38, v38, v16, v17
	s_nop 3
	v_max3_f32 v38, v38, v18, v19
	v_max3_f32 v38, v38, v20, v21
	v_max3_f32 v38, v38, v22, v23
	v_max3_f32 v38, v38, v24, v25
	v_max3_f32 v38, v38, v26, v27
	v_max3_f32 v38, v38, v28, v29
	v_max3_f32 v38, v38, v30, v31
	v_max3_f32 v38, v38, v32, v33
	v_mov_b32_e32 v39, v38
	s_nop 1
	v_permlane32_swap_b32_e32 v38, v39
	v_max_f32_e32 v39, v39, v39
	v_max_f32_e32 v38, v38, v38
	v_max_f32_e32 v38, v38, v39
	v_add_f32_e32 v39, 0x7149f2ca, v38
	v_cmp_ge_f32_e32 vcc, s0, v39
	s_cmp_eq_u64 vcc, exec
	v_max_f32_e32 v137, 0xf149f2ca, v38
	s_cselect_b64 s[6:7], -1, 0
	v_cndmask_b32_e64 v118, v137, v178, s[6:7]
	v_sub_f32_e32 v2, v2, v118
	v_sub_f32_e32 v3, v3, v118
	v_sub_f32_e32 v34, v18, v118
	v_sub_f32_e32 v35, v19, v118
	v_exp_f32_e32 v88, v2
	v_exp_f32_e32 v89, v3
	v_sub_f32_e32 v2, v4, v118
	v_sub_f32_e32 v3, v5, v118
	v_sub_f32_e32 v36, v20, v118
	v_sub_f32_e32 v37, v21, v118
	v_exp_f32_e32 v92, v2
	v_exp_f32_e32 v93, v3
	v_sub_f32_e32 v2, v6, v118
	v_sub_f32_e32 v3, v7, v118
	v_sub_f32_e32 v82, v22, v118
	v_sub_f32_e32 v83, v23, v118
	v_exp_f32_e32 v94, v2
	v_exp_f32_e32 v95, v3
	v_sub_f32_e32 v2, v8, v118
	v_sub_f32_e32 v3, v9, v118
	v_sub_f32_e32 v84, v24, v118
	v_sub_f32_e32 v85, v25, v118
	v_exp_f32_e32 v96, v2
	v_exp_f32_e32 v97, v3
	v_sub_f32_e32 v2, v10, v118
	v_sub_f32_e32 v3, v11, v118
	v_sub_f32_e32 v86, v26, v118
	v_sub_f32_e32 v87, v27, v118
	v_exp_f32_e32 v122, v2
	v_exp_f32_e32 v123, v3
	v_sub_f32_e32 v2, v12, v118
	v_sub_f32_e32 v3, v13, v118
	v_sub_f32_e32 v116, v28, v118
	v_sub_f32_e32 v117, v29, v118
	v_exp_f32_e32 v128, v2
	v_exp_f32_e32 v129, v3
	v_sub_f32_e32 v2, v14, v118
	v_sub_f32_e32 v3, v15, v118
	v_sub_f32_e32 v30, v30, v118
	v_sub_f32_e32 v31, v31, v118
	v_exp_f32_e32 v140, v2
	v_exp_f32_e32 v141, v3
	v_sub_f32_e32 v2, v16, v118
	v_sub_f32_e32 v3, v17, v118
	v_sub_f32_e32 v32, v32, v118
	v_sub_f32_e32 v33, v33, v118
	s_waitcnt lgkmcnt(0)
	s_barrier
	v_exp_f32_e32 v142, v2
	v_exp_f32_e32 v143, v3
	ds_read_b128 v[2:5], v124 offset:24576
	ds_read_b128 v[6:9], v124 offset:28672
	ds_read_b128 v[10:13], v125 offset:24576
	ds_read_b128 v[14:17], v125 offset:28672
	ds_read_b128 v[18:21], v130 offset:24576
	ds_read_b128 v[22:25], v130 offset:28672
	s_waitcnt lgkmcnt(5)
	v_mfma_f32_32x32x16_bf16 v[50:65], v[2:5], v[74:77], 0
	v_exp_f32_e32 v144, v34
	v_exp_f32_e32 v145, v35
	v_exp_f32_e32 v154, v36
	v_exp_f32_e32 v155, v37
	ds_read_b128 v[2:5], v135 offset:24576
	ds_read_b128 v[26:29], v135 offset:28672
	v_exp_f32_e32 v82, v82
	v_exp_f32_e32 v83, v83
	s_waitcnt lgkmcnt(6)
	v_mfma_f32_32x32x16_bf16 v[34:49], v[6:9], v[74:77], 0
	v_exp_f32_e32 v6, v84
	v_exp_f32_e32 v7, v85
	v_exp_f32_e32 v8, v86
	v_exp_f32_e32 v9, v87
	v_exp_f32_e32 v84, v116
	v_exp_f32_e32 v85, v117
	v_cvt_pk_bf16_f32 v138, v122, v123
	s_waitcnt lgkmcnt(5)
	v_mfma_f32_32x32x16_bf16 v[50:65], v[10:13], v[70:73], v[50:65]
	v_exp_f32_e32 v10, v30
	v_exp_f32_e32 v11, v31
	v_add_f32_e32 v30, 0, v88
	v_add_f32_e32 v31, 0, v89
	v_exp_f32_e32 v12, v32
	v_add_f32_e32 v30, v92, v30
	v_add_f32_e32 v31, v93, v31
	v_exp_f32_e32 v13, v33
	v_add_f32_e32 v30, v94, v30
	v_add_f32_e32 v31, v95, v31
	s_waitcnt lgkmcnt(4)
	v_mfma_f32_32x32x16_bf16 v[34:49], v[14:17], v[70:73], v[34:49]
	v_add_f32_e64 v14, v96, v30
	v_add_f32_e64 v15, v97, v31
	v_cvt_pk_bf16_f32 v139, v128, v129
	v_cvt_pk_bf16_f32 v156, v10, v11
	v_cvt_pk_bf16_f32 v157, v12, v13
	v_add_f32_e64 v14, v122, v14
	v_add_f32_e64 v15, v123, v15
	s_waitcnt lgkmcnt(3)
	v_mfma_f32_32x32x16_bf16 v[50:65], v[18:21], v[66:69], v[50:65]
	v_add_f32_e64 v14, v128, v14
	v_add_f32_e64 v15, v129, v15
	v_cvt_pk_bf16_f32 v18, v88, v89
	v_cvt_pk_bf16_f32 v19, v92, v93
	v_cvt_pk_bf16_f32 v20, v94, v95
	v_cvt_pk_bf16_f32 v21, v96, v97
	v_add_f32_e64 v14, v140, v14
	v_add_f32_e64 v15, v141, v15
	s_waitcnt lgkmcnt(2)
	v_mfma_f32_32x32x16_bf16 v[34:49], v[22:25], v[66:69], v[34:49]
	v_add_f32_e64 v14, v142, v14
	v_add_f32_e64 v15, v143, v15
	v_cvt_pk_bf16_f32 v140, v140, v141
	v_permlane32_swap_b32_e32 v18, v20
	v_add_f32_e64 v14, v144, v14
	v_add_f32_e64 v15, v145, v15
	v_permlane32_swap_b32_e32 v19, v21
	v_add_f32_e32 v14, v154, v14
	v_add_f32_e32 v15, v155, v15
	s_waitcnt lgkmcnt(1)
	v_mfma_f32_32x32x16_bf16 v[50:65], v[2:5], v[78:81], v[50:65]
	v_add_f32_e64 v14, v82, v14
	v_add_f32_e64 v15, v83, v15
	v_cvt_pk_bf16_f32 v141, v142, v143
	v_permlane32_swap_b32_e32 v138, v140
	v_add_f32_e64 v14, v6, v14
	v_add_f32_e64 v15, v7, v15
	v_cvt_pk_bf16_f32 v142, v144, v145
	v_cvt_pk_bf16_f32 v143, v154, v155
	s_waitcnt lgkmcnt(0)
	v_mfma_f32_32x32x16_bf16 v[34:49], v[26:29], v[78:81], v[34:49]
	v_add_f32_e64 v14, v8, v14
	v_add_f32_e64 v15, v9, v15
	v_cvt_pk_bf16_f32 v144, v82, v83
	v_cvt_pk_bf16_f32 v145, v6, v7
	v_cvt_pk_bf16_f32 v154, v8, v9
	v_cvt_pk_bf16_f32 v155, v84, v85
	v_permlane32_swap_b32_e32 v139, v141
	v_add_f32_e64 v14, v84, v14
	v_add_f32_e64 v15, v85, v15
	v_permlane32_swap_b32_e32 v142, v144
	v_add_f32_e32 v14, v10, v14
	v_add_f32_e32 v15, v11, v15
	v_permlane32_swap_b32_e32 v143, v145
	v_add_f32_e32 v14, v12, v14
	v_add_f32_e32 v15, v13, v15
	v_permlane32_swap_b32_e32 v154, v156
	v_add_f32_e32 v116, v14, v15
	v_add_f32_e32 v117, v15, v14
	v_permlane32_swap_b32_e32 v155, v157
	v_mov_b32_e32 v117, v116
	s_nop 1
	v_permlane32_swap_b32_e32 v116, v117
	s_mov_b64 s[4:5], 0x30000
	v_lshl_add_u64 v[2:3], v[90:91], 0, s[4:5]
	s_mov_b64 s[4:5], 0x38000
	v_lshl_add_u64 v[4:5], v[90:91], 0, s[4:5]
	s_mov_b32 s4, 0x30000
	flat_load_dwordx4 v[82:85], v[2:3] offset:512
	flat_load_dwordx4 v[86:89], v[4:5] offset:512
	v_add_co_u32_e32 v2, vcc, s4, v90
	s_mov_b32 s4, 0x38000
	s_nop 0
	v_addc_co_u32_e32 v3, vcc, 0, v91, vcc
	v_add_co_u32_e32 v4, vcc, s4, v90
	s_nop 1
	v_addc_co_u32_e32 v5, vcc, 0, v91, vcc
	flat_load_dwordx4 v[90:93], v[2:3]
	flat_load_dwordx4 v[94:97], v[4:5]
	ds_read_b64_tr_b16 v[2:3], v127 offset:0
	ds_read_b64_tr_b16 v[4:5], v127 offset:0x400
	ds_read_b64_tr_b16 v[22:23], v127 offset:0x800
	ds_read_b64_tr_b16 v[24:25], v127 offset:0xc00
	ds_read_b64_tr_b16 v[26:27], v127 offset:0x1000
	ds_read_b64_tr_b16 v[28:29], v127 offset:0x1400
	ds_read_b64_tr_b16 v[30:31], v127 offset:0x1800
	ds_read_b64_tr_b16 v[32:33], v127 offset:0x1c00
	s_waitcnt lgkmcnt(0)
	s_nop 0
	v_mfma_f32_32x32x16_bf16 v[2:17], v[18:21], v[2:5], 0
	v_mfma_f32_32x32x16_bf16 v[2:17], v[138:141], v[22:25], v[2:17]
	ds_read_b64_tr_b16 v[22:23], v127 offset:0x200
	ds_read_b64_tr_b16 v[24:25], v127 offset:0x600
	ds_read_b64_tr_b16 v[158:159], v127 offset:0xa00
	ds_read_b64_tr_b16 v[160:161], v127 offset:0xe00
	ds_read_b64_tr_b16 v[162:163], v127 offset:0x1200
	ds_read_b64_tr_b16 v[164:165], v127 offset:0x1600
	ds_read_b64_tr_b16 v[166:167], v127 offset:0x1a00
	v_mfma_f32_32x32x16_bf16 v[2:17], v[142:145], v[26:29], v[2:17]
	ds_read_b64_tr_b16 v[168:169], v127 offset:0x1e00
	s_waitcnt lgkmcnt(0)
	v_mfma_f32_32x32x16_bf16 v[2:17], v[154:157], v[30:33], v[2:17]
	v_max_f32_e32 v26, v51, v51
	v_max_f32_e32 v27, v50, v50
	v_max_f32_e32 v26, v27, v26
	v_max3_f32 v26, v26, v52, v53
	v_max3_f32 v120, v26, v54, v55
	v_mfma_f32_32x32x16_bf16 v[18:33], v[18:21], v[22:25], 0
	v_max3_f32 v120, v120, v56, v57
	v_max3_f32 v120, v120, v58, v59
	v_max3_f32 v120, v120, v60, v61
	v_max3_f32 v120, v120, v62, v63
	v_max3_f32 v120, v120, v64, v65
	v_max3_f32 v120, v120, v34, v35
	v_max3_f32 v120, v120, v36, v37
	v_mfma_f32_32x32x16_bf16 v[18:33], v[138:141], v[158:161], v[18:33]
	v_max3_f32 v120, v120, v38, v39
	v_max3_f32 v120, v120, v40, v41
	v_max3_f32 v120, v120, v42, v43
	v_max3_f32 v120, v120, v44, v45
	v_max3_f32 v120, v120, v46, v47
	v_max3_f32 v120, v120, v48, v49
	v_mov_b32_e32 v122, v120
	v_mfma_f32_32x32x16_bf16 v[18:33], v[142:145], v[162:165], v[18:33]
	s_nop 0
	v_permlane32_swap_b32_e32 v120, v122
	v_max_f32_e32 v122, v122, v122
	v_max_f32_e32 v120, v120, v120
	v_max_f32_e32 v122, v120, v122
	v_sub_f32_e32 v120, v122, v118
	v_cmp_ge_f32_e32 vcc, s0, v120
	v_mfma_f32_32x32x16_bf16 v[18:33], v[154:157], v[166:169], v[18:33]
	s_cmp_lg_u64 vcc, exec
	s_mov_b64 s[8:9], -1
	v_mov_b32_e32 v120, v118
	s_cbranch_scc1 .LBB0_500
	s_andn2_b64 vcc, exec, s[8:9]
	s_cbranch_vccnz .LBB0_480

.LBB0_484:
	v_mov_b32_e32 v121, v120
	v_sub_f32_e32 v50, v50, v120
	v_sub_f32_e32 v51, v51, v120
	v_and_b32_e32 v98, 0xffffffe0, v136
	v_exp_f32_e32 v110, v50
	v_exp_f32_e32 v111, v51
	v_sub_f32_e32 v50, v52, v120
	v_sub_f32_e32 v51, v53, v120
	v_sub_f32_e32 v100, v34, v120
	v_sub_f32_e32 v101, v35, v121
	v_exp_f32_e32 v112, v50
	v_exp_f32_e32 v113, v51
	v_sub_f32_e32 v50, v54, v120
	v_sub_f32_e32 v51, v55, v120
	v_or_b32_e32 v99, 0x2000, v127
	v_exp_f32_e32 v118, v50
	v_exp_f32_e32 v119, v51
	v_sub_f32_e32 v50, v56, v120
	v_sub_f32_e32 v51, v57, v120
	v_sub_f32_e32 v144, v36, v120
	v_sub_f32_e32 v145, v37, v121
	v_exp_f32_e32 v122, v50
	v_exp_f32_e32 v123, v51
	v_sub_f32_e32 v50, v58, v120
	v_sub_f32_e32 v51, v59, v120
	v_sub_f32_e32 v192, v38, v120
	v_sub_f32_e32 v193, v39, v121
	v_exp_f32_e32 v102, v50
	v_exp_f32_e32 v103, v51
	v_sub_f32_e32 v50, v60, v120
	v_sub_f32_e32 v51, v61, v120
	v_sub_f32_e32 v194, v40, v120
	v_sub_f32_e32 v195, v41, v121
	v_exp_f32_e32 v104, v50
	v_exp_f32_e32 v105, v51
	v_sub_f32_e32 v50, v62, v120
	v_sub_f32_e32 v51, v63, v120
	v_sub_f32_e32 v196, v42, v120
	v_sub_f32_e32 v197, v43, v121
	v_exp_f32_e32 v108, v50
	v_exp_f32_e32 v109, v51
	v_sub_f32_e32 v50, v64, v120
	v_sub_f32_e32 v51, v65, v120
	v_sub_f32_e32 v198, v44, v120
	v_sub_f32_e32 v199, v45, v121
	v_exp_f32_e32 v106, v50
	v_exp_f32_e32 v107, v51
	v_sub_f32_e32 v200, v46, v120
	v_sub_f32_e32 v201, v47, v121
	v_sub_f32_e32 v120, v48, v120
	v_sub_f32_e32 v121, v49, v121
	s_waitcnt lgkmcnt(0)
	s_barrier
	ds_read_b128 v[34:37], v124 offset:16384
	ds_read_b128 v[38:41], v124 offset:20480
	ds_read_b128 v[140:143], v125 offset:16384
	ds_read_b128 v[154:157], v125 offset:20480
	ds_read_b128 v[158:161], v130 offset:16384
	ds_read_b128 v[162:165], v130 offset:20480
	s_waitcnt lgkmcnt(0)
	v_mfma_f32_32x32x16_bf16 v[50:65], v[34:37], v[74:77], 0
	v_exp_f32_e32 v202, v100
	v_exp_f32_e32 v203, v101
	v_add_f32_e32 v100, 0, v110
	v_add_f32_e32 v101, 0, v111
	v_exp_f32_e32 v144, v144
	v_add_f32_e32 v100, v112, v100
	v_add_f32_e32 v101, v113, v101
	v_exp_f32_e32 v145, v145
	v_add_f32_e32 v100, v118, v100
	v_add_f32_e32 v101, v119, v101
	v_mfma_f32_32x32x16_bf16 v[34:49], v[38:41], v[74:77], 0
	v_add_f32_e64 v100, v122, v100
	v_add_f32_e64 v101, v123, v101
	ds_read_b128 v[166:169], v135 offset:16384
	ds_read_b128 v[180:183], v135 offset:20480
	v_add_f32_e64 v100, v102, v100
	v_add_f32_e64 v101, v103, v101
	v_exp_f32_e32 v192, v192
	v_add_f32_e32 v100, v104, v100
	v_add_f32_e32 v101, v105, v101
	v_exp_f32_e32 v193, v193
	v_add_f32_e32 v100, v108, v100
	v_add_f32_e32 v101, v109, v101
	v_mfma_f32_32x32x16_bf16 v[50:65], v[140:143], v[70:73], v[50:65]
	v_exp_f32_e32 v194, v194
	v_exp_f32_e32 v195, v195
	v_add_f32_e32 v100, v106, v100
	v_add_f32_e32 v101, v107, v101
	v_exp_f32_e32 v196, v196
	v_exp_f32_e32 v197, v197
	v_add_f32_e32 v100, v202, v100
	v_add_f32_e32 v101, v203, v101
	v_exp_f32_e32 v198, v198
	v_mfma_f32_32x32x16_bf16 v[34:49], v[154:157], v[70:73], v[34:49]
	v_exp_f32_e32 v199, v199
	v_add_f32_e32 v100, v144, v100
	v_add_f32_e32 v101, v145, v101
	v_exp_f32_e32 v140, v200
	v_exp_f32_e32 v141, v201
	v_add_f32_e32 v100, v192, v100
	v_add_f32_e32 v101, v193, v101
	v_exp_f32_e32 v142, v120
	v_exp_f32_e32 v143, v121
	v_mfma_f32_32x32x16_bf16 v[50:65], v[158:161], v[66:69], v[50:65]
	v_add_f32_e64 v100, v194, v100
	v_add_f32_e64 v101, v195, v101
	v_cvt_pk_bf16_f32 v102, v102, v103
	v_cvt_pk_bf16_f32 v103, v104, v105
	v_cvt_pk_bf16_f32 v104, v108, v109
	v_cvt_pk_bf16_f32 v110, v110, v111
	v_cvt_pk_bf16_f32 v111, v112, v113
	v_add_f32_e64 v100, v196, v100
	v_add_f32_e64 v101, v197, v101
	v_mfma_f32_32x32x16_bf16 v[34:49], v[162:165], v[66:69], v[34:49]
	v_add_f32_e64 v100, v198, v100
	v_add_f32_e64 v101, v199, v101
	v_cvt_pk_bf16_f32 v112, v118, v119
	v_cvt_pk_bf16_f32 v113, v122, v123
	v_cvt_pk_bf16_f32 v105, v106, v107
	v_permlane32_swap_b32_e32 v102, v104
	v_add_f32_e64 v100, v140, v100
	v_add_f32_e64 v101, v141, v101
	s_waitcnt lgkmcnt(0)
	v_mfma_f32_32x32x16_bf16 v[50:65], v[166:169], v[78:81], v[50:65]
	v_add_f32_e64 v100, v142, v100
	v_add_f32_e64 v101, v143, v101
	v_cvt_pk_bf16_f32 v106, v202, v203
	v_cvt_pk_bf16_f32 v107, v144, v145
	v_cvt_pk_bf16_f32 v108, v192, v193
	v_cvt_pk_bf16_f32 v109, v194, v195
	v_cvt_pk_bf16_f32 v118, v196, v197
	v_pk_add_f32 v[100:101], v[100:101], v[100:101] op_sel:[0,1] op_sel_hi:[1,0]
	v_mfma_f32_32x32x16_bf16 v[34:49], v[180:183], v[78:81], v[34:49]
	v_mov_b32_e32 v101, v100
	s_nop 1
	v_permlane32_swap_b32_e32 v100, v101
	v_cvt_pk_bf16_f32 v119, v198, v199
	v_cvt_pk_bf16_f32 v120, v140, v141
	v_cvt_pk_bf16_f32 v121, v142, v143
	v_permlane32_swap_b32_e32 v110, v112
	v_permlane32_swap_b32_e32 v111, v113
	v_permlane32_swap_b32_e32 v103, v105
	v_permlane32_swap_b32_e32 v106, v108
	v_permlane32_swap_b32_e32 v107, v109
	v_permlane32_swap_b32_e32 v118, v120
	v_permlane32_swap_b32_e32 v119, v121
	ds_read_b64_tr_b16 v[140:141], v99 offset:0
	ds_read_b64_tr_b16 v[142:143], v99 offset:0x400
	ds_read_b64_tr_b16 v[154:155], v99 offset:0x800
	ds_read_b64_tr_b16 v[156:157], v99 offset:0xc00
	ds_read_b64_tr_b16 v[158:159], v99 offset:0x1000
	ds_read_b64_tr_b16 v[160:161], v99 offset:0x1400
	ds_read_b64_tr_b16 v[162:163], v99 offset:0x1800
	ds_read_b64_tr_b16 v[164:165], v99 offset:0x1c00
	s_waitcnt lgkmcnt(0)
	s_nop 0
	v_mfma_f32_32x32x16_bf16 v[2:17], v[110:113], v[140:143], v[2:17]
	ds_read_b64_tr_b16 v[140:141], v99 offset:0x200
	ds_read_b64_tr_b16 v[142:143], v99 offset:0x600
	v_mfma_f32_32x32x16_bf16 v[2:17], v[102:105], v[154:157], v[2:17]
	ds_read_b64_tr_b16 v[154:155], v99 offset:0xa00
	ds_read_b64_tr_b16 v[156:157], v99 offset:0xe00
	v_mfma_f32_32x32x16_bf16 v[2:17], v[106:109], v[158:161], v[2:17]
	ds_read_b64_tr_b16 v[158:159], v99 offset:0x1200
	ds_read_b64_tr_b16 v[160:161], v99 offset:0x1600
	ds_read_b64_tr_b16 v[166:167], v99 offset:0x1a00
	ds_read_b64_tr_b16 v[168:169], v99 offset:0x1e00
	s_waitcnt lgkmcnt(0)
	v_mfma_f32_32x32x16_bf16 v[2:17], v[118:121], v[162:165], v[2:17]
	v_mfma_f32_32x32x16_bf16 v[18:33], v[110:113], v[140:143], v[18:33]
	v_max_f32_e32 v122, v51, v51
	v_max_f32_e32 v123, v50, v50
	v_max_f32_e32 v122, v123, v122
	v_max3_f32 v122, v122, v52, v53
	v_max3_f32 v122, v122, v54, v55
	v_max3_f32 v110, v122, v56, v57
	v_max3_f32 v110, v110, v58, v59
	v_mfma_f32_32x32x16_bf16 v[18:33], v[102:105], v[154:157], v[18:33]
	v_max3_f32 v110, v110, v60, v61
	v_max3_f32 v110, v110, v62, v63
	v_max3_f32 v110, v110, v64, v65
	v_max3_f32 v110, v110, v34, v35
	v_max3_f32 v110, v110, v36, v37
	v_max3_f32 v102, v110, v38, v39
	v_max3_f32 v102, v102, v40, v41
	v_mfma_f32_32x32x16_bf16 v[18:33], v[106:109], v[158:161], v[18:33]
	v_max3_f32 v102, v102, v42, v43
	v_max3_f32 v102, v102, v44, v45
	v_max3_f32 v102, v102, v46, v47
	v_max3_f32 v102, v102, v48, v49
	v_mov_b32_e32 v103, v102
	s_nop 1
	v_permlane32_swap_b32_e32 v102, v103
	v_mfma_f32_32x32x16_bf16 v[18:33], v[118:121], v[166:169], v[18:33]
	v_max_f32_e32 v103, v103, v103
	v_max_f32_e32 v102, v102, v102
	v_max_f32_e32 v102, v102, v103
	v_sub_f32_e32 v103, v102, v138
	v_cmp_ge_f32_e32 vcc, s0, v103
	s_cmp_lg_u64 vcc, exec
	s_cbranch_scc1 .LBB0_501
	v_mov_b32_e32 v102, v138

.LBB0_491:
	v_mov_b32_e32 v103, v102
	v_sub_f32_e32 v50, v50, v102
	v_sub_f32_e32 v51, v51, v102
	v_sub_f32_e32 v82, 0xf149f2ca, v137
	v_exp_f32_e32 v90, v50
	v_exp_f32_e32 v91, v51
	v_sub_f32_e32 v50, v52, v102
	v_sub_f32_e32 v51, v53, v102
	v_exp_f32_e32 v105, v82
	v_exp_f32_e32 v92, v50
	v_exp_f32_e32 v93, v51
	v_sub_f32_e32 v50, v54, v102
	v_sub_f32_e32 v51, v55, v102
	v_sub_f32_e32 v112, v34, v102
	v_sub_f32_e32 v113, v35, v103
	v_exp_f32_e32 v94, v50
	v_exp_f32_e32 v95, v51
	v_sub_f32_e32 v50, v56, v102
	v_sub_f32_e32 v51, v57, v102
	v_sub_f32_e32 v144, v36, v102
	v_sub_f32_e32 v145, v37, v103
	v_exp_f32_e32 v96, v50
	v_exp_f32_e32 v97, v51
	v_sub_f32_e32 v50, v58, v102
	v_sub_f32_e32 v51, v59, v102
	v_sub_f32_e32 v154, v38, v102
	v_sub_f32_e32 v155, v39, v103
	v_exp_f32_e32 v82, v50
	v_exp_f32_e32 v83, v51
	v_sub_f32_e32 v50, v60, v102
	v_sub_f32_e32 v51, v61, v102
	v_sub_f32_e32 v156, v40, v102
	v_sub_f32_e32 v157, v41, v103
	v_exp_f32_e32 v84, v50
	v_exp_f32_e32 v85, v51
	v_sub_f32_e32 v50, v62, v102
	v_sub_f32_e32 v51, v63, v102
	v_sub_f32_e32 v158, v42, v102
	v_sub_f32_e32 v159, v43, v103
	v_exp_f32_e32 v88, v50
	v_exp_f32_e32 v89, v51
	v_sub_f32_e32 v50, v64, v102
	v_sub_f32_e32 v51, v65, v102
	v_sub_f32_e32 v160, v44, v102
	v_sub_f32_e32 v161, v45, v103
	v_exp_f32_e32 v86, v50
	v_exp_f32_e32 v87, v51
	v_sub_f32_e32 v162, v46, v102
	v_sub_f32_e32 v163, v47, v103
	v_sub_f32_e32 v102, v48, v102
	v_sub_f32_e32 v103, v49, v103
	s_waitcnt lgkmcnt(0)
	s_barrier
	ds_read_b128 v[34:37], v124 offset:24576
	ds_read_b128 v[38:41], v124 offset:28672
	ds_read_b128 v[108:111], v125 offset:24576
	ds_read_b128 v[118:121], v125 offset:28672
	ds_read_b128 v[122:125], v130 offset:24576
	ds_read_b128 v[130:133], v130 offset:28672
	s_waitcnt lgkmcnt(5)
	v_mfma_f32_32x32x16_bf16 v[50:65], v[34:37], v[74:77], 0
	v_exp_f32_e32 v112, v112
	v_exp_f32_e32 v113, v113
	ds_read_b128 v[136:139], v135 offset:24576
	ds_read_b128 v[140:143], v135 offset:28672
	v_exp_f32_e32 v134, v144
	v_exp_f32_e32 v135, v145
	v_exp_f32_e32 v144, v154
	v_exp_f32_e32 v145, v155
	s_waitcnt lgkmcnt(6)
	v_mfma_f32_32x32x16_bf16 v[34:49], v[38:41], v[74:77], 0
	v_add_f32_e64 v74, v90, 0
	v_add_f32_e64 v75, v91, 0
	v_exp_f32_e32 v154, v156
	v_add_f32_e32 v74, v92, v74
	v_add_f32_e32 v75, v93, v75
	v_exp_f32_e32 v155, v157
	v_add_f32_e32 v74, v94, v74
	v_add_f32_e32 v75, v95, v75
	v_exp_f32_e32 v156, v158
	v_exp_f32_e32 v157, v159
	s_waitcnt lgkmcnt(5)
	v_mfma_f32_32x32x16_bf16 v[50:65], v[108:111], v[70:73], v[50:65]
	v_exp_f32_e32 v158, v160
	v_exp_f32_e32 v159, v161
	v_exp_f32_e32 v108, v162
	v_exp_f32_e32 v109, v163
	v_exp_f32_e32 v102, v102
	v_exp_f32_e32 v103, v103
	v_cvt_pk_bf16_f32 v76, v112, v113
	s_waitcnt lgkmcnt(4)
	v_mfma_f32_32x32x16_bf16 v[34:49], v[118:121], v[70:73], v[34:49]
	v_add_f32_e64 v70, v96, v74
	v_add_f32_e64 v71, v97, v75
	v_cvt_pk_bf16_f32 v72, v82, v83
	v_cvt_pk_bf16_f32 v73, v84, v85
	v_cvt_pk_bf16_f32 v74, v88, v89
	v_cvt_pk_bf16_f32 v75, v86, v87
	v_cvt_pk_bf16_f32 v77, v134, v135
	v_add_f32_e64 v70, v82, v70
	v_add_f32_e64 v71, v83, v71
	s_waitcnt lgkmcnt(3)
	v_mfma_f32_32x32x16_bf16 v[50:65], v[122:125], v[66:69], v[50:65]
	v_add_f32_e64 v70, v84, v70
	v_add_f32_e64 v71, v85, v71
	v_cvt_pk_bf16_f32 v82, v108, v109
	v_cvt_pk_bf16_f32 v83, v102, v103
	v_permlane32_swap_b32_e32 v72, v74
	v_add_f32_e64 v70, v88, v70
	v_add_f32_e64 v71, v89, v71
	v_permlane32_swap_b32_e32 v73, v75
	s_waitcnt lgkmcnt(2)
	v_mfma_f32_32x32x16_bf16 v[34:49], v[130:133], v[66:69], v[34:49]
	v_add_f32_e64 v70, v86, v70
	v_add_f32_e64 v71, v87, v71
	v_cvt_pk_bf16_f32 v66, v90, v91
	v_cvt_pk_bf16_f32 v68, v94, v95
	v_cvt_pk_bf16_f32 v67, v92, v93
	v_cvt_pk_bf16_f32 v69, v96, v97
	v_add_f32_e64 v70, v112, v70
	v_add_f32_e64 v71, v113, v71
	s_waitcnt lgkmcnt(1)
	v_mfma_f32_32x32x16_bf16 v[50:65], v[136:139], v[78:81], v[50:65]
	v_add_f32_e64 v70, v134, v70
	v_add_f32_e64 v71, v135, v71
	v_permlane32_swap_b32_e32 v66, v68
	v_add_f32_e64 v70, v144, v70
	v_add_f32_e64 v71, v145, v71
	v_permlane32_swap_b32_e32 v67, v69
	v_add_f32_e32 v70, v154, v70
	v_add_f32_e32 v71, v155, v71
	s_waitcnt lgkmcnt(0)
	v_mfma_f32_32x32x16_bf16 v[34:49], v[140:143], v[78:81], v[34:49]
	v_add_f32_e64 v70, v156, v70
	v_add_f32_e64 v71, v157, v71
	v_cvt_pk_bf16_f32 v78, v144, v145
	v_cvt_pk_bf16_f32 v79, v154, v155
	v_cvt_pk_bf16_f32 v80, v156, v157
	v_cvt_pk_bf16_f32 v81, v158, v159
	v_add_f32_e64 v70, v158, v70
	v_add_f32_e64 v71, v159, v71
	v_permlane32_swap_b32_e32 v76, v78
	v_add_f32_e32 v70, v108, v70
	v_add_f32_e32 v71, v109, v71
	v_permlane32_swap_b32_e32 v77, v79
	v_add_f32_e32 v70, v102, v70
	v_add_f32_e32 v71, v103, v71
	v_permlane32_swap_b32_e32 v80, v82
	v_pk_add_f32 v[70:71], v[70:71], v[70:71] op_sel:[0,1] op_sel_hi:[1,0]
	v_permlane32_swap_b32_e32 v81, v83
	v_mov_b32_e32 v71, v70
	s_nop 1
	v_permlane32_swap_b32_e32 v70, v71
	ds_read_b64_tr_b16 v[84:85], v127 offset:0
	ds_read_b64_tr_b16 v[86:87], v127 offset:0x400
	ds_read_b64_tr_b16 v[88:89], v127 offset:0x800
	ds_read_b64_tr_b16 v[90:91], v127 offset:0xc00
	ds_read_b64_tr_b16 v[92:93], v127 offset:0x1000
	ds_read_b64_tr_b16 v[94:95], v127 offset:0x1400
	ds_read_b64_tr_b16 v[108:109], v127 offset:0x1800
	ds_read_b64_tr_b16 v[110:111], v127 offset:0x1c00
	s_waitcnt lgkmcnt(0)
	s_nop 0
	v_mfma_f32_32x32x16_bf16 v[2:17], v[66:69], v[84:87], v[2:17]
	ds_read_b64_tr_b16 v[84:85], v127 offset:0x200
	ds_read_b64_tr_b16 v[86:87], v127 offset:0x600
	v_mfma_f32_32x32x16_bf16 v[2:17], v[72:75], v[88:91], v[2:17]
	ds_read_b64_tr_b16 v[88:89], v127 offset:0xa00
	ds_read_b64_tr_b16 v[90:91], v127 offset:0xe00
	v_mfma_f32_32x32x16_bf16 v[2:17], v[76:79], v[92:95], v[2:17]
	ds_read_b64_tr_b16 v[92:93], v127 offset:0x1200
	ds_read_b64_tr_b16 v[94:95], v127 offset:0x1600
	ds_read_b64_tr_b16 v[118:119], v127 offset:0x1a00
	ds_read_b64_tr_b16 v[120:121], v127 offset:0x1e00
	s_waitcnt lgkmcnt(0)
	v_mfma_f32_32x32x16_bf16 v[2:17], v[80:83], v[108:111], v[2:17]
	v_mfma_f32_32x32x16_bf16 v[18:33], v[66:69], v[84:87], v[18:33]
	v_max_f32_e32 v96, v51, v51
	v_max_f32_e32 v97, v50, v50
	v_max_f32_e32 v96, v97, v96
	v_max3_f32 v96, v96, v52, v53
	v_max3_f32 v96, v96, v54, v55
	v_max3_f32 v66, v96, v56, v57
	v_max3_f32 v66, v66, v58, v59
	v_mfma_f32_32x32x16_bf16 v[18:33], v[72:75], v[88:91], v[18:33]
	v_max3_f32 v66, v66, v60, v61
	v_max3_f32 v66, v66, v62, v63
	v_max3_f32 v66, v66, v64, v65
	v_max3_f32 v66, v66, v34, v35
	v_max3_f32 v66, v66, v36, v37
	v_max3_f32 v66, v66, v38, v39
	v_max3_f32 v66, v66, v40, v41
	v_mfma_f32_32x32x16_bf16 v[18:33], v[76:79], v[92:95], v[18:33]
	v_max3_f32 v66, v66, v42, v43
	v_max3_f32 v66, v66, v44, v45
	v_max3_f32 v66, v66, v46, v47
	v_max3_f32 v66, v66, v48, v49
	v_mov_b32_e32 v67, v66
	s_nop 1
	v_permlane32_swap_b32_e32 v66, v67
	v_mfma_f32_32x32x16_bf16 v[18:33], v[80:83], v[118:121], v[18:33]
	v_max_f32_e32 v67, v67, v67
	v_max_f32_e32 v66, v66, v66
	v_max_f32_e32 v66, v66, v67
	v_sub_f32_e32 v67, v66, v106
	v_cmp_ge_f32_e32 vcc, s0, v67
	s_cmp_lg_u64 vcc, exec
	s_cbranch_scc1 .LBB0_502
	v_mov_b32_e32 v66, v106

.LBB0_498:
	v_mov_b32_e32 v67, v66
	v_sub_f32_e32 v50, v50, v66
	v_sub_f32_e32 v51, v51, v66
	v_sub_f32_e32 v34, v34, v66
	v_sub_f32_e32 v35, v35, v67
	v_exp_f32_e32 v68, v50
	v_exp_f32_e32 v69, v51
	v_sub_f32_e32 v50, v52, v66
	v_sub_f32_e32 v51, v53, v66
	v_sub_f32_e32 v52, v60, v66
	v_sub_f32_e32 v53, v61, v66
	v_exp_f32_e32 v72, v50
	v_exp_f32_e32 v73, v51
	v_sub_f32_e32 v50, v54, v66
	v_sub_f32_e32 v51, v55, v66
	v_exp_f32_e32 v52, v52
	v_exp_f32_e32 v74, v50
	v_exp_f32_e32 v75, v51
	v_sub_f32_e32 v50, v56, v66
	v_sub_f32_e32 v51, v57, v66
	v_exp_f32_e32 v53, v53
	v_exp_f32_e32 v76, v50
	v_exp_f32_e32 v77, v51
	v_sub_f32_e32 v50, v58, v66
	v_sub_f32_e32 v51, v59, v66
	v_exp_f32_e32 v58, v34
	v_exp_f32_e32 v50, v50
	v_exp_f32_e32 v51, v51
	v_exp_f32_e32 v59, v35
	v_add_f32_e32 v34, 0, v68
	v_add_f32_e32 v35, 0, v69
	v_sub_f32_e32 v54, v62, v66
	v_sub_f32_e32 v55, v63, v66
	v_add_f32_e32 v34, v72, v34
	v_add_f32_e32 v35, v73, v35
	v_exp_f32_e32 v54, v54
	v_exp_f32_e32 v55, v55
	v_sub_f32_e32 v56, v64, v66
	v_sub_f32_e32 v57, v65, v66
	v_add_f32_e32 v34, v74, v34
	v_add_f32_e32 v35, v75, v35
	v_exp_f32_e32 v56, v56
	v_exp_f32_e32 v57, v57
	v_add_f32_e32 v34, v76, v34
	v_add_f32_e32 v35, v77, v35
	v_sub_f32_e32 v36, v36, v66
	v_sub_f32_e32 v37, v37, v67
	v_add_f32_e32 v34, v50, v34
	v_add_f32_e32 v35, v51, v35
	v_sub_f32_e32 v38, v38, v66
	v_sub_f32_e32 v39, v39, v67
	v_exp_f32_e32 v60, v36
	v_exp_f32_e32 v61, v37
	v_add_f32_e32 v34, v52, v34
	v_add_f32_e32 v35, v53, v35
	v_sub_f32_e32 v40, v40, v66
	v_sub_f32_e32 v41, v41, v67
	v_exp_f32_e32 v62, v38
	v_exp_f32_e32 v63, v39
	v_add_f32_e32 v34, v54, v34
	v_add_f32_e32 v35, v55, v35
	v_sub_f32_e32 v42, v42, v66
	v_sub_f32_e32 v43, v43, v67
	v_exp_f32_e32 v64, v40
	v_exp_f32_e32 v65, v41
	v_add_f32_e32 v34, v56, v34
	v_add_f32_e32 v35, v57, v35
	v_sub_f32_e32 v44, v44, v66
	v_sub_f32_e32 v45, v45, v67
	v_sub_f32_e32 v46, v46, v66
	v_sub_f32_e32 v47, v47, v67
	v_sub_f32_e32 v48, v48, v66
	v_sub_f32_e32 v49, v49, v67
	v_exp_f32_e32 v66, v42
	v_exp_f32_e32 v67, v43
	v_add_f32_e32 v34, v58, v34
	v_add_f32_e32 v35, v59, v35
	v_exp_f32_e32 v80, v44
	v_exp_f32_e32 v81, v45
	v_add_f32_e32 v34, v60, v34
	v_add_f32_e32 v35, v61, v35
	v_exp_f32_e32 v82, v46
	v_exp_f32_e32 v83, v47
	v_add_f32_e32 v34, v62, v34
	v_add_f32_e32 v35, v63, v35
	v_exp_f32_e32 v84, v48
	v_exp_f32_e32 v85, v49
	v_add_f32_e32 v34, v64, v34
	v_add_f32_e32 v35, v65, v35
	v_cvt_pk_bf16_f32 v36, v68, v69
	v_cvt_pk_bf16_f32 v37, v72, v73
	v_cvt_pk_bf16_f32 v38, v74, v75
	v_cvt_pk_bf16_f32 v39, v76, v77
	v_cvt_pk_bf16_f32 v40, v50, v51
	s_nop 0
	v_add_f32_e32 v34, v66, v34
	v_add_f32_e32 v35, v67, v35
	v_cvt_pk_bf16_f32 v41, v52, v53
	v_cvt_pk_bf16_f32 v42, v54, v55
	v_cvt_pk_bf16_f32 v43, v56, v57
	v_cvt_pk_bf16_f32 v44, v58, v59
	v_cvt_pk_bf16_f32 v45, v60, v61
	s_nop 0
	v_add_f32_e32 v34, v80, v34
	v_add_f32_e32 v35, v81, v35
	v_cvt_pk_bf16_f32 v46, v62, v63
	v_cvt_pk_bf16_f32 v47, v64, v65
	v_cvt_pk_bf16_f32 v48, v66, v67
	v_cvt_pk_bf16_f32 v49, v80, v81
	v_cvt_pk_bf16_f32 v50, v82, v83
	s_nop 0
	v_add_f32_e32 v34, v82, v34
	v_add_f32_e32 v35, v83, v35
	v_cvt_pk_bf16_f32 v51, v84, v85
	v_permlane32_swap_b32_e32 v36, v38
	v_add_f32_e32 v34, v84, v34
	v_add_f32_e32 v35, v85, v35
	v_permlane32_swap_b32_e32 v37, v39
	v_pk_add_f32 v[34:35], v[34:35], v[34:35] op_sel:[0,1] op_sel_hi:[1,0]
	v_permlane32_swap_b32_e32 v40, v42
	v_mov_b32_e32 v35, v34
	s_nop 1
	v_permlane32_swap_b32_e32 v34, v35
	v_permlane32_swap_b32_e32 v41, v43
	v_permlane32_swap_b32_e32 v44, v46
	v_permlane32_swap_b32_e32 v45, v47
	v_permlane32_swap_b32_e32 v48, v50
	v_permlane32_swap_b32_e32 v49, v51
	ds_read_b64_tr_b16 v[52:53], v99 offset:0
	ds_read_b64_tr_b16 v[54:55], v99 offset:0x400
	ds_read_b64_tr_b16 v[56:57], v99 offset:0x800
	ds_read_b64_tr_b16 v[58:59], v99 offset:0xc00
	ds_read_b64_tr_b16 v[60:61], v99 offset:0x1000
	ds_read_b64_tr_b16 v[62:63], v99 offset:0x1400
	ds_read_b64_tr_b16 v[64:65], v99 offset:0x1800
	ds_read_b64_tr_b16 v[66:67], v99 offset:0x1c00
	s_waitcnt lgkmcnt(0)
	s_nop 0
	v_mfma_f32_32x32x16_bf16 v[2:17], v[36:39], v[52:55], v[2:17]
	ds_read_b64_tr_b16 v[52:53], v99 offset:0x200
	ds_read_b64_tr_b16 v[54:55], v99 offset:0x600
	v_mfma_f32_32x32x16_bf16 v[2:17], v[40:43], v[56:59], v[2:17]
	ds_read_b64_tr_b16 v[56:57], v99 offset:0xa00
	ds_read_b64_tr_b16 v[58:59], v99 offset:0xe00
	v_mfma_f32_32x32x16_bf16 v[2:17], v[44:47], v[60:63], v[2:17]
	ds_read_b64_tr_b16 v[60:61], v99 offset:0x1200
	ds_read_b64_tr_b16 v[62:63], v99 offset:0x1600
	ds_read_b64_tr_b16 v[72:73], v99 offset:0x1a00
	ds_read_b64_tr_b16 v[74:75], v99 offset:0x1e00
	s_waitcnt lgkmcnt(0)
	v_mfma_f32_32x32x16_bf16 v[2:17], v[48:51], v[64:67], v[2:17]
	v_mfma_f32_32x32x16_bf16 v[18:33], v[36:39], v[52:55], v[18:33]
	v_mfma_f32_32x32x16_bf16 v[18:33], v[40:43], v[56:59], v[18:33]
	v_mfma_f32_32x32x16_bf16 v[18:33], v[44:47], v[60:63], v[18:33]
	v_mfma_f32_32x32x16_bf16 v[18:33], v[48:51], v[72:75], v[18:33]
	s_and_saveexec_b64 s[14:15], s[8:9]
	s_cbranch_execz .LBB0_472
	v_mul_f32_e32 v36, 0, v105
	v_cndmask_b32_e64 v36, v36, 0, s[6:7]
	v_add_f32_e32 v37, v116, v117
	v_add_f32_e32 v36, v36, v37
	v_add_f32_e32 v37, v100, v101
	v_fmac_f32_e32 v37, v36, v126
	v_add_f32_e32 v36, v70, v71
	v_fmac_f32_e32 v36, v37, v104
	v_add_f32_e32 v34, v34, v35
	v_fmac_f32_e32 v34, v36, v78
	ds_write_b32 v129, v34 offset:32768
	s_branch .LBB0_472

.LBB0_626:
	s_or_b64 exec, exec, s[12:13]
	v_sub_u32_e32 v12, v2, v4
	v_max_i32_e32 v42, 0x100, v12
	v_add_u32_e32 v1, 0x180, v12
	v_add_u32_e32 v2, 0xffffff00, v42
	v_min_i32_e32 v1, v1, v3
	v_mov_b64_e32 v[6:7], s[38:39]
	s_mov_b32 s4, 0xa0000
	v_mov_b32_e32 v3, v0
	v_mov_b32_e32 v52, v170
	s_waitcnt lgkmcnt(0)
	s_barrier
	v_mad_u64_u32 v[8:9], s[4:5], v134, s4, v[6:7]
	v_lshlrev_b32_e32 v10, 7, v136
	v_mov_b32_e32 v11, v0
	v_lshl_add_u64 v[4:5], v[4:5], 0, v[2:3]
	v_sub_u32_e32 v51, v1, v2
	v_lshl_add_u64 v[8:9], v[8:9], 0, v[10:11]
	v_ashrrev_i32_e32 v2, 1, v52
	v_mad_u64_u32 v[6:7], s[4:5], v4, s59, v[6:7]
	v_bfe_u32 v1, v52, 5, 1
	v_bfi_b32 v140, s1, v2, v52
	v_mov_b32_e32 v4, v7
	v_and_b32_e32 v138, 0xffffffe0, v2
	v_mad_i64_i32 v[2:3], s[4:5], v140, s59, v[8:9]
	v_lshlrev_b32_e32 v142, 4, v1
	v_mov_b32_e32 v143, v0
	v_mad_u64_u32 v[4:5], s[4:5], v5, s59, v[4:5]
	v_lshl_add_u64 v[2:3], v[2:3], 0, v[142:143]
	v_ashrrev_i32_e32 v50, 3, v52
	v_mov_b32_e32 v7, v4
	flat_load_dwordx4 v[78:81], v[2:3]
	flat_load_dwordx4 v[74:77], v[2:3] offset:32
	flat_load_dwordx4 v[70:73], v[2:3] offset:64
	flat_load_dwordx4 v[66:69], v[2:3] offset:96
	v_and_b32_e32 v3, 0x1fffff0, v50
	v_lshlrev_b32_e32 v4, 1, v50
	v_lshlrev_b32_e32 v2, 3, v52
	v_and_or_b32 v3, v4, 8, v3
	v_and_b32_e32 v141, 56, v2
	v_lshrrev_b32_e32 v4, 1, v50
	v_lshrrev_b32_e32 v3, 2, v3
	v_bfe_u32 v2, v2, 5, 1
	v_and_b32_e32 v5, 3, v50
	v_lshl_add_u64 v[144:145], v[6:7], 0, v[10:11]
	v_or_b32_e32 v3, v3, v2
	v_and_or_b32 v4, v4, 4, v5
	v_lshlrev_b32_e32 v6, 1, v141
	v_lshlrev_b32_e32 v3, 9, v3
	v_lshlrev_b32_e32 v4, 6, v4
	v_and_b32_e32 v5, 48, v6
	v_add_u32_e32 v7, 32, v50
	v_or3_b32 v157, v3, v4, v5
	v_and_b32_e32 v3, 0x1fffff0, v7
	v_lshlrev_b32_e32 v8, 1, v7
	v_and_or_b32 v3, v8, 8, v3
	v_lshrrev_b32_e32 v3, 2, v3
	v_or_b32_e32 v2, v3, v2
	v_lshlrev_b32_e32 v2, 9, v2
	v_or3_b32 v164, v2, v4, v5
	v_mad_i64_i32 v[2:3], s[4:5], v50, s86, 0
	v_mad_i64_i32 v[4:5], s[4:5], v7, s86, 0
	v_or_b32_e32 v2, v2, v141
	v_or_b32_e32 v4, v4, v141
	v_lshl_add_u64 v[2:3], v[2:3], 1, v[144:145]
	v_lshl_add_u64 v[4:5], v[4:5], 1, v[144:145]
	flat_load_dwordx4 v[82:85], v[2:3] offset:1024
	flat_load_dwordx4 v[90:93], v[4:5] offset:1024
	flat_load_dwordx4 v[86:89], v[2:3] offset:512
	flat_load_dwordx4 v[94:97], v[4:5] offset:512
	v_lshlrev_b32_e32 v3, 4, v50
	v_lshlrev_b32_e32 v2, 7, v50
	v_and_b32_e32 v3, 0x70, v3
	v_bitop3_b32 v167, v6, v2, v3 bitop3:0xde
	v_lshlrev_b32_e32 v2, 7, v7
	v_and_b32_e32 v149, 31, v52
	v_bitop3_b32 v168, v6, v2, v3 bitop3:0xde
	v_lshlrev_b32_e32 v2, 4, v52
	v_lshlrev_b32_e32 v44, 7, v149
	v_and_b32_e32 v45, 0x70, v2
	v_bitop3_b32 v166, v142, v44, v45 bitop3:0xde
	s_waitcnt vmcnt(0)
	v_add_u32_e32 v43, v138, v12
	v_or_b32_e32 v34, 32, v142
	v_bitop3_b32 v169, v34, v44, v45 bitop3:0xde
	v_sub_u32_e32 v139, v42, v43
	v_sub_u32_e32 v53, v139, v149
	v_lshl_add_u32 v48, v53, 2, v142
	s_waitcnt vmcnt(0) lgkmcnt(0)
	ds_write_b128 v157, v[82:85]
	ds_write_b128 v164, v[90:93]
	ds_write_b128 v167, v[86:89] offset:16384
	ds_write_b128 v168, v[94:97] offset:16384
	s_waitcnt lgkmcnt(0)
	s_barrier
	ds_read_b128 v[2:5], v166 offset:16384
	ds_read_b128 v[18:21], v166 offset:20480
	s_waitcnt lgkmcnt(1)
	v_mfma_f32_32x32x16_bf16 v[2:17], v[2:5], v[78:81], 0
	ds_read_b128 v[34:37], v169 offset:16384
	ds_read_b128 v[38:41], v169 offset:20480
	s_waitcnt lgkmcnt(2)
	v_mfma_f32_32x32x16_bf16 v[18:33], v[18:21], v[78:81], 0
	s_waitcnt lgkmcnt(1)
	v_mfma_f32_32x32x16_bf16 v[2:17], v[34:37], v[74:77], v[2:17]
	v_or_b32_e32 v34, 64, v142
	v_bitop3_b32 v192, v34, v44, v45 bitop3:0xde
	s_waitcnt lgkmcnt(0)
	v_mfma_f32_32x32x16_bf16 v[18:33], v[38:41], v[74:77], v[18:33]
	ds_read_b128 v[34:37], v192 offset:16384
	ds_read_b128 v[38:41], v192 offset:20480
	s_waitcnt lgkmcnt(1)
	v_mfma_f32_32x32x16_bf16 v[2:17], v[34:37], v[70:73], v[2:17]
	v_or_b32_e32 v34, 0x60, v142
	v_bitop3_b32 v191, v34, v44, v45 bitop3:0xde
	s_waitcnt lgkmcnt(0)
	v_mfma_f32_32x32x16_bf16 v[18:33], v[38:41], v[70:73], v[18:33]
	ds_read_b128 v[34:37], v191 offset:16384
	ds_read_b128 v[38:41], v191 offset:20480
	s_waitcnt lgkmcnt(1)
	v_mfma_f32_32x32x16_bf16 v[2:17], v[34:37], v[66:69], v[2:17]
	v_add_u32_e32 v34, 0x9200, v48
	ds_read2_b32 v[34:35], v34 offset1:1
	v_add_u32_e32 v36, 0x9280, v48
	ds_read2_b32 v[36:37], v36 offset1:1
	s_waitcnt lgkmcnt(2)
	v_mfma_f32_32x32x16_bf16 v[18:33], v[38:41], v[66:69], v[18:33]
	s_waitcnt lgkmcnt(1)
	s_nop 4
	v_add_f32_e64 v34, v2, v34
	v_add_f32_e64 v35, v3, v35
	v_add_u32_e32 v2, 0x9208, v48
	ds_read2_b32 v[2:3], v2 offset1:1
	s_waitcnt lgkmcnt(1)
	s_nop 0
	v_add_f32_e32 v18, v18, v36
	v_add_f32_e32 v19, v19, v37
	v_add_u32_e32 v36, 0x9288, v48
	ds_read2_b32 v[38:39], v36 offset1:1
	s_waitcnt lgkmcnt(1)
	v_add_f32_e32 v36, v4, v2
	v_add_f32_e32 v37, v5, v3
	v_add_u32_e32 v2, 0x9220, v48
	ds_read2_b32 v[2:3], v2 offset1:1
	v_add_u32_e32 v4, 0x92a0, v48
	s_waitcnt lgkmcnt(1)
	v_add_f32_e32 v20, v20, v38
	v_add_f32_e32 v21, v21, v39
	ds_read2_b32 v[4:5], v4 offset1:1
	s_waitcnt lgkmcnt(1)
	v_add_f32_e32 v38, v6, v2
	v_add_f32_e32 v39, v7, v3
	v_add_u32_e32 v2, 0x9228, v48
	ds_read2_b32 v[2:3], v2 offset1:1
	s_waitcnt lgkmcnt(1)
	v_add_f32_e32 v22, v22, v4
	v_add_f32_e32 v23, v23, v5
	v_add_u32_e32 v4, 0x92a8, v48
	ds_read2_b32 v[4:5], v4 offset1:1
	v_add_u32_e32 v6, 0x60, v50
	s_waitcnt lgkmcnt(1)
	v_add_f32_e32 v40, v8, v2
	v_add_f32_e32 v41, v9, v3
	v_add_u32_e32 v2, 0x9240, v48
	ds_read2_b32 v[2:3], v2 offset1:1
	s_waitcnt lgkmcnt(1)
	v_add_f32_e32 v24, v24, v4
	v_add_f32_e32 v25, v25, v5
	v_add_u32_e32 v4, 0x92c0, v48
	ds_read2_b32 v[4:5], v4 offset1:1
	v_mad_i64_i32 v[6:7], s[4:5], v6, s86, 0
	s_waitcnt lgkmcnt(1)
	v_add_f32_e32 v42, v10, v2
	v_add_f32_e32 v43, v11, v3
	v_add_u32_e32 v2, 0x9248, v48
	ds_read2_b32 v[2:3], v2 offset1:1
	s_waitcnt lgkmcnt(1)
	v_add_f32_e32 v26, v26, v4
	v_add_f32_e32 v27, v27, v5
	v_add_u32_e32 v4, 0x92c8, v48
	ds_read2_b32 v[4:5], v4 offset1:1
	v_or_b32_e32 v6, v6, v141
	s_waitcnt lgkmcnt(1)
	v_add_f32_e32 v44, v12, v2
	v_add_f32_e32 v45, v13, v3
	v_add_u32_e32 v2, 0x9260, v48
	ds_read2_b32 v[2:3], v2 offset1:1
	s_waitcnt lgkmcnt(1)
	v_add_f32_e32 v28, v28, v4
	v_add_f32_e32 v29, v29, v5
	v_add_u32_e32 v4, 0x92e0, v48
	ds_read2_b32 v[4:5], v4 offset1:1
	s_waitcnt lgkmcnt(1)
	v_add_f32_e32 v46, v14, v2
	v_add_f32_e32 v47, v15, v3
	v_add_u32_e32 v2, 0x9268, v48
	ds_read2_b32 v[2:3], v2 offset1:1
	s_waitcnt lgkmcnt(1)
	v_add_f32_e32 v30, v30, v4
	v_add_f32_e32 v31, v31, v5
	v_add_u32_e32 v4, 0x92e8, v48
	ds_read2_b32 v[4:5], v4 offset1:1
	v_lshl_add_u64 v[14:15], v[6:7], 1, v[144:145]
	s_waitcnt lgkmcnt(1)
	v_add_f32_e32 v48, v16, v2
	v_add_f32_e32 v49, v17, v3
	v_max_f32_e32 v2, v34, v35
	v_max3_f32 v2, v2, v36, v37
	v_max3_f32 v2, v2, v38, v39
	v_max3_f32 v2, v2, v40, v41
	v_max3_f32 v2, v2, v42, v43
	v_max3_f32 v2, v2, v44, v45
	v_max3_f32 v2, v2, v46, v47
	v_max3_f32 v2, v2, v48, v49
	v_max3_f32 v2, v2, v18, v19
	v_max3_f32 v2, v2, v20, v21
	v_max3_f32 v2, v2, v22, v23
	v_max3_f32 v2, v2, v24, v25
	v_max3_f32 v2, v2, v26, v27
	v_max3_f32 v2, v2, v28, v29
	s_waitcnt lgkmcnt(0)
	v_add_f32_e32 v32, v32, v4
	v_add_f32_e32 v33, v33, v5
	v_max3_f32 v2, v2, v30, v31
	v_max3_f32 v2, v2, v32, v33
	v_mov_b32_e32 v3, v2
	s_nop 1
	v_permlane32_swap_b32_e32 v2, v3
	v_max_f32_e32 v3, v3, v3
	v_max_f32_e32 v2, v2, v2
	v_max_f32_e32 v54, v2, v3
	v_add_f32_e32 v2, 0x7149f2ca, v54
	v_cmp_ge_f32_e32 vcc, s0, v2
	v_add_u32_e32 v2, 64, v50
	v_mad_i64_i32 v[2:3], s[4:5], v2, s86, 0
	v_or_b32_e32 v2, v2, v141
	v_lshl_add_u64 v[10:11], v[2:3], 1, v[144:145]
	flat_load_dwordx4 v[2:5], v[10:11] offset:1024
	flat_load_dwordx4 v[6:9], v[14:15] offset:1024
	s_nop 0
	flat_load_dwordx4 v[10:13], v[10:11] offset:512
	s_nop 0
	flat_load_dwordx4 v[14:17], v[14:15] offset:512
	s_cmp_eq_u64 vcc, exec
	s_movk_i32 s4, 0xbf
	s_cselect_b64 vcc, -1, 0
	v_cmp_lt_i32_e64 s[12:13], s4, v51
	s_and_saveexec_b64 s[8:9], s[12:13]
	s_cbranch_execz .LBB0_628
	v_add_u32_e32 v55, 0x80, v50
	v_mad_i64_i32 v[56:57], s[4:5], v55, s86, 0
	v_add_u32_e32 v55, 0xa0, v50
	v_or_b32_e32 v56, v56, v141
	v_mad_i64_i32 v[58:59], s[4:5], v55, s86, 0
	v_lshl_add_u64 v[56:57], v[56:57], 1, v[144:145]
	v_or_b32_e32 v58, v58, v141
	v_lshl_add_u64 v[58:59], v[58:59], 1, v[144:145]
	flat_load_dwordx4 v[82:85], v[56:57] offset:1024
	flat_load_dwordx4 v[86:89], v[56:57] offset:512
	flat_load_dwordx4 v[90:93], v[58:59] offset:1024
	flat_load_dwordx4 v[94:97], v[58:59] offset:512
.LBB0_628:
	s_or_b64 exec, exec, s[8:9]
	v_max_f32_e32 v54, 0xf149f2ca, v54
	v_cndmask_b32_e32 v114, v54, v178, vcc
	v_sub_f32_e32 v34, v34, v114
	v_sub_f32_e32 v35, v35, v114
	v_and_b32_e32 v151, 63, v52
	v_exp_f32_e32 v112, v34
	v_exp_f32_e32 v113, v35
	v_sub_f32_e32 v34, v36, v114
	v_sub_f32_e32 v35, v37, v114
	v_sub_f32_e32 v37, 0xf149f2ca, v54
	v_exp_f32_e32 v110, v34
	v_exp_f32_e32 v111, v35
	v_sub_f32_e32 v34, v38, v114
	v_sub_f32_e32 v35, v39, v114
	v_exp_f32_e32 v37, v37
	v_exp_f32_e32 v108, v34
	v_exp_f32_e32 v109, v35
	v_sub_f32_e32 v34, v40, v114
	v_sub_f32_e32 v35, v41, v114
	v_lshlrev_b32_e32 v36, 1, v151
	v_exp_f32_e32 v106, v34
	v_exp_f32_e32 v107, v35
	v_sub_f32_e32 v34, v42, v114
	v_sub_f32_e32 v35, v43, v114
	v_and_b32_e32 v36, 32, v36
	v_exp_f32_e32 v104, v34
	v_exp_f32_e32 v105, v35
	v_sub_f32_e32 v34, v44, v114
	v_sub_f32_e32 v35, v45, v114
	s_waitcnt vmcnt(4)
	s_waitcnt vmcnt(0) lgkmcnt(0)
	ds_write_b128 v157, v[2:5] offset:8192
	ds_write_b128 v164, v[6:9] offset:8192
	ds_write_b128 v167, v[10:13] offset:24576
	ds_write_b128 v168, v[14:17] offset:24576
	v_exp_f32_e32 v102, v34
	v_exp_f32_e32 v103, v35
	v_sub_f32_e32 v34, v46, v114
	v_sub_f32_e32 v35, v47, v114
	v_mov_b32_e32 v17, 0
	v_exp_f32_e32 v100, v34
	v_exp_f32_e32 v101, v35
	v_sub_f32_e32 v34, v48, v114
	v_sub_f32_e32 v35, v49, v114
	v_cndmask_b32_e64 v163, v37, 1.0, vcc
	v_exp_f32_e32 v98, v34
	v_ashrrev_i32_e32 v34, 31, v51
	v_lshrrev_b32_e32 v34, 26, v34
	v_add_u32_e32 v34, v51, v34
	v_exp_f32_e32 v99, v35
	v_ashrrev_i32_e32 v193, 6, v34
	v_and_b32_e32 v34, 0x3fffffc0, v52
	v_lshlrev_b32_e32 v35, 4, v151
	v_lshlrev_b32_e32 v143, 2, v34
	v_lshlrev_b32_e32 v34, 3, v151
	v_and_b32_e32 v35, 0xc0, v35
	v_and_or_b32 v35, v34, 24, v35
	v_and_b32_e32 v34, 0x100, v34
	v_or3_b32 v194, v35, v36, v34
	v_sub_f32_e32 v126, v18, v114
	v_sub_f32_e32 v127, v19, v114
	v_sub_f32_e32 v128, v20, v114
	v_sub_f32_e32 v129, v21, v114
	v_sub_f32_e32 v198, v22, v114
	v_sub_f32_e32 v119, v23, v114
	v_sub_f32_e32 v120, v24, v114
	v_sub_f32_e32 v121, v25, v114
	v_sub_f32_e32 v122, v26, v114
	v_sub_f32_e32 v123, v27, v114
	v_sub_f32_e32 v124, v28, v114
	v_sub_f32_e32 v125, v29, v114
	v_sub_f32_e32 v115, v30, v114
	v_sub_f32_e32 v116, v31, v114
	v_sub_f32_e32 v117, v32, v114
	v_sub_f32_e32 v118, v33, v114
	v_lshl_add_u32 v155, v149, 2, v143
	v_or_b32_e32 v162, 0x2000, v194
	v_mov_b32_e32 v16, v17
	v_mov_b32_e32 v15, v17
	v_mov_b32_e32 v14, v17
	v_mov_b32_e32 v13, v17
	v_mov_b32_e32 v12, v17
	v_mov_b32_e32 v11, v17
	v_mov_b32_e32 v10, v17
	v_mov_b32_e32 v9, v17
	v_mov_b32_e32 v8, v17
	v_mov_b32_e32 v7, v17
	v_mov_b32_e32 v6, v17
	v_mov_b32_e32 v5, v17
	v_mov_b32_e32 v4, v17
	v_mov_b32_e32 v3, v17
	v_mov_b32_e32 v2, v17
	v_mov_b32_e32 v33, v17
	v_mov_b32_e32 v32, v17
	v_mov_b32_e32 v31, v17
	v_mov_b32_e32 v30, v17
	v_mov_b32_e32 v29, v17
	v_mov_b32_e32 v28, v17
	v_mov_b32_e32 v27, v17
	v_mov_b32_e32 v26, v17
	v_mov_b32_e32 v25, v17
	v_mov_b32_e32 v24, v17
	v_mov_b32_e32 v23, v17
	v_mov_b32_e32 v22, v17
	v_mov_b32_e32 v21, v17
	v_mov_b32_e32 v20, v17
	v_mov_b32_e32 v19, v17
	v_mov_b32_e32 v18, v17
	v_mov_b32_e32 v165, v17
	s_waitcnt lgkmcnt(0)
	s_barrier
	s_and_saveexec_b64 s[22:23], s[12:13]
	s_cbranch_execz .LBB0_650
	v_lshlrev_b32_e32 v2, 2, v53
	s_mov_b32 s4, 0x9300
	v_mov_b32_e32 v165, 0
	v_cmp_gt_u32_e64 s[12:13], 32, v151
	v_add3_u32 v195, v142, v2, s4
	v_add_u32_e32 v196, 0x120, v50
	s_mov_b32 s30, 4
	s_mov_b64 s[64:65], 0
	v_mov_b32_e32 v18, 0
	v_mov_b32_e32 v19, v165
	v_mov_b32_e32 v20, v165
	v_mov_b32_e32 v21, v165
	v_mov_b32_e32 v22, v165
	v_mov_b32_e32 v23, v165
	v_mov_b32_e32 v24, v165
	v_mov_b32_e32 v25, v165
	v_mov_b32_e32 v26, v165
	v_mov_b32_e32 v27, v165
	v_mov_b32_e32 v28, v165
	v_mov_b32_e32 v29, v165
	v_mov_b32_e32 v30, v165
	v_mov_b32_e32 v31, v165
	v_mov_b32_e32 v32, v165
	v_mov_b32_e32 v33, v165
	v_mov_b32_e32 v2, 0
	v_mov_b32_e32 v3, v165
	v_mov_b32_e32 v4, v165
	v_mov_b32_e32 v5, v165
	v_mov_b32_e32 v6, v165
	v_mov_b32_e32 v7, v165
	v_mov_b32_e32 v8, v165
	v_mov_b32_e32 v9, v165
	v_mov_b32_e32 v10, v165
	v_mov_b32_e32 v11, v165
	v_mov_b32_e32 v12, v165
	v_mov_b32_e32 v13, v165
	v_mov_b32_e32 v14, v165
	v_mov_b32_e32 v15, v165
	v_mov_b32_e32 v16, v165
	v_mov_b32_e32 v17, v165
	s_branch .LBB0_632

.LBB0_631:
	v_sub_f32_e32 v50, v50, v64
	v_sub_f32_e32 v51, v51, v64
	v_sub_f32_e32 v98, v116, v64
	v_sub_f32_e32 v99, v117, v64
	v_exp_f32_e32 v110, v50
	v_exp_f32_e32 v111, v51
	v_sub_f32_e32 v50, v52, v64
	v_sub_f32_e32 v51, v53, v64
	v_exp_f32_e32 v112, v98
	v_exp_f32_e32 v108, v50
	v_exp_f32_e32 v109, v51
	v_sub_f32_e32 v50, v54, v64
	v_sub_f32_e32 v51, v55, v64
	v_exp_f32_e32 v113, v99
	v_exp_f32_e32 v106, v50
	v_exp_f32_e32 v107, v51
	v_sub_f32_e32 v50, v56, v64
	v_sub_f32_e32 v51, v57, v64
	s_and_b64 s[4:5], exec, s[14:15]
	v_exp_f32_e32 v104, v50
	v_exp_f32_e32 v105, v51
	v_sub_f32_e32 v50, v58, v64
	v_sub_f32_e32 v51, v59, v64
	v_sub_f32_e32 v126, v34, v64
	v_exp_f32_e32 v102, v50
	v_exp_f32_e32 v103, v51
	v_sub_f32_e32 v50, v60, v64
	v_sub_f32_e32 v51, v61, v64
	v_add_f32_e32 v34, v158, v159
	v_exp_f32_e32 v100, v50
	v_exp_f32_e32 v101, v51
	v_sub_f32_e32 v50, v62, v64
	v_sub_f32_e32 v51, v63, v64
	s_or_b64 s[64:65], s[4:5], s[64:65]
	v_exp_f32_e32 v98, v50
	v_exp_f32_e32 v99, v51
	v_fmac_f32_e32 v34, v163, v165
	v_add_f32_e32 v165, v160, v161
	v_sub_f32_e32 v127, v35, v64
	v_sub_f32_e32 v128, v36, v64
	v_sub_f32_e32 v129, v37, v64
	v_sub_f32_e32 v198, v38, v64
	v_sub_f32_e32 v119, v39, v64
	v_sub_f32_e32 v120, v40, v64
	v_sub_f32_e32 v121, v41, v64
	v_sub_f32_e32 v122, v42, v64
	v_sub_f32_e32 v123, v43, v64
	v_sub_f32_e32 v124, v44, v64
	v_sub_f32_e32 v125, v45, v64
	v_sub_f32_e32 v115, v46, v64
	v_sub_f32_e32 v116, v47, v64
	v_sub_f32_e32 v117, v48, v64
	v_sub_f32_e32 v118, v49, v64
	v_fmac_f32_e32 v165, v34, v197
	v_add_u32_e32 v195, 0x200, v195
	v_add_u32_e32 v196, 0x80, v196
	s_add_i32 s30, s30, 2
	v_mov_b32_e32 v163, v65
	s_waitcnt lgkmcnt(0)
	s_barrier
	s_andn2_b64 exec, exec, s[64:65]
	s_cbranch_execz .LBB0_649
.LBB0_632:
	ds_read_b128 v[34:37], v166 offset:24576
	ds_read_b128 v[50:53], v166 offset:28672
	ds_read_b128 v[158:161], v169 offset:24576
	ds_read_b128 v[200:203], v169 offset:28672
	v_exp_f32_e32 v204, v117
	v_exp_f32_e32 v126, v126
	s_waitcnt lgkmcnt(3)
	v_mfma_f32_32x32x16_bf16 v[34:49], v[34:37], v[78:81], 0
	v_exp_f32_e32 v127, v127
	v_exp_f32_e32 v128, v128
	v_exp_f32_e32 v129, v129
	v_exp_f32_e32 v180, v120
	v_exp_f32_e32 v181, v121
	v_exp_f32_e32 v182, v122
	v_exp_f32_e32 v183, v123
	s_waitcnt lgkmcnt(2)
	v_mfma_f32_32x32x16_bf16 v[50:65], v[50:53], v[78:81], 0
	v_exp_f32_e32 v205, v118
	v_cvt_pk_bf16_f32 v118, v108, v109
	v_cvt_pk_bf16_f32 v120, v104, v105
	v_cvt_pk_bf16_f32 v121, v102, v103
	v_cvt_pk_bf16_f32 v122, v100, v101
	v_cvt_pk_bf16_f32 v123, v98, v99
	s_waitcnt lgkmcnt(0)
	v_mfma_f32_32x32x16_bf16 v[50:65], v[200:203], v[74:77], v[50:65]
	v_permlane32_swap_b32_e32 v120, v122
	v_permlane32_swap_b32_e32 v121, v123
	v_mfma_f32_32x32x16_bf16 v[34:49], v[158:161], v[74:77], v[34:49]
	ds_read_b128 v[158:161], v192 offset:24576
	ds_read_b128 v[200:203], v192 offset:28672
	s_waitcnt lgkmcnt(0)
	v_mfma_f32_32x32x16_bf16 v[50:65], v[200:203], v[70:73], v[50:65]
	v_mfma_f32_32x32x16_bf16 v[34:49], v[158:161], v[70:73], v[34:49]
	ds_read_b128 v[158:161], v191 offset:24576
	ds_read_b128 v[200:203], v191 offset:28672
	s_waitcnt lgkmcnt(0)
	v_mfma_f32_32x32x16_bf16 v[50:65], v[200:203], v[66:69], v[50:65]
	v_exp_f32_e32 v203, v116
	v_add_f32_e32 v116, 0, v112
	v_add_f32_e32 v117, 0, v113
	v_exp_f32_e32 v200, v124
	v_add_f32_e32 v116, v110, v116
	v_add_f32_e32 v117, v111, v117
	v_exp_f32_e32 v201, v125
	v_add_f32_e32 v116, v108, v116
	v_add_f32_e32 v117, v109, v117
	v_exp_f32_e32 v202, v115
	v_add_f32_e32 v116, v106, v116
	v_add_f32_e32 v117, v107, v117
	v_mfma_f32_32x32x16_bf16 v[34:49], v[158:161], v[66:69], v[34:49]
	v_add_f32_e64 v116, v104, v116
	v_add_f32_e64 v117, v105, v117
	v_exp_f32_e32 v160, v198
	v_add_f32_e32 v116, v102, v116
	v_add_f32_e32 v117, v103, v117
	v_exp_f32_e32 v161, v119
	v_add_f32_e32 v116, v100, v116
	v_add_f32_e32 v117, v101, v117
	v_cvt_pk_bf16_f32 v119, v106, v107
	v_cvt_pk_bf16_f32 v124, v126, v127
	v_cvt_pk_bf16_f32 v125, v128, v129
	v_cvt_pk_bf16_f32 v198, v182, v183
	v_cvt_pk_bf16_f32 v199, v200, v201
	s_nop 0
	v_add_f32_e32 v116, v98, v116
	v_add_f32_e32 v117, v99, v117
	s_nop 0
	v_add_f32_e32 v116, v126, v116
	v_add_f32_e32 v117, v127, v117
	v_cvt_pk_bf16_f32 v126, v160, v161
	v_cvt_pk_bf16_f32 v127, v180, v181
	s_nop 0
	v_add_f32_e32 v116, v128, v116
	v_add_f32_e32 v117, v129, v117
	v_permlane32_swap_b32_e32 v124, v126
	v_add_f32_e32 v116, v160, v116
	v_add_f32_e32 v117, v161, v117
	v_permlane32_swap_b32_e32 v125, v127
	v_add_f32_e32 v116, v180, v116
	v_add_f32_e32 v117, v181, v117
	s_nop 0
	v_add_f32_e32 v116, v182, v116
	v_add_f32_e32 v117, v183, v117
	s_nop 0
	v_add_f32_e32 v116, v200, v116
	v_add_f32_e32 v117, v201, v117
	v_cvt_pk_bf16_f32 v200, v202, v203
	v_cvt_pk_bf16_f32 v201, v204, v205
	s_nop 0
	v_add_f32_e32 v116, v202, v116
	v_add_f32_e32 v117, v203, v117
	v_permlane32_swap_b32_e32 v198, v200
	v_add_f32_e32 v116, v204, v116
	v_add_f32_e32 v117, v205, v117
	v_permlane32_swap_b32_e32 v199, v201
	v_add_f32_e32 v158, v116, v117
	v_add_f32_e32 v159, v117, v116
	v_cvt_pk_bf16_f32 v116, v112, v113
	v_cvt_pk_bf16_f32 v117, v110, v111
	s_nop 0
	v_mov_b32_e32 v159, v158
	s_nop 1
	v_permlane32_swap_b32_e32 v158, v159
	v_permlane32_swap_b32_e32 v116, v118
	v_permlane32_swap_b32_e32 v117, v119
	v_add_u32_e32 v98, 0xffffffa0, v196
	v_mad_i64_i32 v[98:99], s[4:5], v98, s86, 0
	v_or_b32_e32 v98, v98, v141
	v_lshl_add_u64 v[102:103], v[98:99], 1, v[144:145]
	v_subrev_u32_e32 v98, 64, v196
	v_mad_i64_i32 v[98:99], s[4:5], v98, s86, 0
	v_or_b32_e32 v98, v98, v141
	v_lshl_add_u64 v[106:107], v[98:99], 1, v[144:145]
	flat_load_dwordx4 v[98:101], v[102:103] offset:1024
	s_nop 0
	flat_load_dwordx4 v[102:105], v[102:103] offset:512
	s_nop 0
	flat_load_dwordx4 v[110:113], v[106:107] offset:1024
	s_nop 0
	flat_load_dwordx4 v[106:109], v[106:107] offset:512
	ds_read_b64_tr_b16 v[202:203], v194 offset:0
	ds_read_b64_tr_b16 v[204:205], v194 offset:0x400
	ds_read_b64_tr_b16 v[206:207], v194 offset:0x800
	ds_read_b64_tr_b16 v[208:209], v194 offset:0xc00
	ds_read_b64_tr_b16 v[210:211], v194 offset:0x1000
	ds_read_b64_tr_b16 v[212:213], v194 offset:0x1400
	ds_read_b64_tr_b16 v[214:215], v194 offset:0x1800
	ds_read_b64_tr_b16 v[216:217], v194 offset:0x1c00
	s_waitcnt lgkmcnt(0)
	s_nop 0
	v_mfma_f32_32x32x16_bf16 v[18:33], v[116:119], v[202:205], v[18:33]
	ds_read_b64_tr_b16 v[202:203], v194 offset:0x200
	ds_read_b64_tr_b16 v[204:205], v194 offset:0x600
	v_mfma_f32_32x32x16_bf16 v[18:33], v[120:123], v[206:209], v[18:33]
	ds_read_b64_tr_b16 v[206:207], v194 offset:0xa00
	ds_read_b64_tr_b16 v[208:209], v194 offset:0xe00
	v_mfma_f32_32x32x16_bf16 v[18:33], v[124:127], v[210:213], v[18:33]
	ds_read_b64_tr_b16 v[210:211], v194 offset:0x1200
	ds_read_b64_tr_b16 v[212:213], v194 offset:0x1600
	v_mfma_f32_32x32x16_bf16 v[18:33], v[198:201], v[214:217], v[18:33]
	ds_read_b64_tr_b16 v[214:215], v194 offset:0x1a00
	ds_read_b64_tr_b16 v[216:217], v194 offset:0x1e00
	s_waitcnt lgkmcnt(0)
	v_mfma_f32_32x32x16_bf16 v[2:17], v[116:119], v[202:205], v[2:17]
	ds_read2_b32 v[116:117], v195 offset1:1
	ds_read2_b32 v[118:119], v195 offset0:32 offset1:33
	s_waitcnt lgkmcnt(0)
	v_add_f32_e64 v116, v34, v116
	v_add_f32_e64 v117, v35, v117
	v_add_f32_e32 v34, v50, v118
	v_add_f32_e32 v35, v51, v119
	ds_read2_b32 v[50:51], v195 offset0:2 offset1:3
	ds_read2_b32 v[118:119], v195 offset0:34 offset1:35
	v_mfma_f32_32x32x16_bf16 v[2:17], v[120:123], v[206:209], v[2:17]
	s_waitcnt lgkmcnt(0)
	v_add_f32_e64 v50, v36, v50
	v_add_f32_e64 v51, v37, v51
	v_add_f32_e64 v36, v52, v118
	v_add_f32_e64 v37, v53, v119
	ds_read2_b32 v[52:53], v195 offset0:8 offset1:9
	ds_read2_b32 v[118:119], v195 offset0:40 offset1:41
	s_waitcnt lgkmcnt(0)
	v_add_f32_e32 v52, v38, v52
	v_add_f32_e32 v53, v39, v53
	v_add_f32_e32 v38, v54, v118
	v_add_f32_e32 v39, v55, v119
	ds_read2_b32 v[54:55], v195 offset0:10 offset1:11
	ds_read2_b32 v[118:119], v195 offset0:42 offset1:43
	v_mfma_f32_32x32x16_bf16 v[2:17], v[124:127], v[210:213], v[2:17]
	s_waitcnt lgkmcnt(0)
	v_add_f32_e64 v54, v40, v54
	v_add_f32_e64 v55, v41, v55
	v_add_f32_e64 v40, v56, v118
	v_add_f32_e64 v41, v57, v119
	ds_read2_b32 v[56:57], v195 offset0:16 offset1:17
	ds_read2_b32 v[118:119], v195 offset0:48 offset1:49
	s_waitcnt lgkmcnt(0)
	v_add_f32_e32 v56, v42, v56
	v_add_f32_e32 v57, v43, v57
	v_add_f32_e32 v42, v58, v118
	v_add_f32_e32 v43, v59, v119
	ds_read2_b32 v[58:59], v195 offset0:18 offset1:19
	ds_read2_b32 v[118:119], v195 offset0:50 offset1:51
	v_mfma_f32_32x32x16_bf16 v[2:17], v[198:201], v[214:217], v[2:17]
	s_waitcnt lgkmcnt(0)
	v_add_f32_e64 v58, v44, v58
	v_add_f32_e64 v59, v45, v59
	v_add_f32_e64 v44, v60, v118
	v_add_f32_e64 v45, v61, v119
	ds_read2_b32 v[60:61], v195 offset0:24 offset1:25
	ds_read2_b32 v[118:119], v195 offset0:56 offset1:57
	s_waitcnt lgkmcnt(0)
	v_add_f32_e32 v60, v46, v60
	v_add_f32_e32 v61, v47, v61
	v_add_f32_e32 v46, v62, v118
	v_add_f32_e32 v47, v63, v119
	ds_read2_b32 v[62:63], v195 offset0:26 offset1:27
	ds_read2_b32 v[118:119], v195 offset0:58 offset1:59
	s_waitcnt lgkmcnt(0)
	v_add_f32_e32 v62, v48, v62
	v_add_f32_e32 v63, v49, v63
	v_add_f32_e32 v48, v64, v118
	v_add_f32_e32 v49, v65, v119
	v_max_f32_e32 v64, v116, v117
	v_max3_f32 v64, v64, v50, v51
	v_max3_f32 v64, v64, v52, v53
	v_max3_f32 v64, v64, v54, v55
	v_max3_f32 v64, v64, v56, v57
	v_max3_f32 v64, v64, v58, v59
	v_max3_f32 v64, v64, v60, v61
	v_max3_f32 v64, v64, v62, v63
	v_max3_f32 v64, v64, v34, v35
	v_max3_f32 v64, v64, v36, v37
	v_max3_f32 v64, v64, v38, v39
	v_max3_f32 v64, v64, v40, v41
	v_max3_f32 v64, v64, v42, v43
	v_max3_f32 v64, v64, v44, v45
	v_max3_f32 v64, v64, v46, v47
	v_max3_f32 v64, v64, v48, v49
	v_mov_b32_e32 v65, v64
	s_nop 1
	v_permlane32_swap_b32_e32 v64, v65
	v_max_f32_e32 v65, v65, v65
	v_max_f32_e32 v64, v64, v64
	v_max_f32_e32 v64, v64, v65
	v_sub_f32_e32 v65, v64, v114
	v_cmp_ge_f32_e32 vcc, s0, v65
	s_cmp_lg_u64 vcc, exec
	s_cbranch_scc1 .LBB0_647
	v_mov_b32_e32 v64, v114

.LBB0_639:
	v_mov_b32_e32 v65, v64
	v_sub_f32_e32 v50, v50, v64
	v_sub_f32_e32 v51, v51, v64
	v_sub_f32_e32 v114, v116, v64
	v_sub_f32_e32 v115, v117, v64
	v_exp_f32_e32 v128, v50
	v_exp_f32_e32 v129, v51
	v_sub_f32_e32 v50, v52, v64
	v_sub_f32_e32 v51, v53, v64
	v_exp_f32_e32 v114, v114
	v_exp_f32_e32 v116, v50
	v_exp_f32_e32 v117, v51
	v_sub_f32_e32 v50, v54, v64
	v_sub_f32_e32 v51, v55, v64
	v_exp_f32_e32 v115, v115
	v_exp_f32_e32 v126, v50
	v_exp_f32_e32 v127, v51
	v_sub_f32_e32 v50, v56, v64
	v_sub_f32_e32 v51, v57, v64
	v_sub_f32_e32 v160, v34, v64
	v_sub_f32_e32 v161, v35, v65
	v_exp_f32_e32 v118, v50
	v_exp_f32_e32 v119, v51
	v_sub_f32_e32 v50, v58, v64
	v_sub_f32_e32 v51, v59, v64
	v_sub_f32_e32 v180, v36, v64
	v_sub_f32_e32 v181, v37, v65
	v_exp_f32_e32 v124, v50
	v_exp_f32_e32 v125, v51
	v_sub_f32_e32 v50, v60, v64
	v_sub_f32_e32 v51, v61, v64
	v_sub_f32_e32 v182, v38, v64
	v_sub_f32_e32 v183, v39, v65
	v_exp_f32_e32 v120, v50
	v_exp_f32_e32 v121, v51
	v_sub_f32_e32 v50, v62, v64
	v_sub_f32_e32 v51, v63, v64
	v_sub_f32_e32 v208, v40, v64
	v_sub_f32_e32 v209, v41, v65
	v_exp_f32_e32 v122, v50
	v_exp_f32_e32 v123, v51
	v_sub_f32_e32 v210, v42, v64
	v_sub_f32_e32 v211, v43, v65
	v_sub_f32_e32 v212, v44, v64
	v_sub_f32_e32 v213, v45, v65
	v_sub_f32_e32 v214, v46, v64
	v_sub_f32_e32 v215, v47, v65
	v_sub_f32_e32 v216, v48, v64
	v_sub_f32_e32 v217, v49, v65
	s_waitcnt lgkmcnt(0)
	s_barrier
	ds_read_b128 v[34:37], v166 offset:16384
	ds_read_b128 v[50:53], v166 offset:20480
	ds_read_b128 v[200:203], v169 offset:16384
	ds_read_b128 v[204:207], v169 offset:20480
	v_exp_f32_e32 v180, v180
	v_exp_f32_e32 v181, v181
	s_waitcnt lgkmcnt(0)
	v_mfma_f32_32x32x16_bf16 v[34:49], v[34:37], v[78:81], 0
	v_exp_f32_e32 v182, v182
	v_exp_f32_e32 v183, v183
	v_mfma_f32_32x32x16_bf16 v[50:65], v[50:53], v[78:81], 0
	v_mfma_f32_32x32x16_bf16 v[34:49], v[200:203], v[74:77], v[34:49]
	v_mfma_f32_32x32x16_bf16 v[50:65], v[204:207], v[74:77], v[50:65]
	ds_read_b128 v[200:203], v192 offset:16384
	ds_read_b128 v[204:207], v192 offset:20480
	s_waitcnt lgkmcnt(0)
	v_mfma_f32_32x32x16_bf16 v[34:49], v[200:203], v[70:73], v[34:49]
	v_mfma_f32_32x32x16_bf16 v[50:65], v[204:207], v[70:73], v[50:65]
	ds_read_b128 v[200:203], v191 offset:16384
	ds_read_b128 v[204:207], v191 offset:20480
	s_waitcnt lgkmcnt(0)
	v_mfma_f32_32x32x16_bf16 v[34:49], v[200:203], v[66:69], v[34:49]
	v_exp_f32_e32 v200, v160
	v_exp_f32_e32 v201, v161
	v_add_f32_e32 v160, 0, v114
	v_add_f32_e32 v161, 0, v115
	v_exp_f32_e32 v202, v208
	v_add_f32_e32 v160, v128, v160
	v_add_f32_e32 v161, v129, v161
	v_exp_f32_e32 v203, v209
	v_add_f32_e32 v160, v116, v160
	v_add_f32_e32 v161, v117, v161
	v_mfma_f32_32x32x16_bf16 v[50:65], v[204:207], v[66:69], v[50:65]
	v_add_f32_e64 v160, v126, v160
	v_add_f32_e64 v161, v127, v161
	v_exp_f32_e32 v204, v210
	v_add_f32_e32 v160, v118, v160
	v_add_f32_e32 v161, v119, v161
	v_exp_f32_e32 v205, v211
	v_add_f32_e32 v160, v124, v160
	v_add_f32_e32 v161, v125, v161
	v_exp_f32_e32 v206, v212
	v_add_f32_e32 v160, v120, v160
	v_add_f32_e32 v161, v121, v161
	v_exp_f32_e32 v207, v213
	v_add_f32_e32 v160, v122, v160
	v_add_f32_e32 v161, v123, v161
	v_exp_f32_e32 v208, v214
	v_add_f32_e32 v160, v200, v160
	v_add_f32_e32 v161, v201, v161
	v_exp_f32_e32 v209, v215
	v_add_f32_e32 v160, v180, v160
	v_add_f32_e32 v161, v181, v161
	v_exp_f32_e32 v210, v216
	v_add_f32_e32 v160, v182, v160
	v_add_f32_e32 v161, v183, v161
	v_exp_f32_e32 v211, v217
	v_add_f32_e32 v160, v202, v160
	v_add_f32_e32 v161, v203, v161
	v_cvt_pk_bf16_f32 v114, v114, v115
	v_cvt_pk_bf16_f32 v115, v128, v129
	v_cvt_pk_bf16_f32 v116, v116, v117
	v_cvt_pk_bf16_f32 v117, v126, v127
	v_cvt_pk_bf16_f32 v118, v118, v119
	s_nop 0
	v_add_f32_e32 v160, v204, v160
	v_add_f32_e32 v161, v205, v161
	v_cvt_pk_bf16_f32 v119, v124, v125
	v_cvt_pk_bf16_f32 v120, v120, v121
	v_cvt_pk_bf16_f32 v121, v122, v123
	v_cvt_pk_bf16_f32 v122, v200, v201
	v_cvt_pk_bf16_f32 v123, v180, v181
	s_nop 0
	v_add_f32_e32 v160, v206, v160
	v_add_f32_e32 v161, v207, v161
	v_cvt_pk_bf16_f32 v124, v182, v183
	v_cvt_pk_bf16_f32 v125, v202, v203
	v_cvt_pk_bf16_f32 v126, v204, v205
	v_cvt_pk_bf16_f32 v127, v206, v207
	v_cvt_pk_bf16_f32 v128, v208, v209
	s_nop 0
	v_add_f32_e32 v160, v208, v160
	v_add_f32_e32 v161, v209, v161
	v_cvt_pk_bf16_f32 v129, v210, v211
	v_permlane32_swap_b32_e32 v114, v116
	v_add_f32_e32 v160, v210, v160
	v_add_f32_e32 v161, v211, v161
	v_permlane32_swap_b32_e32 v115, v117
	v_pk_add_f32 v[160:161], v[160:161], v[160:161] op_sel:[0,1] op_sel_hi:[1,0]
	v_permlane32_swap_b32_e32 v118, v120
	v_mov_b32_e32 v161, v160
	s_nop 1
	v_permlane32_swap_b32_e32 v160, v161
	v_permlane32_swap_b32_e32 v119, v121
	v_permlane32_swap_b32_e32 v122, v124
	v_permlane32_swap_b32_e32 v123, v125
	v_permlane32_swap_b32_e32 v126, v128
	v_permlane32_swap_b32_e32 v127, v129
	v_cmp_lt_i32_e32 vcc, s30, v193
	v_cmp_ge_i32_e64 s[14:15], s30, v193
	s_and_saveexec_b64 s[8:9], vcc
	s_cbranch_execz .LBB0_641
	v_subrev_u32_e32 v82, 32, v196
	v_mad_i64_i32 v[82:83], s[4:5], v82, s86, 0
	v_or_b32_e32 v82, v82, v141
	v_lshl_add_u64 v[86:87], v[82:83], 1, v[144:145]
	v_mad_i64_i32 v[82:83], s[4:5], v196, s86, 0
	v_or_b32_e32 v82, v82, v141
	v_lshl_add_u64 v[94:95], v[82:83], 1, v[144:145]
	flat_load_dwordx4 v[82:85], v[86:87] offset:1024
	s_nop 0
	flat_load_dwordx4 v[86:89], v[86:87] offset:512
	s_nop 0
	flat_load_dwordx4 v[90:93], v[94:95] offset:1024
	s_nop 0
	flat_load_dwordx4 v[94:97], v[94:95] offset:512
.LBB0_641:
	s_or_b64 exec, exec, s[8:9]
	ds_read_b64_tr_b16 v[200:201], v162 offset:0
	ds_read_b64_tr_b16 v[202:203], v162 offset:0x400
	ds_read_b64_tr_b16 v[204:205], v162 offset:0x800
	ds_read_b64_tr_b16 v[206:207], v162 offset:0xc00
	ds_read_b64_tr_b16 v[208:209], v162 offset:0x1000
	ds_read_b64_tr_b16 v[210:211], v162 offset:0x1400
	ds_read_b64_tr_b16 v[212:213], v162 offset:0x1800
	ds_read_b64_tr_b16 v[214:215], v162 offset:0x1c00
	s_waitcnt lgkmcnt(0)
	s_nop 0
	v_mfma_f32_32x32x16_bf16 v[18:33], v[114:117], v[200:203], v[18:33]
	ds_read_b64_tr_b16 v[200:201], v162 offset:0x200
	ds_read_b64_tr_b16 v[202:203], v162 offset:0x600
	v_mfma_f32_32x32x16_bf16 v[18:33], v[118:121], v[204:207], v[18:33]
	ds_read_b64_tr_b16 v[204:205], v162 offset:0xa00
	ds_read_b64_tr_b16 v[206:207], v162 offset:0xe00
	v_mfma_f32_32x32x16_bf16 v[18:33], v[122:125], v[208:211], v[18:33]
	ds_read_b64_tr_b16 v[208:209], v162 offset:0x1200
	ds_read_b64_tr_b16 v[210:211], v162 offset:0x1600
	v_mfma_f32_32x32x16_bf16 v[18:33], v[126:129], v[212:215], v[18:33]
	ds_read_b64_tr_b16 v[212:213], v162 offset:0x1a00
	ds_read_b64_tr_b16 v[214:215], v162 offset:0x1e00
	s_waitcnt lgkmcnt(0)
	v_mfma_f32_32x32x16_bf16 v[2:17], v[114:117], v[200:203], v[2:17]
	v_mfma_f32_32x32x16_bf16 v[2:17], v[118:121], v[204:207], v[2:17]
	ds_read2_b32 v[114:115], v195 offset0:64 offset1:65
	ds_read2_b32 v[118:119], v195 offset0:96 offset1:97
	s_waitcnt lgkmcnt(0)
	v_add_f32_e64 v116, v34, v114
	v_add_f32_e64 v117, v35, v115
	v_add_f32_e32 v34, v50, v118
	v_add_f32_e32 v35, v51, v119
	ds_read2_b32 v[50:51], v195 offset0:66 offset1:67
	ds_read2_b32 v[114:115], v195 offset0:98 offset1:99
	v_mfma_f32_32x32x16_bf16 v[2:17], v[122:125], v[208:211], v[2:17]
	s_waitcnt lgkmcnt(0)
	v_add_f32_e64 v50, v36, v50
	v_add_f32_e64 v51, v37, v51
	v_add_f32_e64 v36, v52, v114
	v_add_f32_e64 v37, v53, v115
	ds_read2_b32 v[52:53], v195 offset0:72 offset1:73
	ds_read2_b32 v[114:115], v195 offset0:104 offset1:105
	s_waitcnt lgkmcnt(0)
	v_add_f32_e32 v52, v38, v52
	v_add_f32_e32 v53, v39, v53
	v_add_f32_e32 v38, v54, v114
	v_add_f32_e32 v39, v55, v115
	ds_read2_b32 v[54:55], v195 offset0:74 offset1:75
	ds_read2_b32 v[114:115], v195 offset0:106 offset1:107
	v_mfma_f32_32x32x16_bf16 v[2:17], v[126:129], v[212:215], v[2:17]
	s_waitcnt lgkmcnt(0)
	v_add_f32_e64 v54, v40, v54
	v_add_f32_e64 v55, v41, v55
	v_add_f32_e64 v40, v56, v114
	v_add_f32_e64 v41, v57, v115
	ds_read2_b32 v[56:57], v195 offset0:80 offset1:81
	ds_read2_b32 v[114:115], v195 offset0:112 offset1:113
	s_waitcnt lgkmcnt(0)
	v_add_f32_e32 v56, v42, v56
	v_add_f32_e32 v57, v43, v57
	v_add_f32_e32 v42, v58, v114
	v_add_f32_e32 v43, v59, v115
	ds_read2_b32 v[58:59], v195 offset0:82 offset1:83
	ds_read2_b32 v[114:115], v195 offset0:114 offset1:115
	s_waitcnt lgkmcnt(0)
	v_add_f32_e32 v58, v44, v58
	v_add_f32_e32 v59, v45, v59
	v_add_f32_e32 v44, v60, v114
	v_add_f32_e32 v45, v61, v115
	ds_read2_b32 v[60:61], v195 offset0:88 offset1:89
	ds_read2_b32 v[114:115], v195 offset0:120 offset1:121
	s_waitcnt lgkmcnt(0)
	v_add_f32_e32 v60, v46, v60
	v_add_f32_e32 v61, v47, v61
	v_add_f32_e32 v46, v62, v114
	v_add_f32_e32 v47, v63, v115
	ds_read2_b32 v[62:63], v195 offset0:90 offset1:91
	ds_read2_b32 v[114:115], v195 offset0:122 offset1:123
	s_waitcnt lgkmcnt(0)
	v_add_f32_e32 v62, v48, v62
	v_add_f32_e32 v63, v49, v63
	v_add_f32_e32 v48, v64, v114
	v_add_f32_e32 v49, v65, v115
	v_max_f32_e32 v64, v116, v117
	v_max3_f32 v64, v64, v50, v51
	v_max3_f32 v64, v64, v52, v53
	v_max3_f32 v64, v64, v54, v55
	v_max3_f32 v64, v64, v56, v57
	v_max3_f32 v64, v64, v58, v59
	v_max3_f32 v64, v64, v60, v61
	v_max3_f32 v64, v64, v62, v63
	v_max3_f32 v64, v64, v34, v35
	v_max3_f32 v64, v64, v36, v37
	v_max3_f32 v64, v64, v38, v39
	v_max3_f32 v64, v64, v40, v41
	v_max3_f32 v64, v64, v42, v43
	v_max3_f32 v64, v64, v44, v45
	v_max3_f32 v64, v64, v46, v47
	v_max3_f32 v64, v64, v48, v49
	v_mov_b32_e32 v65, v64
	s_nop 1
	v_permlane32_swap_b32_e32 v64, v65
	v_max_f32_e32 v65, v65, v65
	v_max_f32_e32 v64, v64, v64
	v_max_f32_e32 v64, v64, v65
	v_sub_f32_e32 v65, v64, v198
	v_cmp_ge_f32_e32 vcc, s0, v65
	s_cmp_lg_u64 vcc, exec
	s_cbranch_scc1 .LBB0_648
	v_mov_b32_e32 v64, v198

.LBB0_650:
	s_or_b64 exec, exec, s[22:23]
	v_lshlrev_b32_e32 v82, 6, v136
	v_ashrrev_i32_e32 v141, 31, v140
	ds_read_b128 v[34:37], v166 offset:24576
	ds_read_b128 v[50:53], v166 offset:28672
	v_exp_f32_e32 v88, v124
	v_exp_f32_e32 v89, v125
	v_exp_f32_e32 v90, v115
	s_waitcnt lgkmcnt(1)
	v_mfma_f32_32x32x16_bf16 v[34:49], v[34:37], v[78:81], 0
	v_exp_f32_e32 v91, v116
	v_exp_f32_e32 v92, v117
	v_exp_f32_e32 v93, v118
	s_waitcnt lgkmcnt(0)
	v_mfma_f32_32x32x16_bf16 v[50:65], v[50:53], v[78:81], 0
	ds_read_b128 v[78:81], v169 offset:24576
	ds_read_b128 v[84:87], v169 offset:28672
	s_waitcnt lgkmcnt(1)
	v_mfma_f32_32x32x16_bf16 v[34:49], v[78:81], v[74:77], v[34:49]
	s_waitcnt lgkmcnt(0)
	v_mfma_f32_32x32x16_bf16 v[50:65], v[84:87], v[74:77], v[50:65]
	ds_read_b128 v[74:77], v192 offset:24576
	ds_read_b128 v[78:81], v192 offset:28672
	v_exp_f32_e32 v84, v120
	v_exp_f32_e32 v85, v121
	v_exp_f32_e32 v86, v122
	v_exp_f32_e32 v87, v123
	s_waitcnt lgkmcnt(1)
	v_mfma_f32_32x32x16_bf16 v[34:49], v[74:77], v[70:73], v[34:49]
	s_waitcnt lgkmcnt(0)
	v_mfma_f32_32x32x16_bf16 v[50:65], v[78:81], v[70:73], v[50:65]
	ds_read_b128 v[70:73], v191 offset:24576
	ds_read_b128 v[74:77], v191 offset:28672
	v_exp_f32_e32 v78, v128
	v_exp_f32_e32 v79, v129
	v_exp_f32_e32 v80, v198
	v_exp_f32_e32 v81, v119
	s_waitcnt lgkmcnt(1)
	v_mfma_f32_32x32x16_bf16 v[34:49], v[70:73], v[66:69], v[34:49]
	v_cvt_pk_bf16_f32 v70, v108, v109
	v_cvt_pk_bf16_f32 v71, v106, v107
	v_cvt_pk_bf16_f32 v72, v104, v105
	v_cvt_pk_bf16_f32 v73, v102, v103
	s_waitcnt lgkmcnt(0)
	v_mfma_f32_32x32x16_bf16 v[50:65], v[74:77], v[66:69], v[50:65]
	v_add_f32_e64 v66, v112, 0
	v_add_f32_e64 v67, v113, 0
	v_exp_f32_e32 v76, v126
	v_add_f32_e32 v66, v110, v66
	v_add_f32_e32 v67, v111, v67
	v_exp_f32_e32 v77, v127
	v_add_f32_e32 v66, v108, v66
	v_add_f32_e32 v67, v109, v67
	v_cvt_pk_bf16_f32 v68, v112, v113
	v_cvt_pk_bf16_f32 v69, v110, v111
	v_cvt_pk_bf16_f32 v74, v100, v101
	v_cvt_pk_bf16_f32 v75, v98, v99
	s_nop 0
	v_add_f32_e32 v66, v106, v66
	v_add_f32_e32 v67, v107, v67
	v_permlane32_swap_b32_e32 v68, v70
	v_add_f32_e32 v66, v104, v66
	v_add_f32_e32 v67, v105, v67
	v_permlane32_swap_b32_e32 v69, v71
	v_add_f32_e32 v66, v102, v66
	v_add_f32_e32 v67, v103, v67
	v_permlane32_swap_b32_e32 v72, v74
	v_add_f32_e32 v66, v100, v66
	v_add_f32_e32 v67, v101, v67
	v_permlane32_swap_b32_e32 v73, v75
	v_add_f32_e32 v66, v98, v66
	v_add_f32_e32 v67, v99, v67
	s_nop 0
	v_add_f32_e32 v66, v76, v66
	v_add_f32_e32 v67, v77, v67
	v_cvt_pk_bf16_f32 v76, v76, v77
	v_cvt_pk_bf16_f32 v77, v78, v79
	s_nop 0
	v_add_f32_e32 v66, v78, v66
	v_add_f32_e32 v67, v79, v67
	v_cvt_pk_bf16_f32 v78, v80, v81
	v_cvt_pk_bf16_f32 v79, v84, v85
	s_nop 0
	v_add_f32_e32 v66, v80, v66
	v_add_f32_e32 v67, v81, v67
	v_permlane32_swap_b32_e32 v76, v78
	v_add_f32_e32 v66, v84, v66
	v_add_f32_e32 v67, v85, v67
	v_cvt_pk_bf16_f32 v84, v86, v87
	v_cvt_pk_bf16_f32 v85, v88, v89
	v_permlane32_swap_b32_e32 v77, v79
	v_add_f32_e32 v66, v86, v66
	v_add_f32_e32 v67, v87, v67
	v_cvt_pk_bf16_f32 v86, v90, v91
	v_cvt_pk_bf16_f32 v87, v92, v93
	s_nop 0
	v_add_f32_e32 v66, v88, v66
	v_add_f32_e32 v67, v89, v67
	v_permlane32_swap_b32_e32 v84, v86
	v_add_f32_e32 v66, v90, v66
	v_add_f32_e32 v67, v91, v67
	v_permlane32_swap_b32_e32 v85, v87
	v_add_f32_e32 v66, v92, v66
	v_add_f32_e32 v67, v93, v67
	s_nop 0
	v_pk_add_f32 v[66:67], v[66:67], v[66:67] op_sel:[0,1] op_sel_hi:[1,0]
	s_nop 0
	v_mov_b32_e32 v67, v66
	s_nop 1
	v_permlane32_swap_b32_e32 v66, v67
	ds_read_b64_tr_b16 v[88:89], v194 offset:0
	ds_read_b64_tr_b16 v[90:91], v194 offset:0x400
	ds_read_b64_tr_b16 v[92:93], v194 offset:0x800
	ds_read_b64_tr_b16 v[94:95], v194 offset:0xc00
	ds_read_b64_tr_b16 v[96:97], v194 offset:0x1000
	ds_read_b64_tr_b16 v[98:99], v194 offset:0x1400
	ds_read_b64_tr_b16 v[100:101], v194 offset:0x1800
	ds_read_b64_tr_b16 v[102:103], v194 offset:0x1c00
	s_waitcnt lgkmcnt(0)
	s_nop 0
	v_mfma_f32_32x32x16_bf16 v[18:33], v[68:71], v[88:91], v[18:33]
	ds_read_b64_tr_b16 v[88:89], v194 offset:0x200
	ds_read_b64_tr_b16 v[90:91], v194 offset:0x600
	v_mfma_f32_32x32x16_bf16 v[18:33], v[72:75], v[92:95], v[18:33]
	ds_read_b64_tr_b16 v[92:93], v194 offset:0xa00
	ds_read_b64_tr_b16 v[94:95], v194 offset:0xe00
	v_mfma_f32_32x32x16_bf16 v[18:33], v[76:79], v[96:99], v[18:33]
	ds_read_b64_tr_b16 v[96:97], v194 offset:0x1200
	ds_read_b64_tr_b16 v[98:99], v194 offset:0x1600
	v_mfma_f32_32x32x16_bf16 v[18:33], v[84:87], v[100:103], v[18:33]
	ds_read_b64_tr_b16 v[100:101], v194 offset:0x1a00
	ds_read_b64_tr_b16 v[102:103], v194 offset:0x1e00
	s_waitcnt lgkmcnt(0)
	v_mfma_f32_32x32x16_bf16 v[2:17], v[68:71], v[88:91], v[2:17]
	v_lshlrev_b32_e32 v68, 6, v193
	v_sub_u32_e32 v68, v68, v149
	v_lshlrev_b32_e32 v68, 2, v68
	v_lshlrev_b32_e32 v69, 2, v139
	v_mfma_f32_32x32x16_bf16 v[2:17], v[72:75], v[92:95], v[2:17]
	v_add3_u32 v72, v68, v69, v142
	v_add_u32_e32 v68, 0x9100, v72
	v_add_u32_e32 v70, 0x9180, v72
	ds_read2_b32 v[68:69], v68 offset1:1
	ds_read2_b32 v[70:71], v70 offset1:1
	s_waitcnt lgkmcnt(1)
	v_add_f32_e32 v68, v34, v68
	v_add_f32_e32 v69, v35, v69
	s_waitcnt lgkmcnt(0)
	v_add_f32_e32 v34, v50, v70
	v_add_f32_e32 v35, v51, v71
	v_add_u32_e32 v50, 0x9108, v72
	v_add_u32_e32 v70, 0x9188, v72
	ds_read2_b32 v[50:51], v50 offset1:1
	ds_read2_b32 v[70:71], v70 offset1:1
	v_mfma_f32_32x32x16_bf16 v[2:17], v[76:79], v[96:99], v[2:17]
	s_waitcnt lgkmcnt(1)
	v_add_f32_e64 v50, v36, v50
	v_add_f32_e64 v51, v37, v51
	s_waitcnt lgkmcnt(0)
	v_add_f32_e64 v36, v52, v70
	v_add_f32_e64 v37, v53, v71
	v_add_u32_e32 v52, 0x9120, v72
	v_add_u32_e32 v70, 0x91a0, v72
	ds_read2_b32 v[52:53], v52 offset1:1
	ds_read2_b32 v[70:71], v70 offset1:1
	v_mfma_f32_32x32x16_bf16 v[2:17], v[84:87], v[100:103], v[2:17]
	s_waitcnt lgkmcnt(1)
	v_add_f32_e64 v52, v38, v52
	v_add_f32_e64 v53, v39, v53
	s_waitcnt lgkmcnt(0)
	v_add_f32_e64 v38, v54, v70
	v_add_f32_e64 v39, v55, v71
	v_add_u32_e32 v54, 0x9128, v72
	v_add_u32_e32 v70, 0x91a8, v72
	ds_read2_b32 v[54:55], v54 offset1:1
	ds_read2_b32 v[70:71], v70 offset1:1
	s_waitcnt lgkmcnt(1)
	v_add_f32_e32 v54, v40, v54
	v_add_f32_e32 v55, v41, v55
	s_waitcnt lgkmcnt(0)
	v_add_f32_e32 v40, v56, v70
	v_add_f32_e32 v41, v57, v71
	v_add_u32_e32 v56, 0x9140, v72
	v_add_u32_e32 v70, 0x91c0, v72
	ds_read2_b32 v[56:57], v56 offset1:1
	ds_read2_b32 v[70:71], v70 offset1:1
	s_waitcnt lgkmcnt(1)
	v_add_f32_e32 v56, v42, v56
	v_add_f32_e32 v57, v43, v57
	s_waitcnt lgkmcnt(0)
	v_add_f32_e32 v42, v58, v70
	v_add_f32_e32 v43, v59, v71
	v_add_u32_e32 v58, 0x9148, v72
	v_add_u32_e32 v70, 0x91c8, v72
	ds_read2_b32 v[58:59], v58 offset1:1
	ds_read2_b32 v[70:71], v70 offset1:1
	s_waitcnt lgkmcnt(1)
	v_add_f32_e32 v58, v44, v58
	v_add_f32_e32 v59, v45, v59
	s_waitcnt lgkmcnt(0)
	v_add_f32_e32 v44, v60, v70
	v_add_f32_e32 v45, v61, v71
	v_add_u32_e32 v60, 0x9160, v72
	v_add_u32_e32 v70, 0x91e0, v72
	ds_read2_b32 v[60:61], v60 offset1:1
	ds_read2_b32 v[70:71], v70 offset1:1
	s_waitcnt lgkmcnt(1)
	v_add_f32_e32 v60, v46, v60
	v_add_f32_e32 v61, v47, v61
	s_waitcnt lgkmcnt(0)
	v_add_f32_e32 v46, v62, v70
	v_add_f32_e32 v47, v63, v71
	v_add_u32_e32 v62, 0x9168, v72
	v_add_u32_e32 v70, 0x91e8, v72
	ds_read2_b32 v[62:63], v62 offset1:1
	ds_read2_b32 v[70:71], v70 offset1:1
	s_waitcnt lgkmcnt(1)
	v_add_f32_e32 v62, v48, v62
	v_add_f32_e32 v63, v49, v63
	s_waitcnt lgkmcnt(0)
	v_add_f32_e32 v48, v64, v70
	v_add_f32_e32 v49, v65, v71
	v_max_f32_e32 v64, v68, v69
	v_max3_f32 v64, v64, v50, v51
	v_max3_f32 v64, v64, v52, v53
	v_max3_f32 v64, v64, v54, v55
	v_max3_f32 v64, v64, v56, v57
	v_max3_f32 v64, v64, v58, v59
	v_max3_f32 v64, v64, v60, v61
	v_max3_f32 v64, v64, v62, v63
	v_max3_f32 v64, v64, v34, v35
	v_max3_f32 v64, v64, v36, v37
	v_max3_f32 v64, v64, v38, v39
	v_max3_f32 v64, v64, v40, v41
	v_max3_f32 v64, v64, v42, v43
	v_max3_f32 v64, v64, v44, v45
	v_max3_f32 v64, v64, v46, v47
	v_max3_f32 v64, v64, v48, v49
	v_mov_b32_e32 v65, v64
	s_nop 1
	v_permlane32_swap_b32_e32 v64, v65
	v_max_f32_e32 v65, v65, v65
	v_max_f32_e32 v64, v64, v64
	v_max_f32_e32 v64, v64, v65
	v_sub_f32_e32 v65, v64, v114
	v_cmp_ge_f32_e32 vcc, s0, v65
	s_cmp_lg_u64 vcc, exec
	s_cbranch_scc1 .LBB0_839
	v_mov_b32_e32 v64, v114

.LBB0_657:
	v_mov_b32_e32 v65, v64
	v_sub_f32_e32 v68, v68, v64
	v_sub_f32_e32 v69, v69, v64
	v_sub_f32_e32 v50, v50, v64
	v_sub_f32_e32 v51, v51, v64
	v_exp_f32_e32 v74, v68
	v_exp_f32_e32 v75, v69
	v_exp_f32_e32 v72, v50
	v_exp_f32_e32 v73, v51
	v_sub_f32_e32 v50, v52, v64
	v_sub_f32_e32 v51, v53, v64
	v_sub_f32_e32 v34, v34, v64
	v_sub_f32_e32 v35, v35, v65
	v_exp_f32_e32 v70, v50
	v_exp_f32_e32 v71, v51
	v_sub_f32_e32 v50, v54, v64
	v_sub_f32_e32 v51, v55, v64
	v_sub_f32_e32 v36, v36, v64
	v_sub_f32_e32 v37, v37, v65
	v_exp_f32_e32 v68, v50
	v_exp_f32_e32 v69, v51
	v_sub_f32_e32 v50, v56, v64
	v_sub_f32_e32 v51, v57, v64
	v_sub_f32_e32 v38, v38, v64
	v_sub_f32_e32 v39, v39, v65
	v_exp_f32_e32 v56, v50
	v_exp_f32_e32 v57, v51
	v_sub_f32_e32 v50, v58, v64
	v_sub_f32_e32 v51, v59, v64
	v_exp_f32_e32 v58, v34
	v_exp_f32_e32 v59, v35
	v_add_f32_e32 v34, 0, v74
	v_add_f32_e32 v35, 0, v75
	v_exp_f32_e32 v54, v50
	v_exp_f32_e32 v55, v51
	v_sub_f32_e32 v50, v60, v64
	v_sub_f32_e32 v51, v61, v64
	v_add_f32_e32 v34, v72, v34
	v_add_f32_e32 v35, v73, v35
	v_exp_f32_e32 v52, v50
	v_exp_f32_e32 v53, v51
	v_sub_f32_e32 v50, v62, v64
	v_sub_f32_e32 v51, v63, v64
	v_add_f32_e32 v34, v70, v34
	v_add_f32_e32 v35, v71, v35
	v_exp_f32_e32 v50, v50
	v_exp_f32_e32 v51, v51
	v_add_f32_e32 v34, v68, v34
	v_add_f32_e32 v35, v69, v35
	v_exp_f32_e32 v60, v36
	v_add_f32_e32 v34, v56, v34
	v_add_f32_e32 v35, v57, v35
	v_exp_f32_e32 v61, v37
	v_add_f32_e32 v34, v54, v34
	v_add_f32_e32 v35, v55, v35
	v_sub_f32_e32 v40, v40, v64
	v_sub_f32_e32 v41, v41, v65
	v_exp_f32_e32 v62, v38
	v_exp_f32_e32 v63, v39
	v_add_f32_e32 v34, v52, v34
	v_add_f32_e32 v35, v53, v35
	v_sub_f32_e32 v42, v42, v64
	v_sub_f32_e32 v43, v43, v65
	v_sub_f32_e32 v44, v44, v64
	v_sub_f32_e32 v45, v45, v65
	v_sub_f32_e32 v46, v46, v64
	v_sub_f32_e32 v47, v47, v65
	v_sub_f32_e32 v48, v48, v64
	v_sub_f32_e32 v49, v49, v65
	v_exp_f32_e32 v64, v40
	v_exp_f32_e32 v65, v41
	v_add_f32_e32 v34, v50, v34
	v_add_f32_e32 v35, v51, v35
	v_exp_f32_e32 v78, v42
	v_exp_f32_e32 v79, v43
	v_add_f32_e32 v34, v58, v34
	v_add_f32_e32 v35, v59, v35
	v_exp_f32_e32 v80, v44
	v_exp_f32_e32 v81, v45
	v_add_f32_e32 v34, v60, v34
	v_add_f32_e32 v35, v61, v35
	v_exp_f32_e32 v84, v46
	v_exp_f32_e32 v85, v47
	v_add_f32_e32 v34, v62, v34
	v_add_f32_e32 v35, v63, v35
	v_exp_f32_e32 v86, v48
	v_exp_f32_e32 v87, v49
	v_add_f32_e32 v34, v64, v34
	v_add_f32_e32 v35, v65, v35
	v_cvt_pk_bf16_f32 v36, v74, v75
	v_cvt_pk_bf16_f32 v37, v72, v73
	v_cvt_pk_bf16_f32 v38, v70, v71
	v_cvt_pk_bf16_f32 v39, v68, v69
	v_cvt_pk_bf16_f32 v40, v56, v57
	s_nop 0
	v_add_f32_e32 v34, v78, v34
	v_add_f32_e32 v35, v79, v35
	v_cvt_pk_bf16_f32 v41, v54, v55
	v_cvt_pk_bf16_f32 v42, v52, v53
	v_cvt_pk_bf16_f32 v43, v50, v51
	v_cvt_pk_bf16_f32 v44, v58, v59
	v_cvt_pk_bf16_f32 v45, v60, v61
	s_nop 0
	v_add_f32_e32 v34, v80, v34
	v_add_f32_e32 v35, v81, v35
	v_cvt_pk_bf16_f32 v46, v62, v63
	v_cvt_pk_bf16_f32 v47, v64, v65
	v_cvt_pk_bf16_f32 v48, v78, v79
	v_cvt_pk_bf16_f32 v49, v80, v81
	v_cvt_pk_bf16_f32 v50, v84, v85
	s_nop 0
	v_add_f32_e32 v34, v84, v34
	v_add_f32_e32 v35, v85, v35
	v_cvt_pk_bf16_f32 v51, v86, v87
	v_permlane32_swap_b32_e32 v36, v38
	v_add_f32_e32 v34, v86, v34
	v_add_f32_e32 v35, v87, v35
	v_permlane32_swap_b32_e32 v37, v39
	v_pk_add_f32 v[34:35], v[34:35], v[34:35] op_sel:[0,1] op_sel_hi:[1,0]
	v_permlane32_swap_b32_e32 v40, v42
	v_mov_b32_e32 v35, v34
	s_nop 1
	v_permlane32_swap_b32_e32 v34, v35
	v_permlane32_swap_b32_e32 v41, v43
	v_permlane32_swap_b32_e32 v44, v46
	v_permlane32_swap_b32_e32 v45, v47
	v_permlane32_swap_b32_e32 v48, v50
	v_permlane32_swap_b32_e32 v49, v51
	ds_read_b64_tr_b16 v[52:53], v162 offset:0
	ds_read_b64_tr_b16 v[54:55], v162 offset:0x400
	ds_read_b64_tr_b16 v[56:57], v162 offset:0x800
	ds_read_b64_tr_b16 v[58:59], v162 offset:0xc00
	ds_read_b64_tr_b16 v[60:61], v162 offset:0x1000
	ds_read_b64_tr_b16 v[62:63], v162 offset:0x1400
	ds_read_b64_tr_b16 v[68:69], v162 offset:0x1800
	ds_read_b64_tr_b16 v[70:71], v162 offset:0x1c00
	s_waitcnt lgkmcnt(0)
	s_nop 0
	v_mfma_f32_32x32x16_bf16 v[18:33], v[36:39], v[52:55], v[18:33]
	ds_read_b64_tr_b16 v[52:53], v162 offset:0x200
	ds_read_b64_tr_b16 v[54:55], v162 offset:0x600
	v_mfma_f32_32x32x16_bf16 v[18:33], v[40:43], v[56:59], v[18:33]
	ds_read_b64_tr_b16 v[56:57], v162 offset:0xa00
	ds_read_b64_tr_b16 v[58:59], v162 offset:0xe00
	v_mfma_f32_32x32x16_bf16 v[18:33], v[44:47], v[60:63], v[18:33]
	ds_read_b64_tr_b16 v[60:61], v162 offset:0x1200
	ds_read_b64_tr_b16 v[62:63], v162 offset:0x1600
	v_mfma_f32_32x32x16_bf16 v[18:33], v[48:51], v[68:71], v[18:33]
	ds_read_b64_tr_b16 v[68:69], v162 offset:0x1a00
	ds_read_b64_tr_b16 v[70:71], v162 offset:0x1e00
	s_waitcnt lgkmcnt(0)
	v_mfma_f32_32x32x16_bf16 v[2:17], v[36:39], v[52:55], v[2:17]
	v_cmp_gt_u32_e32 vcc, 32, v151
	v_mfma_f32_32x32x16_bf16 v[2:17], v[40:43], v[56:59], v[2:17]
	v_mfma_f32_32x32x16_bf16 v[2:17], v[44:47], v[60:63], v[2:17]
	v_mfma_f32_32x32x16_bf16 v[2:17], v[48:51], v[68:71], v[2:17]
	s_and_saveexec_b64 s[12:13], vcc
	s_cbranch_execz .LBB0_659
	v_lshlrev_b64 v[36:37], 11, v[134:135]
	v_lshl_add_u64 v[36:37], s[78:79], 0, v[36:37]
	v_lshl_add_u64 v[36:37], v[136:137], 2, v[36:37]
	v_lshl_add_u64 v[36:37], v[140:141], 4, v[36:37]
	flat_load_dword v36, v[36:37]
	v_max_f32_e32 v39, v76, v76
	v_add_f32_e32 v34, v34, v35
	v_add_f32_e32 v38, v66, v67
	v_fmac_f32_e32 v38, v165, v163
	v_fmac_f32_e32 v34, v38, v77
	s_waitcnt vmcnt(0) lgkmcnt(0)
	v_max_f32_e32 v37, v36, v36
	v_max_f32_e32 v37, v39, v37
	v_sub_f32_e32 v35, v76, v37
	v_sub_f32_e32 v36, v36, v37
	v_exp_f32_e32 v35, v35
	v_exp_f32_e32 v36, v36
	s_nop 0
	v_fma_f32 v34, v34, v35, v36
	v_rcp_f32_e32 v34, v34
	s_nop 0
	v_mul_f32_e32 v35, v35, v34
	v_mul_f32_e32 v34, v36, v34
	v_add_u32_e32 v36, 0x8000, v155
	ds_write2_b32 v36, v35, v34 offset1:32

.LBB0_660:
	s_or_saveexec_b64 s[14:15], s[20:21]
	v_mov_b32_e32 v2, 2
	s_xor_b64 exec, exec, s[14:15]
	s_cbranch_execz .LBB0_699
	s_movk_i32 s4, 0x9bf
	v_cmp_lt_u32_e32 vcc, s4, v127
	s_and_saveexec_b64 s[4:5], vcc
	s_xor_b64 s[4:5], exec, s[4:5]
	v_add_u32_e32 v2, 0xfffff640, v127
	v_lshrrev_b32_e32 v3, 7, v2
	v_lshrrev_b32_e32 v2, 6, v2
	s_or_saveexec_b64 s[8:9], s[4:5]
	v_mov_b32_e32 v157, 32
	v_mov_b32_e32 v4, 15
	v_mov_b32_e32 v5, v127
	s_xor_b64 exec, exec, s[8:9]
	v_add_u32_e32 v5, 0xfffffe40, v127
	v_lshrrev_b32_e32 v2, 8, v5
	v_add_u32_e32 v3, 16, v2
	v_lshrrev_b32_e32 v2, 7, v5
	v_mov_b32_e32 v157, 64
	v_mov_b32_e32 v4, 31
	s_or_b64 exec, exec, s[8:9]
	v_cmp_lt_u32_e32 vcc, 15, v3
	s_and_saveexec_b64 s[4:5], vcc
	s_xor_b64 s[4:5], exec, s[4:5]
	v_add_u32_e32 v6, -16, v3
	v_mov_b32_e32 v7, v0
	v_lshlrev_b64 v[6:7], 12, v[6:7]
	v_lshl_add_u64 v[34:35], v[6:7], 0, s[42:43]
	s_andn2_saveexec_b64 s[8:9], s[4:5]
	v_lshlrev_b32_e32 v34, 11, v3
	v_mov_b32_e32 v35, v0
	s_or_b64 exec, exec, s[8:9]
	v_lshrrev_b32_e32 v3, 2, v5
	v_and_b32_e32 v3, v3, v4
	v_and_b32_e32 v22, 1, v2
	v_lshlrev_b32_e32 v2, 7, v3
	v_mov_b32_e32 v3, v0
	v_lshl_add_u64 v[134:135], v[34:35], 0, v[2:3]
	v_mov_b64_e32 v[2:3], s[38:39]
	v_mad_u64_u32 v[18:19], s[4:5], v134, s59, v[2:3]
	v_mad_u64_u32 v[2:3], s[4:5], v34, s59, v[2:3]
	v_mov_b32_e32 v4, v3
	v_mad_u64_u32 v[4:5], s[4:5], v35, s59, v[4:5]
	v_mov_b32_e32 v3, v4
	v_lshlrev_b32_e32 v36, 7, v22
	v_mov_b32_e32 v37, v0
	v_lshl_add_u64 v[10:11], v[2:3], 0, v[36:37]
	v_mov_b32_e32 v37, v170
	s_mov_b64 s[4:5], 0x1300
	v_ashrrev_i32_e32 v38, 3, v37
	v_lshlrev_b32_e32 v23, 3, v37
	v_add_u32_e32 v24, 32, v38
	v_lshl_add_u64 v[40:41], v[10:11], 0, s[4:5]
	v_and_b32_e32 v84, 56, v23
	v_mad_i64_i32 v[2:3], s[4:5], v38, s86, 0
	v_mad_i64_i32 v[4:5], s[4:5], v24, s86, 0
	v_or_b32_e32 v2, v2, v84
	v_or_b32_e32 v4, v4, v84
	v_lshlrev_b64 v[12:13], 1, v[2:3]
	v_lshlrev_b64 v[14:15], 1, v[4:5]
	v_lshl_add_u64 v[2:3], v[40:41], 0, v[12:13]
	v_lshl_add_u64 v[6:7], v[40:41], 0, v[14:15]
	flat_load_dwordx4 v[2:5], v[2:3]
	s_nop 0
	flat_load_dwordx4 v[6:9], v[6:7]
	v_mov_b32_e32 v16, v19
	s_mov_b64 s[4:5], 0x1200
	v_lshl_add_u64 v[82:83], v[10:11], 0, s[4:5]
	v_mad_u64_u32 v[20:21], s[4:5], v135, s59, v[16:17]
	v_mov_b32_e32 v19, v20
	v_lshlrev_b32_e32 v20, 6, v127
	v_lshl_add_u64 v[10:11], v[82:83], 0, v[12:13]
	v_lshl_add_u64 v[14:15], v[82:83], 0, v[14:15]
	v_and_b32_e32 v20, 0xc0, v20
	flat_load_dwordx4 v[10:13], v[10:11]
	v_lshl_or_b32 v138, v22, 8, v20
	flat_load_dwordx4 v[14:17], v[14:15]
	v_lshlrev_b32_e32 v20, 1, v138
	v_mov_b32_e32 v21, v0
	v_ashrrev_i32_e32 v39, 1, v37
	v_lshl_add_u64 v[18:19], v[18:19], 0, v[20:21]
	v_bfe_u32 v139, v37, 5, 1
	v_bfi_b32 v20, s1, v39, v37
	v_mad_i64_i32 v[18:19], s[4:5], v20, s59, v[18:19]
	v_lshlrev_b32_e32 v136, 4, v139
	v_mov_b32_e32 v137, v0
	v_lshl_add_u64 v[18:19], v[18:19], 0, v[136:137]
	flat_load_dwordx4 v[78:81], v[18:19] offset:3584
	flat_load_dwordx4 v[66:69], v[18:19] offset:3616
	flat_load_dwordx4 v[70:73], v[18:19] offset:3648
	flat_load_dwordx4 v[74:77], v[18:19] offset:3680
	v_and_b32_e32 v20, 0x1fffff0, v38
	v_lshlrev_b32_e32 v21, 1, v38
	v_lshrrev_b32_e32 v22, 1, v38
	v_and_b32_e32 v25, 3, v38
	v_and_or_b32 v20, v21, 8, v20
	v_and_or_b32 v21, v22, 4, v25
	v_and_b32_e32 v25, 0x1fffff0, v24
	v_lshlrev_b32_e32 v26, 1, v24
	v_bfe_u32 v23, v23, 5, 1
	v_lshrrev_b32_e32 v20, 2, v20
	v_and_or_b32 v25, v26, 8, v25
	v_lshlrev_b32_e32 v22, 1, v84
	v_or_b32_e32 v20, v20, v23
	v_lshrrev_b32_e32 v25, 2, v25
	v_lshlrev_b32_e32 v21, 6, v21
	v_and_b32_e32 v27, 48, v22
	v_lshlrev_b32_e32 v20, 9, v20
	v_or_b32_e32 v23, v25, v23
	v_or3_b32 v163, v20, v21, v27
	v_lshlrev_b32_e32 v20, 9, v23
	v_or3_b32 v164, v20, v21, v27
	s_waitcnt vmcnt(0)
	v_and_b32_e32 v137, 31, v37
	v_lshlrev_b32_e32 v85, 4, v37
	v_lshlrev_b32_e32 v62, 7, v137
	v_and_b32_e32 v63, 0x70, v85
	v_bitop3_b32 v169, v136, v62, v63 bitop3:0xde
	v_or_b32_e32 v42, 32, v136
	v_bitop3_b32 v168, v42, v62, v63 bitop3:0xde
	v_or_b32_e32 v64, 0x60, v136
	v_bitop3_b32 v191, v64, v62, v63 bitop3:0xde
	s_waitcnt vmcnt(0) lgkmcnt(0)
	ds_write_b128 v163, v[2:5]
	ds_write_b128 v164, v[6:9]
	v_lshlrev_b32_e32 v3, 4, v38
	v_lshlrev_b32_e32 v2, 7, v38
	v_and_b32_e32 v3, 0x70, v3
	v_bitop3_b32 v165, v22, v2, v3 bitop3:0xde
	v_lshlrev_b32_e32 v2, 7, v24
	v_bitop3_b32 v167, v22, v2, v3 bitop3:0xde
	v_and_b32_e32 v115, 63, v37
	v_and_b32_e32 v140, 0xffffffe0, v39
	v_lshlrev_b32_e32 v39, 3, v115
	v_mov_b32_e32 v151, 0
	ds_write_b128 v165, v[10:13] offset:16384
	s_mov_b32 s30, 4
	ds_write_b128 v167, v[14:17] offset:16384
	s_waitcnt lgkmcnt(0)
	s_barrier
	ds_read_b128 v[2:5], v169 offset:16384
	ds_read_b128 v[18:21], v169 offset:20480
	s_waitcnt lgkmcnt(1)
	v_mfma_f32_32x32x16_bf16 v[2:17], v[2:5], v[78:81], 0
	ds_read_b128 v[42:45], v168 offset:16384
	ds_read_b128 v[46:49], v168 offset:20480
	v_add_u32_e32 v192, -1, v157
	v_cmp_gt_u32_e64 s[12:13], 32, v115
	s_mov_b64 s[20:21], 0
	s_waitcnt lgkmcnt(2)
	v_mfma_f32_32x32x16_bf16 v[18:33], v[18:21], v[78:81], 0
	s_waitcnt lgkmcnt(1)
	v_mfma_f32_32x32x16_bf16 v[2:17], v[42:45], v[66:69], v[2:17]
	v_or_b32_e32 v42, 64, v136
	v_bitop3_b32 v166, v42, v62, v63 bitop3:0xde
	s_waitcnt lgkmcnt(0)
	v_mfma_f32_32x32x16_bf16 v[18:33], v[46:49], v[66:69], v[18:33]
	ds_read_b128 v[42:45], v166 offset:16384
	ds_read_b128 v[46:49], v166 offset:20480
	s_waitcnt lgkmcnt(1)
	v_mfma_f32_32x32x16_bf16 v[2:17], v[42:45], v[70:73], v[2:17]
	v_add_u32_e32 v42, 64, v38
	v_add_u32_e32 v44, 0x60, v38
	v_mad_i64_i32 v[42:43], s[4:5], v42, s86, 0
	v_mad_i64_i32 v[44:45], s[4:5], v44, s86, 0
	v_or_b32_e32 v42, v42, v84
	v_or_b32_e32 v44, v44, v84
	v_lshlrev_b64 v[54:55], 1, v[42:43]
	v_lshlrev_b64 v[56:57], 1, v[44:45]
	v_lshl_add_u64 v[42:43], v[40:41], 0, v[54:55]
	v_lshl_add_u64 v[50:51], v[40:41], 0, v[56:57]
	v_lshl_add_u64 v[54:55], v[82:83], 0, v[54:55]
	v_lshl_add_u64 v[58:59], v[82:83], 0, v[56:57]
	flat_load_dwordx4 v[42:45], v[42:43]
	s_nop 0
	flat_load_dwordx4 v[50:53], v[50:51]
	s_nop 0
	flat_load_dwordx4 v[54:57], v[54:55]
	s_nop 0
	flat_load_dwordx4 v[58:61], v[58:59]
	ds_read_b128 v[62:65], v191 offset:16384
	s_waitcnt lgkmcnt(0)
	v_mfma_f32_32x32x16_bf16 v[18:33], v[46:49], v[70:73], v[18:33]
	v_lshlrev_b32_e32 v46, 2, v37
	v_and_b32_e32 v149, 0xffffff00, v46
	ds_read_b128 v[46:49], v191 offset:20480
	v_lshl_or_b32 v141, v137, 2, v149
	v_mfma_f32_32x32x16_bf16 v[2:17], v[62:65], v[74:77], v[2:17]
	v_and_b32_e32 v62, 0xc0, v85
	v_lshlrev_b32_e32 v63, 1, v37
	v_and_or_b32 v62, v39, 24, v62
	v_and_b32_e32 v63, 32, v63
	v_and_b32_e32 v39, 0x100, v39
	v_or3_b32 v162, v62, v63, v39
	v_add_u32_e32 v62, 0x80, v38
	s_waitcnt lgkmcnt(0)
	v_mfma_f32_32x32x16_bf16 v[18:33], v[46:49], v[74:77], v[18:33]
	s_nop 2
	v_max_f32_e32 v46, v3, v3
	v_max_f32_e32 v47, v2, v2
	v_max_f32_e32 v46, v47, v46
	v_max3_f32 v46, v46, v4, v5
	v_max3_f32 v46, v46, v6, v7
	v_max3_f32 v46, v46, v8, v9
	v_max3_f32 v46, v46, v10, v11
	v_max3_f32 v46, v46, v12, v13
	v_max3_f32 v46, v46, v14, v15
	v_max3_f32 v46, v46, v16, v17
	v_max3_f32 v46, v46, v18, v19
	v_max3_f32 v46, v46, v20, v21
	v_max3_f32 v46, v46, v22, v23
	v_max3_f32 v46, v46, v24, v25
	v_max3_f32 v46, v46, v26, v27
	v_max3_f32 v46, v46, v28, v29
	v_max3_f32 v46, v46, v30, v31
	v_max3_f32 v46, v46, v32, v33
	v_mov_b32_e32 v47, v46
	s_nop 1
	v_permlane32_swap_b32_e32 v46, v47
	v_max_f32_e32 v47, v47, v47
	v_max_f32_e32 v46, v46, v46
	v_max_f32_e32 v98, v46, v47
	v_add_f32_e32 v46, 0x7149f2ca, v98
	v_cmp_ge_f32_e32 vcc, s0, v46
	v_add_u32_e32 v46, 0xa0, v38
	v_mad_i64_i32 v[46:47], s[4:5], v46, s86, 0
	v_or_b32_e32 v46, v46, v84
	v_mad_i64_i32 v[62:63], s[4:5], v62, s86, 0
	v_lshlrev_b64 v[46:47], 1, v[46:47]
	v_or_b32_e32 v62, v62, v84
	v_lshl_add_u64 v[48:49], v[82:83], 0, v[46:47]
	v_lshlrev_b64 v[62:63], 1, v[62:63]
	v_lshl_add_u64 v[46:47], v[40:41], 0, v[46:47]
	v_lshl_add_u64 v[64:65], v[82:83], 0, v[62:63]
	flat_load_dwordx4 v[90:93], v[48:49]
	flat_load_dwordx4 v[82:85], v[64:65]
	v_lshl_add_u64 v[40:41], v[40:41], 0, v[62:63]
	flat_load_dwordx4 v[94:97], v[46:47]
	flat_load_dwordx4 v[86:89], v[40:41]
	s_cmp_eq_u64 vcc, exec
	v_max_f32_e32 v40, 0xf149f2ca, v98
	s_cselect_b64 vcc, -1, 0
	v_cndmask_b32_e32 v114, v40, v178, vcc
	v_sub_f32_e32 v2, v2, v114
	v_sub_f32_e32 v3, v3, v114
	v_ashrrev_i32_e32 v39, 31, v38
	v_exp_f32_e32 v106, v2
	v_exp_f32_e32 v107, v3
	v_sub_f32_e32 v2, v4, v114
	v_sub_f32_e32 v3, v5, v114
	v_sub_f32_e32 v41, 0xf149f2ca, v40
	v_exp_f32_e32 v108, v2
	v_exp_f32_e32 v109, v3
	v_sub_f32_e32 v2, v6, v114
	v_sub_f32_e32 v3, v7, v114
	v_exp_f32_e32 v41, v41
	v_exp_f32_e32 v110, v2
	v_exp_f32_e32 v111, v3
	v_sub_f32_e32 v2, v8, v114
	v_sub_f32_e32 v3, v9, v114
	s_waitcnt vmcnt(4)
	v_cndmask_b32_e64 v193, v41, 1.0, vcc
	v_exp_f32_e32 v112, v2
	v_exp_f32_e32 v113, v3
	v_sub_f32_e32 v2, v10, v114
	v_sub_f32_e32 v3, v11, v114
	v_sub_f32_e32 v128, v18, v114
	v_exp_f32_e32 v98, v2
	v_exp_f32_e32 v99, v3
	v_sub_f32_e32 v2, v12, v114
	v_sub_f32_e32 v3, v13, v114
	v_sub_f32_e32 v129, v19, v114
	v_exp_f32_e32 v100, v2
	v_exp_f32_e32 v101, v3
	v_sub_f32_e32 v2, v14, v114
	v_sub_f32_e32 v3, v15, v114
	v_sub_f32_e32 v160, v20, v114
	v_exp_f32_e32 v104, v2
	v_exp_f32_e32 v105, v3
	v_sub_f32_e32 v2, v16, v114
	v_sub_f32_e32 v3, v17, v114
	v_sub_f32_e32 v161, v21, v114
	v_exp_f32_e32 v102, v2
	v_exp_f32_e32 v103, v3
	v_lshl_add_u64 v[2:3], v[34:35], 0, v[38:39]
	v_mad_u64_u32 v[4:5], s[4:5], v2, s59, 0
	v_mov_b32_e32 v2, v5
	v_mad_u64_u32 v[2:3], s[4:5], v3, s59, v[2:3]
	v_and_b32_e32 v3, 7, v37
	v_lshlrev_b32_e32 v3, 4, v3
	v_readlane_b32 s4, v255, 51
	v_or3_b32 v4, v4, v36, v3
	v_mov_b32_e32 v5, v2
	v_readlane_b32 s5, v255, 52
	v_sub_f32_e32 v120, v22, v114
	v_sub_f32_e32 v121, v23, v114
	v_sub_f32_e32 v122, v24, v114
	v_sub_f32_e32 v123, v25, v114
	v_sub_f32_e32 v124, v26, v114
	v_sub_f32_e32 v125, v27, v114
	v_sub_f32_e32 v126, v28, v114
	v_sub_f32_e32 v127, v29, v114
	v_sub_f32_e32 v116, v30, v114
	v_sub_f32_e32 v117, v31, v114
	v_sub_f32_e32 v118, v32, v114
	v_sub_f32_e32 v119, v33, v114
	v_or_b32_e32 v155, 0x2000, v162
	v_lshl_add_u64 v[142:143], s[4:5], 0, v[4:5]
	v_mov_b32_e32 v2, 0
	v_mov_b32_e32 v3, v151
	v_mov_b32_e32 v4, v151
	v_mov_b32_e32 v5, v151
	v_mov_b32_e32 v6, v151
	v_mov_b32_e32 v7, v151
	v_mov_b32_e32 v8, v151
	v_mov_b32_e32 v9, v151
	v_mov_b32_e32 v10, v151
	v_mov_b32_e32 v11, v151
	v_mov_b32_e32 v12, v151
	v_mov_b32_e32 v13, v151
	v_mov_b32_e32 v14, v151
	v_mov_b32_e32 v15, v151
	v_mov_b32_e32 v16, v151
	v_mov_b32_e32 v17, v151
	v_mov_b32_e32 v18, 0
	v_mov_b32_e32 v19, v151
	v_mov_b32_e32 v20, v151
	v_mov_b32_e32 v21, v151
	v_mov_b32_e32 v22, v151
	v_mov_b32_e32 v23, v151
	v_mov_b32_e32 v24, v151
	v_mov_b32_e32 v25, v151
	v_mov_b32_e32 v26, v151
	v_mov_b32_e32 v27, v151
	v_mov_b32_e32 v28, v151
	v_mov_b32_e32 v29, v151
	v_mov_b32_e32 v30, v151
	v_mov_b32_e32 v31, v151
	v_mov_b32_e32 v32, v151
	v_mov_b32_e32 v33, v151
	s_waitcnt vmcnt(0)
	ds_write_b128 v163, v[42:45] offset:8192
	ds_write_b128 v164, v[50:53] offset:8192
	ds_write_b128 v165, v[54:57] offset:24576
	ds_write_b128 v167, v[58:61] offset:24576
	s_waitcnt lgkmcnt(0)
	s_barrier
	s_branch .LBB0_672

.LBB0_671:
	v_mov_b32_e32 v119, v118
	v_sub_f32_e32 v50, v50, v118
	v_sub_f32_e32 v51, v51, v118
	s_mov_b64 s[4:5], 0xa0000
	v_exp_f32_e32 v106, v50
	v_exp_f32_e32 v107, v51
	v_sub_f32_e32 v50, v52, v118
	v_sub_f32_e32 v51, v53, v118
	v_sub_f32_e32 v128, v34, v118
	v_sub_f32_e32 v129, v35, v119
	v_exp_f32_e32 v108, v50
	v_exp_f32_e32 v109, v51
	v_sub_f32_e32 v50, v54, v118
	v_sub_f32_e32 v51, v55, v118
	v_add_f32_e32 v34, v144, v194
	v_exp_f32_e32 v110, v50
	v_exp_f32_e32 v111, v51
	v_sub_f32_e32 v50, v56, v118
	v_sub_f32_e32 v51, v57, v118
	v_lshl_add_u64 v[142:143], v[142:143], 0, s[4:5]
	v_exp_f32_e32 v112, v50
	v_exp_f32_e32 v113, v51
	v_sub_f32_e32 v50, v58, v118
	v_sub_f32_e32 v51, v59, v118
	s_add_i32 s5, s30, -1
	v_exp_f32_e32 v98, v50
	v_exp_f32_e32 v99, v51
	v_sub_f32_e32 v50, v60, v118
	v_sub_f32_e32 v51, v61, v118
	v_fmac_f32_e32 v34, v193, v151
	v_exp_f32_e32 v100, v50
	v_exp_f32_e32 v101, v51
	v_sub_f32_e32 v50, v62, v118
	v_sub_f32_e32 v51, v63, v118
	v_add_f32_e32 v151, v158, v159
	v_exp_f32_e32 v104, v50
	v_exp_f32_e32 v105, v51
	v_sub_f32_e32 v50, v64, v118
	v_sub_f32_e32 v51, v65, v118
	s_add_i32 s4, s30, 2
	v_exp_f32_e32 v102, v50
	v_exp_f32_e32 v103, v51
	v_cmp_ge_u32_e32 vcc, s5, v192
	v_sub_f32_e32 v160, v36, v118
	v_sub_f32_e32 v161, v37, v119
	v_sub_f32_e32 v120, v38, v118
	v_sub_f32_e32 v121, v39, v119
	v_sub_f32_e32 v122, v40, v118
	v_sub_f32_e32 v123, v41, v119
	v_sub_f32_e32 v124, v42, v118
	v_sub_f32_e32 v125, v43, v119
	v_sub_f32_e32 v126, v44, v118
	v_sub_f32_e32 v127, v45, v119
	v_sub_f32_e32 v116, v46, v118
	v_sub_f32_e32 v117, v47, v119
	v_sub_f32_e32 v118, v48, v118
	v_sub_f32_e32 v119, v49, v119
	v_fmac_f32_e32 v151, v34, v195
	s_or_b64 s[20:21], vcc, s[20:21]
	s_mov_b32 s30, s4
	v_mov_b32_e32 v193, v145
	s_waitcnt lgkmcnt(0)
	s_barrier
	s_andn2_b64 exec, exec, s[20:21]
	s_cbranch_execz .LBB0_689
.LBB0_672:
	ds_read_b128 v[34:37], v169 offset:24576
	ds_read_b128 v[38:41], v169 offset:28672
	ds_read_b128 v[194:197], v168 offset:24576
	ds_read_b128 v[198:201], v168 offset:28672
	v_exp_f32_e32 v128, v128
	v_exp_f32_e32 v129, v129
	s_waitcnt lgkmcnt(3)
	v_mfma_f32_32x32x16_bf16 v[50:65], v[34:37], v[78:81], 0
	v_exp_f32_e32 v158, v160
	v_exp_f32_e32 v159, v161
	v_exp_f32_e32 v160, v120
	v_exp_f32_e32 v161, v121
	v_exp_f32_e32 v180, v122
	v_exp_f32_e32 v181, v123
	v_exp_f32_e32 v182, v124
	s_waitcnt lgkmcnt(2)
	v_mfma_f32_32x32x16_bf16 v[34:49], v[38:41], v[78:81], 0
	v_exp_f32_e32 v183, v125
	v_cvt_pk_bf16_f32 v120, v98, v99
	v_cvt_pk_bf16_f32 v121, v100, v101
	v_cvt_pk_bf16_f32 v122, v104, v105
	v_cvt_pk_bf16_f32 v123, v102, v103
	v_cvt_pk_bf16_f32 v124, v128, v129
	v_cvt_pk_bf16_f32 v125, v158, v159
	s_waitcnt lgkmcnt(0)
	v_mfma_f32_32x32x16_bf16 v[34:49], v[198:201], v[66:69], v[34:49]
	v_permlane32_swap_b32_e32 v120, v122
	v_permlane32_swap_b32_e32 v121, v123
	v_mfma_f32_32x32x16_bf16 v[50:65], v[194:197], v[66:69], v[50:65]
	ds_read_b128 v[194:197], v166 offset:24576
	ds_read_b128 v[198:201], v166 offset:28672
	s_waitcnt lgkmcnt(0)
	v_mfma_f32_32x32x16_bf16 v[34:49], v[198:201], v[70:73], v[34:49]
	v_mfma_f32_32x32x16_bf16 v[50:65], v[194:197], v[70:73], v[50:65]
	ds_read_b128 v[194:197], v191 offset:24576
	ds_read_b128 v[198:201], v191 offset:28672
	s_waitcnt lgkmcnt(0)
	v_mfma_f32_32x32x16_bf16 v[34:49], v[198:201], v[74:77], v[34:49]
	v_exp_f32_e32 v198, v116
	v_exp_f32_e32 v199, v117
	v_add_f32_e32 v116, 0, v106
	v_add_f32_e32 v117, 0, v107
	v_exp_f32_e32 v200, v118
	v_add_f32_e32 v116, v108, v116
	v_add_f32_e32 v117, v109, v117
	v_exp_f32_e32 v201, v119
	v_add_f32_e32 v116, v110, v116
	v_add_f32_e32 v117, v111, v117
	v_mfma_f32_32x32x16_bf16 v[50:65], v[194:197], v[74:77], v[50:65]
	v_add_f32_e64 v116, v112, v116
	v_add_f32_e64 v117, v113, v117
	v_exp_f32_e32 v196, v126
	v_add_f32_e32 v116, v98, v116
	v_add_f32_e32 v117, v99, v117
	v_exp_f32_e32 v197, v127
	v_add_f32_e32 v116, v100, v116
	v_add_f32_e32 v117, v101, v117
	v_cvt_pk_bf16_f32 v118, v110, v111
	v_cvt_pk_bf16_f32 v119, v112, v113
	v_cvt_pk_bf16_f32 v126, v160, v161
	v_cvt_pk_bf16_f32 v127, v180, v181
	s_nop 0
	v_add_f32_e32 v116, v104, v116
	v_add_f32_e32 v117, v105, v117
	v_permlane32_swap_b32_e32 v124, v126
	v_add_f32_e32 v116, v102, v116
	v_add_f32_e32 v117, v103, v117
	v_permlane32_swap_b32_e32 v125, v127
	v_add_f32_e32 v116, v128, v116
	v_add_f32_e32 v117, v129, v117
	s_nop 0
	v_add_f32_e32 v116, v158, v116
	v_add_f32_e32 v117, v159, v117
	v_cvt_pk_bf16_f32 v158, v182, v183
	v_cvt_pk_bf16_f32 v159, v196, v197
	s_nop 0
	v_add_f32_e32 v116, v160, v116
	v_add_f32_e32 v117, v161, v117
	v_cvt_pk_bf16_f32 v160, v198, v199
	v_cvt_pk_bf16_f32 v161, v200, v201
	s_nop 0
	v_add_f32_e32 v116, v180, v116
	v_add_f32_e32 v117, v181, v117
	v_permlane32_swap_b32_e32 v158, v160
	v_add_f32_e32 v116, v182, v116
	v_add_f32_e32 v117, v183, v117
	v_permlane32_swap_b32_e32 v159, v161
	v_add_f32_e32 v116, v196, v116
	v_add_f32_e32 v117, v197, v117
	s_nop 0
	v_add_f32_e32 v116, v198, v116
	v_add_f32_e32 v117, v199, v117
	s_nop 0
	v_add_f32_e32 v116, v200, v116
	v_add_f32_e32 v117, v201, v117
	s_nop 0
	v_add_f32_e32 v144, v116, v117
	v_add_f32_e32 v145, v117, v116
	v_cvt_pk_bf16_f32 v116, v106, v107
	v_cvt_pk_bf16_f32 v117, v108, v109
	s_nop 0
	v_mov_b32_e32 v194, v144
	s_nop 1
	v_permlane32_swap_b32_e32 v144, v194
	v_permlane32_swap_b32_e32 v116, v118
	v_permlane32_swap_b32_e32 v117, v119
	s_mov_b32 s4, 0xfff87f00
	v_add_co_u32_e32 v102, vcc, s4, v142
	s_mov_b32 s4, 0xfffaff00
	s_nop 0
	v_addc_co_u32_e32 v103, vcc, -1, v143, vcc
	v_add_co_u32_e32 v106, vcc, s4, v142
	s_nop 1
	v_addc_co_u32_e32 v107, vcc, -1, v143, vcc
	flat_load_dwordx4 v[98:101], v[102:103] offset:256
	s_nop 0
	flat_load_dwordx4 v[102:105], v[102:103]
	s_nop 0
	flat_load_dwordx4 v[110:113], v[106:107] offset:256
	s_nop 0
	flat_load_dwordx4 v[106:109], v[106:107]
	ds_read_b64_tr_b16 v[196:197], v162 offset:0
	ds_read_b64_tr_b16 v[198:199], v162 offset:0x400
	ds_read_b64_tr_b16 v[200:201], v162 offset:0x800
	ds_read_b64_tr_b16 v[202:203], v162 offset:0xc00
	ds_read_b64_tr_b16 v[204:205], v162 offset:0x1000
	ds_read_b64_tr_b16 v[206:207], v162 offset:0x1400
	ds_read_b64_tr_b16 v[208:209], v162 offset:0x1800
	ds_read_b64_tr_b16 v[210:211], v162 offset:0x1c00
	s_waitcnt lgkmcnt(0)
	s_nop 0
	v_mfma_f32_32x32x16_bf16 v[2:17], v[116:119], v[196:199], v[2:17]
	ds_read_b64_tr_b16 v[196:197], v162 offset:0x200
	ds_read_b64_tr_b16 v[198:199], v162 offset:0x600
	v_mfma_f32_32x32x16_bf16 v[2:17], v[120:123], v[200:203], v[2:17]
	ds_read_b64_tr_b16 v[200:201], v162 offset:0xa00
	ds_read_b64_tr_b16 v[202:203], v162 offset:0xe00
	v_mfma_f32_32x32x16_bf16 v[2:17], v[124:127], v[204:207], v[2:17]
	ds_read_b64_tr_b16 v[204:205], v162 offset:0x1200
	ds_read_b64_tr_b16 v[206:207], v162 offset:0x1600
	v_mfma_f32_32x32x16_bf16 v[2:17], v[158:161], v[208:211], v[2:17]
	ds_read_b64_tr_b16 v[208:209], v162 offset:0x1a00
	ds_read_b64_tr_b16 v[210:211], v162 offset:0x1e00
	s_waitcnt lgkmcnt(0)
	v_mfma_f32_32x32x16_bf16 v[18:33], v[116:119], v[196:199], v[18:33]
	v_max_f32_e32 v115, v51, v51
	v_max_f32_e32 v116, v50, v50
	v_max_f32_e32 v115, v116, v115
	v_max3_f32 v115, v115, v52, v53
	v_max3_f32 v115, v115, v54, v55
	v_max3_f32 v115, v115, v56, v57
	v_max3_f32 v115, v115, v58, v59
	v_mfma_f32_32x32x16_bf16 v[18:33], v[120:123], v[200:203], v[18:33]
	v_max3_f32 v115, v115, v60, v61
	v_max3_f32 v115, v115, v62, v63
	v_max3_f32 v115, v115, v64, v65
	v_max3_f32 v115, v115, v34, v35
	v_max3_f32 v115, v115, v36, v37
	v_max3_f32 v115, v115, v38, v39
	v_max3_f32 v115, v115, v40, v41
	v_mfma_f32_32x32x16_bf16 v[18:33], v[124:127], v[204:207], v[18:33]
	v_max3_f32 v115, v115, v42, v43
	v_max3_f32 v115, v115, v44, v45
	v_max3_f32 v115, v115, v46, v47
	v_max3_f32 v115, v115, v48, v49
	v_mov_b32_e32 v116, v115
	s_nop 1
	v_permlane32_swap_b32_e32 v115, v116
	v_mfma_f32_32x32x16_bf16 v[18:33], v[158:161], v[208:211], v[18:33]
	v_max_f32_e32 v116, v116, v116
	v_max_f32_e32 v115, v115, v115
	v_max_f32_e32 v115, v115, v116
	v_sub_f32_e32 v116, v115, v114
	v_cmp_ge_f32_e32 vcc, s0, v116
	s_cmp_lg_u64 vcc, exec
	s_cbranch_scc1 .LBB0_687
	v_mov_b32_e32 v116, v114

.LBB0_679:
	v_mov_b32_e32 v117, v116
	v_sub_f32_e32 v50, v50, v116
	v_sub_f32_e32 v51, v51, v116
	v_sub_f32_e32 v158, v34, v116
	v_sub_f32_e32 v159, v35, v117
	v_exp_f32_e32 v114, v50
	v_exp_f32_e32 v115, v51
	v_sub_f32_e32 v50, v52, v116
	v_sub_f32_e32 v51, v53, v116
	v_sub_f32_e32 v180, v36, v116
	v_sub_f32_e32 v181, v37, v117
	v_exp_f32_e32 v124, v50
	v_exp_f32_e32 v125, v51
	v_sub_f32_e32 v50, v54, v116
	v_sub_f32_e32 v51, v55, v116
	v_sub_f32_e32 v182, v38, v116
	v_sub_f32_e32 v183, v39, v117
	v_exp_f32_e32 v128, v50
	v_exp_f32_e32 v129, v51
	v_sub_f32_e32 v50, v56, v116
	v_sub_f32_e32 v51, v57, v116
	v_sub_f32_e32 v206, v40, v116
	v_sub_f32_e32 v207, v41, v117
	v_exp_f32_e32 v160, v50
	v_exp_f32_e32 v161, v51
	v_sub_f32_e32 v50, v58, v116
	v_sub_f32_e32 v51, v59, v116
	v_sub_f32_e32 v208, v42, v116
	v_sub_f32_e32 v209, v43, v117
	v_exp_f32_e32 v118, v50
	v_exp_f32_e32 v119, v51
	v_sub_f32_e32 v50, v60, v116
	v_sub_f32_e32 v51, v61, v116
	v_sub_f32_e32 v210, v44, v116
	v_sub_f32_e32 v211, v45, v117
	v_exp_f32_e32 v120, v50
	v_exp_f32_e32 v121, v51
	v_sub_f32_e32 v50, v62, v116
	v_sub_f32_e32 v51, v63, v116
	v_sub_f32_e32 v212, v46, v116
	v_sub_f32_e32 v213, v47, v117
	v_exp_f32_e32 v126, v50
	v_exp_f32_e32 v127, v51
	v_sub_f32_e32 v50, v64, v116
	v_sub_f32_e32 v51, v65, v116
	v_sub_f32_e32 v116, v48, v116
	v_sub_f32_e32 v117, v49, v117
	v_exp_f32_e32 v122, v50
	v_exp_f32_e32 v123, v51
	s_waitcnt lgkmcnt(0)
	s_barrier
	ds_read_b128 v[34:37], v169 offset:16384
	ds_read_b128 v[38:41], v169 offset:20480
	ds_read_b128 v[198:201], v168 offset:16384
	ds_read_b128 v[202:205], v168 offset:20480
	v_exp_f32_e32 v180, v180
	v_exp_f32_e32 v181, v181
	s_waitcnt lgkmcnt(0)
	v_mfma_f32_32x32x16_bf16 v[50:65], v[34:37], v[78:81], 0
	v_exp_f32_e32 v182, v182
	v_exp_f32_e32 v183, v183
	v_mfma_f32_32x32x16_bf16 v[34:49], v[38:41], v[78:81], 0
	v_mfma_f32_32x32x16_bf16 v[34:49], v[202:205], v[66:69], v[34:49]
	v_mfma_f32_32x32x16_bf16 v[50:65], v[198:201], v[66:69], v[50:65]
	ds_read_b128 v[198:201], v166 offset:16384
	ds_read_b128 v[202:205], v166 offset:20480
	s_waitcnt lgkmcnt(0)
	v_mfma_f32_32x32x16_bf16 v[34:49], v[202:205], v[70:73], v[34:49]
	v_mfma_f32_32x32x16_bf16 v[50:65], v[198:201], v[70:73], v[50:65]
	ds_read_b128 v[198:201], v191 offset:16384
	ds_read_b128 v[202:205], v191 offset:20480
	s_waitcnt lgkmcnt(0)
	v_mfma_f32_32x32x16_bf16 v[34:49], v[202:205], v[74:77], v[34:49]
	v_exp_f32_e32 v202, v208
	v_exp_f32_e32 v203, v209
	v_exp_f32_e32 v208, v116
	v_exp_f32_e32 v209, v117
	v_add_f32_e32 v116, 0, v114
	v_add_f32_e32 v117, 0, v115
	v_exp_f32_e32 v204, v210
	v_add_f32_e32 v116, v124, v116
	v_add_f32_e32 v117, v125, v117
	v_mfma_f32_32x32x16_bf16 v[50:65], v[198:201], v[74:77], v[50:65]
	v_add_f32_e64 v116, v128, v116
	v_add_f32_e64 v117, v129, v117
	v_exp_f32_e32 v198, v158
	v_add_f32_e32 v116, v160, v116
	v_add_f32_e32 v117, v161, v117
	v_exp_f32_e32 v199, v159
	v_add_f32_e32 v116, v118, v116
	v_add_f32_e32 v117, v119, v117
	v_exp_f32_e32 v200, v206
	v_add_f32_e32 v116, v120, v116
	v_add_f32_e32 v117, v121, v117
	v_exp_f32_e32 v201, v207
	v_add_f32_e32 v116, v126, v116
	v_add_f32_e32 v117, v127, v117
	v_exp_f32_e32 v205, v211
	v_add_f32_e32 v116, v122, v116
	v_add_f32_e32 v117, v123, v117
	v_exp_f32_e32 v206, v212
	v_add_f32_e32 v116, v198, v116
	v_add_f32_e32 v117, v199, v117
	v_exp_f32_e32 v207, v213
	v_add_f32_e32 v116, v180, v116
	v_add_f32_e32 v117, v181, v117
	v_cvt_pk_bf16_f32 v114, v114, v115
	v_cvt_pk_bf16_f32 v115, v124, v125
	v_cvt_pk_bf16_f32 v118, v118, v119
	v_cvt_pk_bf16_f32 v119, v120, v121
	v_cvt_pk_bf16_f32 v120, v126, v127
	s_nop 0
	v_add_f32_e32 v116, v182, v116
	v_add_f32_e32 v117, v183, v117
	v_cvt_pk_bf16_f32 v121, v122, v123
	v_cvt_pk_bf16_f32 v122, v198, v199
	v_cvt_pk_bf16_f32 v123, v180, v181
	v_cvt_pk_bf16_f32 v124, v182, v183
	v_cvt_pk_bf16_f32 v125, v200, v201
	s_nop 0
	v_add_f32_e32 v116, v200, v116
	v_add_f32_e32 v117, v201, v117
	v_cvt_pk_bf16_f32 v126, v202, v203
	v_cvt_pk_bf16_f32 v127, v204, v205
	v_permlane32_swap_b32_e32 v118, v120
	v_add_f32_e32 v116, v202, v116
	v_add_f32_e32 v117, v203, v117
	v_permlane32_swap_b32_e32 v119, v121
	v_add_f32_e32 v116, v204, v116
	v_add_f32_e32 v117, v205, v117
	v_permlane32_swap_b32_e32 v122, v124
	v_add_f32_e32 v116, v206, v116
	v_add_f32_e32 v117, v207, v117
	v_permlane32_swap_b32_e32 v123, v125
	v_add_f32_e32 v116, v208, v116
	v_add_f32_e32 v117, v209, v117
	s_nop 0
	v_add_f32_e32 v158, v116, v117
	v_add_f32_e32 v159, v117, v116
	v_cvt_pk_bf16_f32 v116, v128, v129
	v_cvt_pk_bf16_f32 v117, v160, v161
	v_cvt_pk_bf16_f32 v128, v206, v207
	v_cvt_pk_bf16_f32 v129, v208, v209
	s_nop 0
	v_mov_b32_e32 v159, v158
	s_nop 1
	v_permlane32_swap_b32_e32 v158, v159
	v_permlane32_swap_b32_e32 v114, v116
	v_permlane32_swap_b32_e32 v115, v117
	v_permlane32_swap_b32_e32 v126, v128
	v_permlane32_swap_b32_e32 v127, v129
	v_cmp_lt_u32_e32 vcc, s30, v157
	s_and_saveexec_b64 s[22:23], vcc
	s_cbranch_execz .LBB0_681
	v_add_co_u32_e32 v82, vcc, 0xfffd8000, v142
	s_nop 1
	v_addc_co_u32_e32 v83, vcc, -1, v143, vcc
	v_add_co_u32_e32 v84, vcc, 0xfffd7f00, v142
	s_nop 1
	v_addc_co_u32_e32 v85, vcc, -1, v143, vcc
	v_add_co_u32_e32 v90, vcc, 0xffffff00, v142
	flat_load_dwordx4 v[86:89], v[82:83]
	s_nop 0
	flat_load_dwordx4 v[82:85], v[84:85]
	v_addc_co_u32_e32 v91, vcc, -1, v143, vcc
	flat_load_dwordx4 v[94:97], v[142:143]
	s_nop 0
	flat_load_dwordx4 v[90:93], v[90:91]

.LBB0_689:
	s_or_b64 exec, exec, s[20:21]
	ds_read_b128 v[34:37], v169 offset:24576
	ds_read_b128 v[38:41], v169 offset:28672
	v_exp_f32_e32 v86, v126
	v_exp_f32_e32 v87, v127
	v_exp_f32_e32 v88, v116
	s_waitcnt lgkmcnt(1)
	v_mfma_f32_32x32x16_bf16 v[50:65], v[34:37], v[78:81], 0
	v_exp_f32_e32 v89, v117
	v_exp_f32_e32 v90, v118
	v_exp_f32_e32 v91, v119
	s_waitcnt lgkmcnt(0)
	v_mfma_f32_32x32x16_bf16 v[34:49], v[38:41], v[78:81], 0
	ds_read_b128 v[78:81], v168 offset:24576
	ds_read_b128 v[82:85], v168 offset:28672
	s_waitcnt lgkmcnt(1)
	v_mfma_f32_32x32x16_bf16 v[50:65], v[78:81], v[66:69], v[50:65]
	s_waitcnt lgkmcnt(0)
	v_mfma_f32_32x32x16_bf16 v[34:49], v[82:85], v[66:69], v[34:49]
	ds_read_b128 v[66:69], v166 offset:24576
	ds_read_b128 v[78:81], v166 offset:28672
	v_exp_f32_e32 v82, v122
	v_exp_f32_e32 v83, v123
	v_exp_f32_e32 v84, v124
	v_exp_f32_e32 v85, v125
	s_waitcnt lgkmcnt(1)
	v_mfma_f32_32x32x16_bf16 v[50:65], v[66:69], v[70:73], v[50:65]
	s_waitcnt lgkmcnt(0)
	v_mfma_f32_32x32x16_bf16 v[34:49], v[78:81], v[70:73], v[34:49]
	ds_read_b128 v[66:69], v191 offset:24576
	ds_read_b128 v[70:73], v191 offset:28672
	v_exp_f32_e32 v78, v160
	v_exp_f32_e32 v79, v161
	v_exp_f32_e32 v80, v120
	v_exp_f32_e32 v81, v121
	s_waitcnt lgkmcnt(1)
	v_mfma_f32_32x32x16_bf16 v[50:65], v[66:69], v[74:77], v[50:65]
	v_add_f32_e64 v66, v106, 0
	v_add_f32_e64 v67, v107, 0
	v_cvt_pk_bf16_f32 v68, v106, v107
	v_cvt_pk_bf16_f32 v69, v108, v109
	v_add_f32_e64 v66, v66, v108
	v_add_f32_e64 v67, v67, v109
	v_add_f32_e64 v66, v66, v110
	v_add_f32_e64 v67, v67, v111
	s_waitcnt lgkmcnt(0)
	v_mfma_f32_32x32x16_bf16 v[34:49], v[70:73], v[74:77], v[34:49]
	v_add_f32_e64 v66, v66, v112
	v_add_f32_e64 v67, v67, v113
	v_exp_f32_e32 v76, v128
	v_exp_f32_e32 v77, v129
	v_add_f32_e32 v66, v66, v98
	v_add_f32_e32 v67, v67, v99
	v_cvt_pk_bf16_f32 v70, v110, v111
	v_cvt_pk_bf16_f32 v71, v112, v113
	v_cvt_pk_bf16_f32 v72, v98, v99
	v_cvt_pk_bf16_f32 v73, v100, v101
	v_cvt_pk_bf16_f32 v74, v104, v105
	s_nop 0
	v_add_f32_e32 v66, v66, v100
	v_add_f32_e32 v67, v67, v101
	v_permlane32_swap_b32_e32 v68, v70
	v_add_f32_e32 v66, v66, v104
	v_add_f32_e32 v67, v67, v105
	v_cvt_pk_bf16_f32 v75, v102, v103
	v_permlane32_swap_b32_e32 v69, v71
	v_add_f32_e32 v66, v66, v102
	v_add_f32_e32 v67, v67, v103
	v_permlane32_swap_b32_e32 v72, v74
	v_add_f32_e32 v66, v76, v66
	v_add_f32_e32 v67, v77, v67
	v_cvt_pk_bf16_f32 v76, v76, v77
	v_cvt_pk_bf16_f32 v77, v78, v79
	v_permlane32_swap_b32_e32 v73, v75
	v_add_f32_e32 v66, v78, v66
	v_add_f32_e32 v67, v79, v67
	v_cvt_pk_bf16_f32 v78, v80, v81
	v_cvt_pk_bf16_f32 v79, v82, v83
	s_nop 0
	v_add_f32_e32 v66, v80, v66
	v_add_f32_e32 v67, v81, v67
	v_cvt_pk_bf16_f32 v80, v84, v85
	v_cvt_pk_bf16_f32 v81, v86, v87
	v_permlane32_swap_b32_e32 v76, v78
	v_add_f32_e32 v66, v82, v66
	v_add_f32_e32 v67, v83, v67
	v_cvt_pk_bf16_f32 v82, v88, v89
	v_cvt_pk_bf16_f32 v83, v90, v91
	v_permlane32_swap_b32_e32 v77, v79
	v_add_f32_e32 v66, v84, v66
	v_add_f32_e32 v67, v85, v67
	v_permlane32_swap_b32_e32 v80, v82
	v_add_f32_e32 v66, v86, v66
	v_add_f32_e32 v67, v87, v67
	v_permlane32_swap_b32_e32 v81, v83
	v_add_f32_e32 v66, v88, v66
	v_add_f32_e32 v67, v89, v67
	s_nop 0
	v_add_f32_e32 v66, v90, v66
	v_add_f32_e32 v67, v91, v67
	s_nop 0
	v_pk_add_f32 v[66:67], v[66:67], v[66:67] op_sel:[0,1] op_sel_hi:[1,0]
	s_nop 0
	v_mov_b32_e32 v67, v66
	s_nop 1
	v_permlane32_swap_b32_e32 v66, v67
	ds_read_b64_tr_b16 v[84:85], v162 offset:0
	ds_read_b64_tr_b16 v[86:87], v162 offset:0x400
	ds_read_b64_tr_b16 v[88:89], v162 offset:0x800
	ds_read_b64_tr_b16 v[90:91], v162 offset:0xc00
	ds_read_b64_tr_b16 v[92:93], v162 offset:0x1000
	ds_read_b64_tr_b16 v[94:95], v162 offset:0x1400
	ds_read_b64_tr_b16 v[96:97], v162 offset:0x1800
	ds_read_b64_tr_b16 v[98:99], v162 offset:0x1c00
	s_waitcnt lgkmcnt(0)
	s_nop 0
	v_mfma_f32_32x32x16_bf16 v[2:17], v[68:71], v[84:87], v[2:17]
	ds_read_b64_tr_b16 v[84:85], v162 offset:0x200
	ds_read_b64_tr_b16 v[86:87], v162 offset:0x600
	v_mfma_f32_32x32x16_bf16 v[2:17], v[72:75], v[88:91], v[2:17]
	ds_read_b64_tr_b16 v[88:89], v162 offset:0xa00
	ds_read_b64_tr_b16 v[90:91], v162 offset:0xe00
	v_mfma_f32_32x32x16_bf16 v[2:17], v[76:79], v[92:95], v[2:17]
	ds_read_b64_tr_b16 v[92:93], v162 offset:0x1200
	ds_read_b64_tr_b16 v[94:95], v162 offset:0x1600
	v_mfma_f32_32x32x16_bf16 v[2:17], v[80:83], v[96:99], v[2:17]
	ds_read_b64_tr_b16 v[96:97], v162 offset:0x1a00
	ds_read_b64_tr_b16 v[98:99], v162 offset:0x1e00
	s_waitcnt lgkmcnt(0)
	v_mfma_f32_32x32x16_bf16 v[18:33], v[68:71], v[84:87], v[18:33]
	v_max_f32_e32 v68, v51, v51
	v_max_f32_e32 v69, v50, v50
	v_max_f32_e32 v68, v69, v68
	v_max3_f32 v68, v68, v52, v53
	v_max3_f32 v68, v68, v54, v55
	v_max3_f32 v68, v68, v56, v57
	v_max3_f32 v68, v68, v58, v59
	v_mfma_f32_32x32x16_bf16 v[18:33], v[72:75], v[88:91], v[18:33]
	v_max3_f32 v68, v68, v60, v61
	v_max3_f32 v68, v68, v62, v63
	v_max3_f32 v68, v68, v64, v65
	v_max3_f32 v68, v68, v34, v35
	v_max3_f32 v68, v68, v36, v37
	v_max3_f32 v68, v68, v38, v39
	v_max3_f32 v68, v68, v40, v41
	v_mfma_f32_32x32x16_bf16 v[18:33], v[76:79], v[92:95], v[18:33]
	v_max3_f32 v68, v68, v42, v43
	v_max3_f32 v68, v68, v44, v45
	v_max3_f32 v68, v68, v46, v47
	v_max3_f32 v68, v68, v48, v49
	v_mov_b32_e32 v69, v68
	s_nop 1
	v_permlane32_swap_b32_e32 v68, v69
	v_mfma_f32_32x32x16_bf16 v[18:33], v[80:83], v[96:99], v[18:33]
	v_max_f32_e32 v69, v69, v69
	v_max_f32_e32 v68, v68, v68
	v_max_f32_e32 v68, v68, v69
	v_sub_f32_e32 v69, v68, v114
	v_cmp_ge_f32_e32 vcc, s0, v69
	s_cmp_lg_u64 vcc, exec
	s_cbranch_scc1 .LBB0_840

.LBB0_696:
	v_mov_b32_e32 v115, v114
	v_sub_f32_e32 v50, v50, v114
	v_sub_f32_e32 v51, v51, v114
	v_sub_f32_e32 v34, v34, v114
	v_sub_f32_e32 v35, v35, v115
	v_exp_f32_e32 v68, v50
	v_exp_f32_e32 v69, v51
	v_sub_f32_e32 v50, v52, v114
	v_sub_f32_e32 v51, v53, v114
	v_sub_f32_e32 v52, v60, v114
	v_sub_f32_e32 v53, v61, v114
	v_exp_f32_e32 v70, v50
	v_exp_f32_e32 v71, v51
	v_sub_f32_e32 v50, v54, v114
	v_sub_f32_e32 v51, v55, v114
	v_exp_f32_e32 v52, v52
	v_exp_f32_e32 v72, v50
	v_exp_f32_e32 v73, v51
	v_sub_f32_e32 v50, v56, v114
	v_sub_f32_e32 v51, v57, v114
	v_exp_f32_e32 v53, v53
	v_exp_f32_e32 v74, v50
	v_exp_f32_e32 v75, v51
	v_sub_f32_e32 v50, v58, v114
	v_sub_f32_e32 v51, v59, v114
	v_exp_f32_e32 v58, v34
	v_exp_f32_e32 v50, v50
	v_exp_f32_e32 v51, v51
	v_exp_f32_e32 v59, v35
	v_add_f32_e32 v34, 0, v68
	v_add_f32_e32 v35, 0, v69
	v_sub_f32_e32 v54, v62, v114
	v_sub_f32_e32 v55, v63, v114
	v_add_f32_e32 v34, v70, v34
	v_add_f32_e32 v35, v71, v35
	v_exp_f32_e32 v54, v54
	v_exp_f32_e32 v55, v55
	v_sub_f32_e32 v56, v64, v114
	v_sub_f32_e32 v57, v65, v114
	v_add_f32_e32 v34, v72, v34
	v_add_f32_e32 v35, v73, v35
	v_exp_f32_e32 v56, v56
	v_exp_f32_e32 v57, v57
	v_add_f32_e32 v34, v74, v34
	v_add_f32_e32 v35, v75, v35
	v_sub_f32_e32 v36, v36, v114
	v_sub_f32_e32 v37, v37, v115
	v_add_f32_e32 v34, v50, v34
	v_add_f32_e32 v35, v51, v35
	v_sub_f32_e32 v38, v38, v114
	v_sub_f32_e32 v39, v39, v115
	v_exp_f32_e32 v60, v36
	v_exp_f32_e32 v61, v37
	v_add_f32_e32 v34, v52, v34
	v_add_f32_e32 v35, v53, v35
	v_sub_f32_e32 v40, v40, v114
	v_sub_f32_e32 v41, v41, v115
	v_exp_f32_e32 v62, v38
	v_exp_f32_e32 v63, v39
	v_add_f32_e32 v34, v54, v34
	v_add_f32_e32 v35, v55, v35
	v_sub_f32_e32 v42, v42, v114
	v_sub_f32_e32 v43, v43, v115
	v_exp_f32_e32 v64, v40
	v_exp_f32_e32 v65, v41
	v_add_f32_e32 v34, v56, v34
	v_add_f32_e32 v35, v57, v35
	v_sub_f32_e32 v44, v44, v114
	v_sub_f32_e32 v45, v45, v115
	v_exp_f32_e32 v78, v42
	v_exp_f32_e32 v79, v43
	v_add_f32_e32 v34, v58, v34
	v_add_f32_e32 v35, v59, v35
	v_sub_f32_e32 v46, v46, v114
	v_sub_f32_e32 v47, v47, v115
	v_exp_f32_e32 v80, v44
	v_exp_f32_e32 v81, v45
	v_add_f32_e32 v34, v60, v34
	v_add_f32_e32 v35, v61, v35
	v_sub_f32_e32 v48, v48, v114
	v_sub_f32_e32 v49, v49, v115
	v_exp_f32_e32 v82, v46
	v_exp_f32_e32 v83, v47
	v_add_f32_e32 v34, v62, v34
	v_add_f32_e32 v35, v63, v35
	v_exp_f32_e32 v84, v48
	v_exp_f32_e32 v85, v49
	v_add_f32_e32 v34, v64, v34
	v_add_f32_e32 v35, v65, v35
	v_cvt_pk_bf16_f32 v36, v68, v69
	v_cvt_pk_bf16_f32 v37, v70, v71
	v_cvt_pk_bf16_f32 v38, v72, v73
	v_cvt_pk_bf16_f32 v39, v74, v75
	v_cvt_pk_bf16_f32 v40, v50, v51
	s_nop 0
	v_add_f32_e32 v34, v78, v34
	v_add_f32_e32 v35, v79, v35
	v_cvt_pk_bf16_f32 v41, v52, v53
	v_cvt_pk_bf16_f32 v42, v54, v55
	v_cvt_pk_bf16_f32 v43, v56, v57
	v_cvt_pk_bf16_f32 v44, v58, v59
	v_cvt_pk_bf16_f32 v45, v60, v61
	s_nop 0
	v_add_f32_e32 v34, v80, v34
	v_add_f32_e32 v35, v81, v35
	v_cvt_pk_bf16_f32 v46, v62, v63
	v_cvt_pk_bf16_f32 v47, v64, v65
	v_cvt_pk_bf16_f32 v48, v78, v79
	v_cvt_pk_bf16_f32 v49, v80, v81
	v_cvt_pk_bf16_f32 v50, v82, v83
	s_nop 0
	v_add_f32_e32 v34, v82, v34
	v_add_f32_e32 v35, v83, v35
	v_cvt_pk_bf16_f32 v51, v84, v85
	v_permlane32_swap_b32_e32 v36, v38
	v_add_f32_e32 v34, v84, v34
	v_add_f32_e32 v35, v85, v35
	v_permlane32_swap_b32_e32 v37, v39
	v_pk_add_f32 v[34:35], v[34:35], v[34:35] op_sel:[0,1] op_sel_hi:[1,0]
	v_permlane32_swap_b32_e32 v40, v42
	v_mov_b32_e32 v35, v34
	s_nop 1
	v_permlane32_swap_b32_e32 v34, v35
	v_permlane32_swap_b32_e32 v41, v43
	v_permlane32_swap_b32_e32 v44, v46
	v_permlane32_swap_b32_e32 v45, v47
	v_permlane32_swap_b32_e32 v48, v50
	v_permlane32_swap_b32_e32 v49, v51
	ds_read_b64_tr_b16 v[52:53], v155 offset:0
	ds_read_b64_tr_b16 v[54:55], v155 offset:0x400
	ds_read_b64_tr_b16 v[56:57], v155 offset:0x800
	ds_read_b64_tr_b16 v[58:59], v155 offset:0xc00
	ds_read_b64_tr_b16 v[60:61], v155 offset:0x1000
	ds_read_b64_tr_b16 v[62:63], v155 offset:0x1400
	ds_read_b64_tr_b16 v[68:69], v155 offset:0x1800
	ds_read_b64_tr_b16 v[70:71], v155 offset:0x1c00
	s_waitcnt lgkmcnt(0)
	s_nop 0
	v_mfma_f32_32x32x16_bf16 v[2:17], v[36:39], v[52:55], v[2:17]
	ds_read_b64_tr_b16 v[52:53], v155 offset:0x200
	ds_read_b64_tr_b16 v[54:55], v155 offset:0x600
	v_mfma_f32_32x32x16_bf16 v[2:17], v[40:43], v[56:59], v[2:17]
	ds_read_b64_tr_b16 v[56:57], v155 offset:0xa00
	ds_read_b64_tr_b16 v[58:59], v155 offset:0xe00
	v_mfma_f32_32x32x16_bf16 v[2:17], v[44:47], v[60:63], v[2:17]
	ds_read_b64_tr_b16 v[60:61], v155 offset:0x1200
	ds_read_b64_tr_b16 v[62:63], v155 offset:0x1600
	v_mfma_f32_32x32x16_bf16 v[2:17], v[48:51], v[68:71], v[2:17]
	ds_read_b64_tr_b16 v[68:69], v155 offset:0x1a00
	ds_read_b64_tr_b16 v[70:71], v155 offset:0x1e00
	s_waitcnt lgkmcnt(0)
	v_mfma_f32_32x32x16_bf16 v[18:33], v[36:39], v[52:55], v[18:33]
	v_mfma_f32_32x32x16_bf16 v[18:33], v[40:43], v[56:59], v[18:33]
	v_mfma_f32_32x32x16_bf16 v[18:33], v[44:47], v[60:63], v[18:33]
	v_mfma_f32_32x32x16_bf16 v[18:33], v[48:51], v[68:71], v[18:33]
	s_and_saveexec_b64 s[4:5], s[12:13]
	v_add_f32_e32 v36, v66, v67
	v_fmac_f32_e32 v36, v151, v145
	v_add_f32_e32 v34, v34, v35
	v_fmac_f32_e32 v34, v36, v76
	ds_write_b32 v141, v34 offset:32768
	s_or_b64 exec, exec, s[4:5]
	v_lshlrev_b64 v[34:35], 11, v[134:135]
	v_lshl_add_u64 v[34:35], s[36:37], 0, v[34:35]
	v_lshlrev_b32_e32 v36, 1, v138
	v_mov_b32_e32 v37, v0
	v_ashrrev_i32_e32 v141, 31, v140
	v_lshl_add_u64 v[34:35], v[34:35], 0, v[36:37]
	v_lshlrev_b64 v[36:37], 11, v[140:141]
	v_lshl_add_u64 v[34:35], v[34:35], 0, v[36:37]
	v_lshlrev_b32_e32 v36, 1, v137
	v_mov_b32_e32 v37, v0
	v_lshl_add_u64 v[34:35], v[34:35], 0, v[36:37]
	v_add_u32_e32 v36, v149, v136
	s_waitcnt lgkmcnt(0)
	v_add_u32_e32 v38, 0x8000, v36
	ds_read2_b32 v[40:41], v38 offset1:1
	ds_read2_b32 v[42:43], v38 offset0:2 offset1:3
	ds_read2_b32 v[44:45], v38 offset0:8 offset1:9
	v_lshlrev_b32_e32 v36, 13, v139
	v_lshl_add_u64 v[46:47], v[34:35], 0, v[36:37]
	s_waitcnt lgkmcnt(2)
	v_rcp_f32_e32 v39, v40
	v_or_b32_e32 v40, 0x800, v36
	v_mul_f32_e32 v2, v2, v39
	v_cvt_pk_bf16_f32 v2, v2, v0
	flat_store_short v[46:47], v2 offset:1024
	v_mul_f32_e32 v2, v18, v39
	v_cvt_pk_bf16_f32 v2, v2, v0
	flat_store_short v[46:47], v2 offset:1088
	v_rcp_f32_e32 v2, v41
	s_waitcnt lgkmcnt(0)
	v_rcp_f32_e32 v18, v42
	v_mov_b32_e32 v41, v0
	v_lshl_add_u64 v[40:41], v[34:35], 0, v[40:41]
	v_mul_f32_e32 v3, v3, v2
	v_mul_f32_e32 v2, v19, v2
	v_cvt_pk_bf16_f32 v3, v3, v0
	v_cvt_pk_bf16_f32 v2, v2, v0
	flat_store_short v[40:41], v3 offset:1024
	flat_store_short v[40:41], v2 offset:1088
	v_or_b32_e32 v2, 0x1000, v36
	v_mov_b32_e32 v3, v0
	v_mul_f32_e32 v4, v4, v18
	v_lshl_add_u64 v[2:3], v[34:35], 0, v[2:3]
	v_cvt_pk_bf16_f32 v4, v4, v0
	flat_store_short v[2:3], v4 offset:1024
	v_mul_f32_e32 v4, v20, v18
	v_cvt_pk_bf16_f32 v4, v4, v0
	flat_store_short v[2:3], v4 offset:1088
	v_rcp_f32_e32 v4, v43
	v_or_b32_e32 v2, 0x1800, v36
	v_mov_b32_e32 v3, v0
	v_lshl_add_u64 v[2:3], v[34:35], 0, v[2:3]
	v_mul_f32_e32 v5, v5, v4
	v_mul_f32_e32 v4, v21, v4
	v_cvt_pk_bf16_f32 v4, v4, v0
	flat_store_short v[2:3], v4 offset:1088
	v_rcp_f32_e32 v4, v44
	v_cvt_pk_bf16_f32 v5, v5, v0
	flat_store_short v[2:3], v5 offset:1024
	v_or_b32_e32 v2, 0x4000, v36
	v_mov_b32_e32 v3, v0
	v_mul_f32_e32 v5, v6, v4
	v_mul_f32_e32 v4, v22, v4
	v_lshl_add_u64 v[2:3], v[34:35], 0, v[2:3]
	v_cvt_pk_bf16_f32 v4, v4, v0
	flat_store_short v[2:3], v4 offset:1088
	v_rcp_f32_e32 v4, v45
	v_cvt_pk_bf16_f32 v5, v5, v0
	flat_store_short v[2:3], v5 offset:1024
	v_or_b32_e32 v2, 0x4800, v36
	v_mov_b32_e32 v3, v0
	v_lshl_add_u64 v[2:3], v[34:35], 0, v[2:3]
	v_mul_f32_e32 v5, v7, v4
	v_mul_f32_e32 v4, v23, v4
	v_cvt_pk_bf16_f32 v5, v5, v0
	flat_store_short v[2:3], v5 offset:1024
	v_cvt_pk_bf16_f32 v4, v4, v0
	flat_store_short v[2:3], v4 offset:1088
	ds_read2_b32 v[2:3], v38 offset0:10 offset1:11
	v_or_b32_e32 v4, 0x5000, v36
	v_mov_b32_e32 v5, v0
	v_lshl_add_u64 v[4:5], v[34:35], 0, v[4:5]
	s_waitcnt lgkmcnt(0)
	v_rcp_f32_e32 v2, v2
	s_nop 0
	v_mul_f32_e32 v6, v8, v2
	v_mul_f32_e32 v2, v24, v2
	v_cvt_pk_bf16_f32 v6, v6, v0
	flat_store_short v[4:5], v6 offset:1024
	v_cvt_pk_bf16_f32 v2, v2, v0
	flat_store_short v[4:5], v2 offset:1088
	v_rcp_f32_e32 v4, v3
	v_or_b32_e32 v2, 0x5800, v36
	v_mov_b32_e32 v3, v0
	v_lshl_add_u64 v[2:3], v[34:35], 0, v[2:3]
	v_mul_f32_e32 v5, v9, v4
	v_mul_f32_e32 v4, v25, v4
	v_cvt_pk_bf16_f32 v5, v5, v0
	flat_store_short v[2:3], v5 offset:1024
	v_cvt_pk_bf16_f32 v4, v4, v0
	flat_store_short v[2:3], v4 offset:1088
	ds_read2_b32 v[2:3], v38 offset0:16 offset1:17
	v_or_b32_e32 v4, 0x8000, v36
	v_mov_b32_e32 v5, v0
	v_lshl_add_u64 v[4:5], v[34:35], 0, v[4:5]
	s_waitcnt lgkmcnt(0)
	v_rcp_f32_e32 v2, v2
	s_nop 0
	v_mul_f32_e32 v6, v10, v2
	v_mul_f32_e32 v2, v26, v2
	v_cvt_pk_bf16_f32 v6, v6, v0
	flat_store_short v[4:5], v6 offset:1024
	v_cvt_pk_bf16_f32 v2, v2, v0
	flat_store_short v[4:5], v2 offset:1088
	v_rcp_f32_e32 v4, v3
	v_or_b32_e32 v2, 0x8800, v36
	v_mov_b32_e32 v3, v0
	v_lshl_add_u64 v[2:3], v[34:35], 0, v[2:3]
	v_mul_f32_e32 v5, v11, v4
	v_mul_f32_e32 v4, v27, v4
	v_cvt_pk_bf16_f32 v5, v5, v0
	flat_store_short v[2:3], v5 offset:1024
	v_cvt_pk_bf16_f32 v4, v4, v0
	flat_store_short v[2:3], v4 offset:1088
	ds_read2_b32 v[2:3], v38 offset0:18 offset1:19
	v_or_b32_e32 v4, 0x9000, v36
	v_mov_b32_e32 v5, v0
	v_lshl_add_u64 v[4:5], v[34:35], 0, v[4:5]
	s_waitcnt lgkmcnt(0)
	v_rcp_f32_e32 v2, v2
	s_nop 0
	v_mul_f32_e32 v6, v12, v2
	v_mul_f32_e32 v2, v28, v2
	v_cvt_pk_bf16_f32 v6, v6, v0
	flat_store_short v[4:5], v6 offset:1024
	v_cvt_pk_bf16_f32 v2, v2, v0
	flat_store_short v[4:5], v2 offset:1088
	v_rcp_f32_e32 v4, v3
	v_or_b32_e32 v2, 0x9800, v36
	v_mov_b32_e32 v3, v0
	v_lshl_add_u64 v[2:3], v[34:35], 0, v[2:3]
	v_mul_f32_e32 v5, v13, v4
	v_mul_f32_e32 v4, v29, v4
	v_cvt_pk_bf16_f32 v5, v5, v0
	flat_store_short v[2:3], v5 offset:1024
	v_cvt_pk_bf16_f32 v4, v4, v0
	flat_store_short v[2:3], v4 offset:1088
	ds_read2_b32 v[2:3], v38 offset0:24 offset1:25
	v_or_b32_e32 v4, 0xc000, v36
	v_mov_b32_e32 v5, v0
	v_lshl_add_u64 v[4:5], v[34:35], 0, v[4:5]
	s_waitcnt lgkmcnt(0)
	v_rcp_f32_e32 v2, v2
	s_nop 0
	v_mul_f32_e32 v6, v14, v2
	v_mul_f32_e32 v2, v30, v2
	v_cvt_pk_bf16_f32 v6, v6, v0
	flat_store_short v[4:5], v6 offset:1024
	v_cvt_pk_bf16_f32 v2, v2, v0
	flat_store_short v[4:5], v2 offset:1088
	v_rcp_f32_e32 v4, v3
	v_or_b32_e32 v2, 0xc800, v36
	v_mov_b32_e32 v3, v0
	v_lshl_add_u64 v[2:3], v[34:35], 0, v[2:3]
	v_mul_f32_e32 v5, v15, v4
	v_mul_f32_e32 v4, v31, v4
	v_cvt_pk_bf16_f32 v5, v5, v0
	flat_store_short v[2:3], v5 offset:1024
	v_cvt_pk_bf16_f32 v4, v4, v0
	flat_store_short v[2:3], v4 offset:1088
	ds_read2_b32 v[2:3], v38 offset0:26 offset1:27
	v_or_b32_e32 v4, 0xd000, v36
	v_mov_b32_e32 v5, v0
	v_lshl_add_u64 v[4:5], v[34:35], 0, v[4:5]
	s_waitcnt lgkmcnt(0)
	v_rcp_f32_e32 v2, v2
	s_nop 0
	v_mul_f32_e32 v6, v16, v2
	v_mul_f32_e32 v2, v32, v2
	v_cvt_pk_bf16_f32 v6, v6, v0
	flat_store_short v[4:5], v6 offset:1024
	v_cvt_pk_bf16_f32 v2, v2, v0
	flat_store_short v[4:5], v2 offset:1088
	v_rcp_f32_e32 v4, v3
	v_or_b32_e32 v2, 0xd800, v36
	v_mov_b32_e32 v3, v0
	v_lshl_add_u64 v[2:3], v[34:35], 0, v[2:3]
	v_mul_f32_e32 v5, v17, v4
	v_mul_f32_e32 v4, v33, v4
	v_cvt_pk_bf16_f32 v5, v5, v0
	flat_store_short v[2:3], v5 offset:1024
	v_cvt_pk_bf16_f32 v4, v4, v0
	flat_store_short v[2:3], v4 offset:1088
	v_mov_b32_e32 v2, v1

.LBB0_714:
	v_lshrrev_b32_e32 v2, v155, v151
	s_and_b32 s4, s22, 0x80
	v_mov_b32_e32 v3, v0
	v_mov_b32_e32 v1, s4
	v_lshl_add_u64 v[2:3], v[114:115], 0, v[2:3]
	v_cndmask_b32_e64 v54, 0, v1, s[12:13]
	v_mad_u64_u32 v[82:83], s[4:5], v2, s59, v[118:119]
	v_mov_b32_e32 v1, v170
	s_waitcnt lgkmcnt(0)
	s_barrier
	v_mov_b32_e32 v6, v83
	v_mad_u64_u32 v[6:7], s[4:5], v3, s59, v[6:7]
	v_ashrrev_i32_e32 v203, 3, v1
	v_lshlrev_b32_e32 v10, 3, v1
	v_add_u32_e32 v11, 32, v203
	v_lshlrev_b32_e32 v4, 4, v54
	v_mov_b32_e32 v83, v6
	v_and_b32_e32 v202, 56, v10
	v_mad_i64_i32 v[6:7], s[4:5], v203, s35, 0
	v_mad_i64_i32 v[8:9], s[4:5], v11, s35, 0
	v_mov_b32_e32 v5, v0
	v_or_b32_e32 v6, v6, v202
	v_or_b32_e32 v8, v8, v202
	v_lshl_add_u64 v[124:125], v[2:3], 0, v[4:5]
	v_lshl_add_u64 v[6:7], v[6:7], 1, v[82:83]
	v_lshl_add_u64 v[8:9], v[8:9], 1, v[82:83]
	v_mad_u64_u32 v[2:3], s[4:5], v124, s59, v[118:119]
	flat_load_dwordx4 v[98:101], v[6:7] offset:1024
	flat_load_dwordx4 v[102:105], v[8:9] offset:1024
	flat_load_dwordx4 v[106:109], v[6:7] offset:512
	flat_load_dwordx4 v[110:113], v[8:9] offset:512
	v_mov_b32_e32 v4, v3
	v_mad_u64_u32 v[4:5], s[4:5], v125, s59, v[4:5]
	v_ashrrev_i32_e32 v55, 1, v1
	v_mov_b32_e32 v3, v4
	v_bfe_u32 v157, v1, 5, 1
	v_bfi_b32 v126, s1, v55, v1
	s_mov_b32 s4, 0x14000
	v_mad_i64_i32 v[2:3], s[4:5], v126, s4, v[2:3]
	v_lshlrev_b32_e32 v134, 4, v157
	v_mov_b32_e32 v135, v0
	v_lshl_add_u64 v[2:3], v[2:3], 0, v[134:135]
	flat_load_dwordx4 v[74:77], v[2:3]
	flat_load_dwordx4 v[66:69], v[2:3] offset:32
	flat_load_dwordx4 v[70:73], v[2:3] offset:64
	flat_load_dwordx4 v[78:81], v[2:3] offset:96
	v_and_b32_e32 v4, 0x1fffff0, v203
	v_lshlrev_b32_e32 v5, 1, v203
	v_lshrrev_b32_e32 v6, 1, v203
	v_and_b32_e32 v8, 3, v203
	v_bfe_u32 v7, v10, 5, 1
	v_lshlrev_b32_e32 v10, 4, v203
	v_and_or_b32 v4, v5, 8, v4
	v_and_or_b32 v5, v6, 4, v8
	v_and_b32_e32 v8, 0x1fffff0, v11
	v_lshlrev_b32_e32 v12, 1, v11
	v_lshlrev_b32_e32 v9, 7, v203
	v_lshlrev_b32_e32 v6, 1, v202
	v_and_b32_e32 v10, 0x70, v10
	v_lshlrev_b32_e32 v11, 7, v11
	v_lshrrev_b32_e32 v4, 2, v4
	v_and_or_b32 v8, v12, 8, v8
	v_and_b32_e32 v135, 31, v1
	v_and_b32_e32 v13, 48, v6
	v_bitop3_b32 v127, v6, v9, v10 bitop3:0xde
	v_bitop3_b32 v197, v6, v11, v10 bitop3:0xde
	v_or_b32_e32 v4, v4, v7
	v_lshrrev_b32_e32 v6, 2, v8
	v_lshlrev_b32_e32 v2, 4, v1
	v_lshlrev_b32_e32 v5, 6, v5
	v_lshlrev_b32_e32 v4, 9, v4
	v_or_b32_e32 v6, v6, v7
	v_lshlrev_b32_e32 v42, 7, v135
	v_and_b32_e32 v43, 0x70, v2
	v_or3_b32 v198, v4, v5, v13
	v_lshlrev_b32_e32 v4, 9, v6
	v_bitop3_b32 v196, v134, v42, v43 bitop3:0xde
	v_or3_b32 v199, v4, v5, v13
	s_waitcnt vmcnt(0)
	v_or_b32_e32 v34, 32, v134
	v_bitop3_b32 v195, v34, v42, v43 bitop3:0xde
	v_and_b32_e32 v128, 0xffffffe0, v55
	s_waitcnt vmcnt(0) lgkmcnt(0)
	ds_write_b128 v198, v[98:101]
	ds_write_b128 v199, v[102:105]
	ds_write_b128 v127, v[106:109] offset:16384
	ds_write_b128 v197, v[110:113] offset:16384
	s_waitcnt lgkmcnt(0)
	s_barrier
	ds_read_b128 v[2:5], v196 offset:16384
	ds_read_b128 v[18:21], v196 offset:20480
	s_waitcnt lgkmcnt(1)
	v_mfma_f32_32x32x16_bf16 v[2:17], v[2:5], v[74:77], 0
	ds_read_b128 v[34:37], v195 offset:16384
	ds_read_b128 v[38:41], v195 offset:20480
	v_add_u32_e32 v54, v54, v128
	v_sub_u32_e32 v192, 0, v54
	s_mov_b64 s[14:15], exec
	s_waitcnt lgkmcnt(2)
	v_mfma_f32_32x32x16_bf16 v[18:33], v[18:21], v[74:77], 0
	s_waitcnt lgkmcnt(1)
	v_mfma_f32_32x32x16_bf16 v[2:17], v[34:37], v[66:69], v[2:17]
	v_or_b32_e32 v34, 64, v134
	v_bitop3_b32 v194, v34, v42, v43 bitop3:0xde
	s_waitcnt lgkmcnt(0)
	v_mfma_f32_32x32x16_bf16 v[18:33], v[38:41], v[66:69], v[18:33]
	ds_read_b128 v[34:37], v194 offset:16384
	ds_read_b128 v[38:41], v194 offset:20480
	s_waitcnt lgkmcnt(1)
	v_mfma_f32_32x32x16_bf16 v[2:17], v[34:37], v[70:73], v[2:17]
	v_or_b32_e32 v34, 0x60, v134
	v_bitop3_b32 v193, v34, v42, v43 bitop3:0xde
	ds_read_b128 v[34:37], v193 offset:16384
	ds_read_b128 v[50:53], v193 offset:20480
	s_waitcnt lgkmcnt(2)
	v_mfma_f32_32x32x16_bf16 v[18:33], v[38:41], v[70:73], v[18:33]
	v_add_u32_e32 v38, 64, v203
	v_mad_i64_i32 v[38:39], s[4:5], v38, s35, 0
	v_or_b32_e32 v38, v38, v202
	v_lshl_add_u64 v[38:39], v[38:39], 1, v[82:83]
	s_waitcnt lgkmcnt(1)
	v_mfma_f32_32x32x16_bf16 v[2:17], v[34:37], v[78:81], v[2:17]
	v_add_u32_e32 v34, 0x60, v203
	v_mad_i64_i32 v[34:35], s[4:5], v34, s35, 0
	v_or_b32_e32 v34, v34, v202
	v_lshl_add_u64 v[42:43], v[34:35], 1, v[82:83]
	flat_load_dwordx4 v[34:37], v[38:39] offset:1024
	s_nop 0
	flat_load_dwordx4 v[38:41], v[38:39] offset:512
	s_nop 0
	flat_load_dwordx4 v[46:49], v[42:43] offset:1024
	s_nop 0
	flat_load_dwordx4 v[42:45], v[42:43] offset:512
	s_waitcnt lgkmcnt(0)
	v_mfma_f32_32x32x16_bf16 v[18:33], v[50:53], v[78:81], v[18:33]
	v_sub_u32_e32 v50, v192, v135
	v_lshl_add_u32 v201, v50, 2, v134
	v_add_u32_e32 v50, 0x9600, v201
	v_add_u32_e32 v52, 0x9680, v201
	v_add_u32_e32 v54, 0x9608, v201
	ds_read2_b32 v[50:51], v50 offset1:1
	ds_read2_b32 v[52:53], v52 offset1:1
	ds_read2_b32 v[54:55], v54 offset1:1
	v_add_u32_e32 v56, 0x9688, v201
	v_add_u32_e32 v58, 0x9628, v201
	s_waitcnt lgkmcnt(0)
	v_add_f32_e32 v50, v2, v50
	v_add_f32_e32 v51, v3, v51
	v_add_f32_e32 v2, v18, v52
	v_add_f32_e32 v3, v19, v53
	v_add_f32_e32 v18, v4, v54
	v_add_f32_e32 v19, v5, v55
	v_add_u32_e32 v4, 0x9620, v201
	v_add_u32_e32 v60, 0x96a8, v201
	ds_read2_b32 v[56:57], v56 offset1:1
	v_add_u32_e32 v5, 0x96a0, v201
	ds_read2_b32 v[52:53], v4 offset1:1
	ds_read2_b32 v[54:55], v5 offset1:1
	ds_read2_b32 v[58:59], v58 offset1:1
	ds_read2_b32 v[60:61], v60 offset1:1
	s_waitcnt lgkmcnt(0)
	v_add_f32_e32 v52, v6, v52
	v_add_f32_e32 v53, v7, v53
	v_add_f32_e32 v6, v22, v54
	v_add_f32_e32 v7, v23, v55
	v_add_u32_e32 v22, 0x9640, v201
	v_add_f32_e32 v4, v20, v56
	v_add_f32_e32 v5, v21, v57
	v_add_f32_e32 v20, v8, v58
	v_add_f32_e32 v21, v9, v59
	v_add_f32_e32 v8, v24, v60
	v_add_f32_e32 v9, v25, v61
	v_add_u32_e32 v24, 0x96c0, v201
	v_add_u32_e32 v25, 0x9648, v201
	ds_read2_b32 v[22:23], v22 offset1:1
	ds_read2_b32 v[54:55], v24 offset1:1
	ds_read2_b32 v[56:57], v25 offset1:1
	v_add_u32_e32 v24, 0x96c8, v201
	ds_read2_b32 v[58:59], v24 offset1:1
	s_waitcnt lgkmcnt(0)
	v_add_f32_e32 v24, v10, v22
	v_add_f32_e32 v25, v11, v23
	v_add_u32_e32 v60, 0x96e8, v201
	v_add_f32_e32 v22, v12, v56
	v_add_f32_e32 v23, v13, v57
	v_add_u32_e32 v12, 0x9660, v201
	v_add_u32_e32 v56, 0x9668, v201
	v_add_f32_e32 v10, v26, v54
	v_add_f32_e32 v11, v27, v55
	v_add_u32_e32 v13, 0x96e0, v201
	ds_read2_b32 v[26:27], v12 offset1:1
	ds_read2_b32 v[54:55], v13 offset1:1
	ds_read2_b32 v[56:57], v56 offset1:1
	ds_read2_b32 v[60:61], v60 offset1:1
	v_add_f32_e32 v12, v28, v58
	v_add_f32_e32 v13, v29, v59
	s_waitcnt lgkmcnt(0)
	v_add_f32_e32 v28, v14, v26
	v_add_f32_e32 v29, v15, v27
	v_add_f32_e32 v14, v30, v54
	v_add_f32_e32 v15, v31, v55
	v_max_f32_e32 v30, v50, v51
	v_max3_f32 v30, v30, v18, v19
	v_max3_f32 v30, v30, v52, v53
	v_max3_f32 v30, v30, v20, v21
	v_max3_f32 v30, v30, v24, v25
	v_max3_f32 v30, v30, v22, v23
	v_add_f32_e32 v26, v16, v56
	v_add_f32_e32 v27, v17, v57
	v_max3_f32 v30, v30, v28, v29
	v_max3_f32 v30, v30, v26, v27
	v_max3_f32 v30, v30, v2, v3
	v_max3_f32 v30, v30, v4, v5
	v_max3_f32 v30, v30, v6, v7
	v_max3_f32 v30, v30, v8, v9
	v_max3_f32 v30, v30, v10, v11
	v_max3_f32 v30, v30, v12, v13
	v_add_f32_e32 v16, v32, v60
	v_add_f32_e32 v17, v33, v61
	v_max3_f32 v30, v30, v14, v15
	v_max3_f32 v30, v30, v16, v17
	v_mov_b32_e32 v31, v30
	s_nop 1
	v_permlane32_swap_b32_e32 v30, v31
	v_max_f32_e32 v31, v31, v31
	v_max_f32_e32 v30, v30, v30
	v_max_f32_e32 v30, v30, v31
	v_add_f32_e32 v31, 0x7149f2ca, v30
	v_cmp_ge_f32_e32 vcc, s0, v31
	s_and_saveexec_b64 s[8:9], s[12:13]
	s_cbranch_execz .LBB0_716
	v_add_u32_e32 v31, 0x80, v203
	v_mad_i64_i32 v[32:33], s[4:5], v31, s35, 0
	v_add_u32_e32 v31, 0xa0, v203
	v_or_b32_e32 v32, v32, v202
	v_mad_i64_i32 v[54:55], s[4:5], v31, s35, 0
	v_lshl_add_u64 v[32:33], v[32:33], 1, v[82:83]
	v_or_b32_e32 v54, v54, v202
	v_lshl_add_u64 v[54:55], v[54:55], 1, v[82:83]
	flat_load_dwordx4 v[98:101], v[32:33] offset:1024
	flat_load_dwordx4 v[106:109], v[32:33] offset:512
	flat_load_dwordx4 v[102:105], v[54:55] offset:1024
	flat_load_dwordx4 v[110:113], v[54:55] offset:512
.LBB0_716:
	s_or_b64 exec, exec, s[8:9]
	v_and_b32_e32 v129, 63, v1
	v_and_b32_e32 v1, 0x3fffffc0, v1
	v_lshlrev_b32_e32 v31, 4, v129
	v_lshlrev_b32_e32 v168, 2, v1
	v_lshlrev_b32_e32 v1, 3, v129
	v_and_b32_e32 v31, 0xc0, v31
	v_lshlrev_b32_e32 v32, 1, v129
	v_and_or_b32 v31, v1, 24, v31
	v_and_b32_e32 v32, 32, v32
	v_and_b32_e32 v1, 0x100, v1
	v_or3_b32 v169, v31, v32, v1
	v_max_f32_e32 v1, v30, v30
	v_max_f32_e32 v1, 0xf149f2ca, v1
	v_sub_f32_e32 v30, 0xf149f2ca, v1
	v_exp_f32_e32 v30, v30
	s_cmp_eq_u64 vcc, s[14:15]
	s_cselect_b64 vcc, -1, 0
	v_cndmask_b32_e32 v200, v1, v178, vcc
	v_cndmask_b32_e64 v191, v30, 1.0, vcc
	v_cndmask_b32_e32 v30, v1, v178, vcc
	v_sub_f32_e32 v18, v18, v30
	v_sub_f32_e32 v19, v19, v30
	v_sub_f32_e32 v32, v50, v30
	v_sub_f32_e32 v33, v51, v30
	v_exp_f32_e32 v96, v18
	v_exp_f32_e32 v97, v19
	v_sub_f32_e32 v18, v52, v30
	v_sub_f32_e32 v19, v53, v30
	v_exp_f32_e32 v138, v32
	v_exp_f32_e32 v94, v18
	v_exp_f32_e32 v95, v19
	v_sub_f32_e32 v18, v20, v30
	v_sub_f32_e32 v19, v21, v30
	v_exp_f32_e32 v139, v33
	v_exp_f32_e32 v92, v18
	v_exp_f32_e32 v93, v19
	v_sub_f32_e32 v18, v24, v30
	v_sub_f32_e32 v19, v25, v30
	v_sub_f32_e32 v142, v14, v30
	v_sub_f32_e32 v143, v15, v30
	v_exp_f32_e32 v90, v18
	v_exp_f32_e32 v91, v19
	v_sub_f32_e32 v18, v22, v30
	v_sub_f32_e32 v19, v23, v30
	v_mov_b32_e32 v14, v0
	v_exp_f32_e32 v88, v18
	v_exp_f32_e32 v89, v19
	v_sub_f32_e32 v18, v28, v30
	v_sub_f32_e32 v19, v29, v30
	v_mov_b32_e32 v15, v0
	v_exp_f32_e32 v86, v18
	v_exp_f32_e32 v87, v19
	v_sub_f32_e32 v18, v26, v30
	v_sub_f32_e32 v19, v27, v30
	v_sub_f32_e32 v166, v2, v30
	v_sub_f32_e32 v167, v3, v30
	v_exp_f32_e32 v84, v18
	v_exp_f32_e32 v85, v19
	v_sub_f32_e32 v164, v4, v30
	v_sub_f32_e32 v165, v5, v30
	v_sub_f32_e32 v162, v6, v30
	v_sub_f32_e32 v163, v7, v30
	v_sub_f32_e32 v160, v8, v30
	v_sub_f32_e32 v161, v9, v30
	v_sub_f32_e32 v158, v10, v30
	v_sub_f32_e32 v159, v11, v30
	v_sub_f32_e32 v144, v12, v30
	v_sub_f32_e32 v145, v13, v30
	v_sub_f32_e32 v140, v16, v30
	v_sub_f32_e32 v141, v17, v30
	s_waitcnt vmcnt(4)
	v_mov_b32_e32 v1, v0
	v_mov_b32_e32 v2, v0
	v_mov_b32_e32 v3, v0
	v_mov_b32_e32 v4, v0
	v_mov_b32_e32 v5, v0
	v_mov_b32_e32 v6, v0
	v_mov_b32_e32 v7, v0
	v_mov_b32_e32 v8, v0
	v_mov_b32_e32 v9, v0
	v_mov_b32_e32 v10, v0
	v_mov_b32_e32 v11, v0
	v_mov_b32_e32 v12, v0
	v_mov_b32_e32 v13, v0
	v_mov_b64_e32 v[32:33], v[14:15]
	v_mov_b64_e32 v[30:31], v[12:13]
	v_mov_b64_e32 v[28:29], v[10:11]
	v_mov_b64_e32 v[26:27], v[8:9]
	v_mov_b64_e32 v[24:25], v[6:7]
	v_mov_b64_e32 v[22:23], v[4:5]
	v_mov_b64_e32 v[20:21], v[2:3]
	v_mov_b64_e32 v[18:19], v[0:1]
	v_mov_b64_e32 v[16:17], v[14:15]
	v_mov_b32_e32 v136, 0
	v_mov_b64_e32 v[14:15], v[12:13]
	v_mov_b64_e32 v[12:13], v[10:11]
	v_mov_b64_e32 v[10:11], v[8:9]
	v_mov_b64_e32 v[8:9], v[6:7]
	v_mov_b64_e32 v[6:7], v[4:5]
	v_mov_b64_e32 v[4:5], v[2:3]
	v_mov_b64_e32 v[2:3], v[0:1]
	s_waitcnt vmcnt(0)
	ds_write_b128 v198, v[34:37] offset:8192
	ds_write_b128 v199, v[46:49] offset:8192
	ds_write_b128 v127, v[38:41] offset:24576
	ds_write_b128 v197, v[42:45] offset:24576
	s_waitcnt lgkmcnt(0)
	s_barrier
	s_and_saveexec_b64 s[20:21], s[12:13]
	s_cbranch_execz .LBB0_732
	ds_read_b128 v[2:5], v196 offset:24576
	ds_read_b128 v[6:9], v196 offset:28672
	v_add_f32_e32 v18, 0, v138
	v_add_f32_e32 v19, 0, v139
	v_exp_f32_e32 v10, v158
	v_add_f32_e32 v18, v18, v96
	v_add_f32_e32 v19, v19, v97
	s_waitcnt lgkmcnt(1)
	v_mfma_f32_32x32x16_bf16 v[34:49], v[2:5], v[74:77], 0
	v_add_f32_e64 v18, v18, v94
	v_add_f32_e64 v19, v19, v95
	v_exp_f32_e32 v11, v159
	v_add_f32_e32 v18, v18, v92
	v_add_f32_e32 v19, v19, v93
	v_exp_f32_e32 v12, v144
	v_add_f32_e32 v18, v18, v90
	v_add_f32_e32 v19, v19, v91
	v_exp_f32_e32 v13, v145
	v_add_f32_e32 v18, v18, v88
	v_add_f32_e32 v19, v19, v89
	s_waitcnt lgkmcnt(0)
	v_mfma_f32_32x32x16_bf16 v[50:65], v[6:9], v[74:77], 0
	ds_read_b128 v[2:5], v195 offset:24576
	ds_read_b128 v[6:9], v195 offset:28672
	v_add_f32_e64 v18, v18, v86
	v_add_f32_e64 v19, v19, v87
	v_exp_f32_e32 v14, v142
	v_add_f32_e32 v18, v18, v84
	v_add_f32_e32 v19, v19, v85
	v_exp_f32_e32 v15, v143
	v_exp_f32_e32 v16, v140
	v_exp_f32_e32 v17, v141
	s_waitcnt lgkmcnt(1)
	v_mfma_f32_32x32x16_bf16 v[34:49], v[2:5], v[66:69], v[34:49]
	v_cvt_pk_bf16_f32 v20, v94, v95
	v_cvt_pk_bf16_f32 v21, v92, v93
	v_cvt_pk_bf16_f32 v140, v86, v87
	v_cvt_pk_bf16_f32 v141, v84, v85
	v_cvt_pk_bf16_f32 v158, v10, v11
	v_cvt_pk_bf16_f32 v159, v12, v13
	s_waitcnt lgkmcnt(0)
	v_mfma_f32_32x32x16_bf16 v[50:65], v[6:9], v[66:69], v[50:65]
	ds_read_b128 v[2:5], v194 offset:24576
	ds_read_b128 v[6:9], v194 offset:28672
	s_waitcnt lgkmcnt(1)
	v_mfma_f32_32x32x16_bf16 v[34:49], v[2:5], v[70:73], v[34:49]
	s_waitcnt lgkmcnt(0)
	v_mfma_f32_32x32x16_bf16 v[50:65], v[6:9], v[70:73], v[50:65]
	ds_read_b128 v[2:5], v193 offset:24576
	ds_read_b128 v[6:9], v193 offset:28672
	s_waitcnt lgkmcnt(1)
	v_mfma_f32_32x32x16_bf16 v[34:49], v[2:5], v[78:81], v[34:49]
	v_exp_f32_e32 v2, v166
	v_exp_f32_e32 v3, v167
	v_exp_f32_e32 v4, v164
	v_exp_f32_e32 v5, v165
	v_cvt_pk_bf16_f32 v142, v2, v3
	v_add_f32_e32 v18, v2, v18
	v_add_f32_e32 v19, v3, v19
	v_cvt_pk_bf16_f32 v143, v4, v5
	s_waitcnt lgkmcnt(0)
	v_mfma_f32_32x32x16_bf16 v[50:65], v[6:9], v[78:81], v[50:65]
	v_exp_f32_e32 v6, v162
	v_exp_f32_e32 v7, v163
	v_exp_f32_e32 v8, v160
	v_exp_f32_e32 v9, v161
	v_add_f32_e32 v18, v4, v18
	v_add_f32_e32 v19, v5, v19
	v_cvt_pk_bf16_f32 v144, v6, v7
	v_cvt_pk_bf16_f32 v145, v8, v9
	v_cvt_pk_bf16_f32 v160, v14, v15
	v_cvt_pk_bf16_f32 v161, v16, v17
	s_nop 0
	v_add_f32_e32 v18, v6, v18
	v_add_f32_e32 v19, v7, v19
	v_permlane32_swap_b32_e32 v142, v144
	v_add_f32_e32 v18, v8, v18
	v_add_f32_e32 v19, v9, v19
	v_permlane32_swap_b32_e32 v143, v145
	v_add_f32_e32 v18, v10, v18
	v_add_f32_e32 v19, v11, v19
	v_permlane32_swap_b32_e32 v158, v160
	v_add_f32_e32 v18, v12, v18
	v_add_f32_e32 v19, v13, v19
	v_permlane32_swap_b32_e32 v159, v161
	v_add_f32_e32 v18, v14, v18
	v_add_f32_e32 v19, v15, v19
	s_nop 0
	v_add_f32_e32 v18, v16, v18
	v_add_f32_e32 v19, v17, v19
	s_nop 0
	v_add_f32_e32 v136, v18, v19
	v_add_f32_e32 v137, v19, v18
	v_cvt_pk_bf16_f32 v18, v138, v139
	v_cvt_pk_bf16_f32 v19, v96, v97
	v_cvt_pk_bf16_f32 v138, v90, v91
	v_cvt_pk_bf16_f32 v139, v88, v89
	s_nop 0
	v_mov_b32_e32 v1, v136
	s_nop 1
	v_permlane32_swap_b32_e32 v136, v1
	v_permlane32_swap_b32_e32 v18, v20
	v_permlane32_swap_b32_e32 v19, v21
	v_permlane32_swap_b32_e32 v138, v140
	v_permlane32_swap_b32_e32 v139, v141
	v_add_u32_e32 v2, 0xc0, v203
	v_mad_i64_i32 v[2:3], s[4:5], v2, s35, 0
	v_add_u32_e32 v4, 0xe0, v203
	v_or_b32_e32 v2, v2, v202
	v_mad_i64_i32 v[4:5], s[4:5], v4, s35, 0
	v_lshl_add_u64 v[2:3], v[2:3], 1, v[82:83]
	v_or_b32_e32 v4, v4, v202
	v_lshl_add_u64 v[4:5], v[4:5], 1, v[82:83]
	flat_load_dwordx4 v[82:85], v[2:3] offset:1024
	flat_load_dwordx4 v[86:89], v[2:3] offset:512
	flat_load_dwordx4 v[94:97], v[4:5] offset:1024
	flat_load_dwordx4 v[90:93], v[4:5] offset:512
	ds_read_b64_tr_b16 v[2:3], v169 offset:0
	ds_read_b64_tr_b16 v[4:5], v169 offset:0x400
	ds_read_b64_tr_b16 v[22:23], v169 offset:0x800
	ds_read_b64_tr_b16 v[24:25], v169 offset:0xc00
	ds_read_b64_tr_b16 v[26:27], v169 offset:0x1000
	ds_read_b64_tr_b16 v[28:29], v169 offset:0x1400
	ds_read_b64_tr_b16 v[30:31], v169 offset:0x1800
	ds_read_b64_tr_b16 v[32:33], v169 offset:0x1c00
	s_waitcnt lgkmcnt(0)
	s_nop 0
	v_mfma_f32_32x32x16_bf16 v[2:17], v[18:21], v[2:5], 0
	v_mfma_f32_32x32x16_bf16 v[2:17], v[138:141], v[22:25], v[2:17]
	ds_read_b64_tr_b16 v[22:23], v169 offset:0x200
	ds_read_b64_tr_b16 v[24:25], v169 offset:0x600
	ds_read_b64_tr_b16 v[162:163], v169 offset:0xa00
	ds_read_b64_tr_b16 v[164:165], v169 offset:0xe00
	ds_read_b64_tr_b16 v[202:203], v169 offset:0x1200
	ds_read_b64_tr_b16 v[204:205], v169 offset:0x1600
	ds_read_b64_tr_b16 v[206:207], v169 offset:0x1a00
	v_mfma_f32_32x32x16_bf16 v[2:17], v[142:145], v[26:29], v[2:17]
	ds_read_b64_tr_b16 v[208:209], v169 offset:0x1e00
	s_waitcnt lgkmcnt(0)
	v_mfma_f32_32x32x16_bf16 v[2:17], v[158:161], v[30:33], v[2:17]
	v_mfma_f32_32x32x16_bf16 v[18:33], v[18:21], v[22:25], 0
	v_add_u32_e32 v137, 0x9700, v201
	v_mfma_f32_32x32x16_bf16 v[18:33], v[138:141], v[162:165], v[18:33]
	ds_read2_b32 v[138:139], v137 offset1:1
	v_add_u32_e32 v137, 0x9780, v201
	ds_read2_b32 v[140:141], v137 offset1:1
	v_add_u32_e32 v137, 0x9788, v201
	s_waitcnt lgkmcnt(0)
	v_add_f32_e32 v138, v34, v138
	v_add_f32_e32 v139, v35, v139
	v_add_f32_e32 v34, v50, v140
	v_add_f32_e32 v35, v51, v141
	v_add_u32_e32 v50, 0x9708, v201
	ds_read2_b32 v[50:51], v50 offset1:1
	ds_read2_b32 v[140:141], v137 offset1:1
	v_add_u32_e32 v137, 0x97a0, v201
	v_mfma_f32_32x32x16_bf16 v[18:33], v[142:145], v[202:205], v[18:33]
	s_waitcnt lgkmcnt(0)
	v_add_f32_e64 v50, v36, v50
	v_add_f32_e64 v51, v37, v51
	v_add_f32_e64 v36, v52, v140
	v_add_f32_e64 v37, v53, v141
	v_add_u32_e32 v52, 0x9720, v201
	ds_read2_b32 v[52:53], v52 offset1:1
	ds_read2_b32 v[140:141], v137 offset1:1
	v_add_u32_e32 v137, 0x97a8, v201
	v_mfma_f32_32x32x16_bf16 v[18:33], v[158:161], v[206:209], v[18:33]
	s_waitcnt lgkmcnt(0)
	v_add_f32_e64 v52, v38, v52
	v_add_f32_e64 v53, v39, v53
	v_add_f32_e64 v38, v54, v140
	v_add_f32_e64 v39, v55, v141
	v_add_u32_e32 v54, 0x9728, v201
	ds_read2_b32 v[54:55], v54 offset1:1
	ds_read2_b32 v[140:141], v137 offset1:1
	v_add_u32_e32 v137, 0x97c0, v201
	s_waitcnt lgkmcnt(0)
	v_add_f32_e32 v54, v40, v54
	v_add_f32_e32 v55, v41, v55
	v_add_f32_e32 v40, v56, v140
	v_add_f32_e32 v41, v57, v141
	v_add_u32_e32 v56, 0x9740, v201
	ds_read2_b32 v[56:57], v56 offset1:1
	ds_read2_b32 v[140:141], v137 offset1:1
	v_add_u32_e32 v137, 0x97c8, v201
	s_waitcnt lgkmcnt(0)
	v_add_f32_e32 v56, v42, v56
	v_add_f32_e32 v57, v43, v57
	v_add_f32_e32 v42, v58, v140
	v_add_f32_e32 v43, v59, v141
	v_add_u32_e32 v58, 0x9748, v201
	ds_read2_b32 v[58:59], v58 offset1:1
	ds_read2_b32 v[140:141], v137 offset1:1
	v_add_u32_e32 v137, 0x97e0, v201
	s_waitcnt lgkmcnt(0)
	v_add_f32_e32 v58, v44, v58
	v_add_f32_e32 v59, v45, v59
	v_add_f32_e32 v44, v60, v140
	v_add_f32_e32 v45, v61, v141
	v_add_u32_e32 v60, 0x9760, v201
	ds_read2_b32 v[60:61], v60 offset1:1
	ds_read2_b32 v[140:141], v137 offset1:1
	v_add_u32_e32 v137, 0x97e8, v201
	s_waitcnt lgkmcnt(0)
	v_add_f32_e32 v60, v46, v60
	v_add_f32_e32 v61, v47, v61
	v_add_f32_e32 v46, v62, v140
	v_add_f32_e32 v47, v63, v141
	v_add_u32_e32 v62, 0x9768, v201
	ds_read2_b32 v[62:63], v62 offset1:1
	ds_read2_b32 v[140:141], v137 offset1:1
	s_waitcnt lgkmcnt(0)
	v_add_f32_e32 v62, v48, v62
	v_add_f32_e32 v63, v49, v63
	v_add_f32_e32 v48, v64, v140
	v_add_f32_e32 v49, v65, v141
	v_max_f32_e32 v64, v138, v139
	v_max3_f32 v64, v64, v50, v51
	v_max3_f32 v64, v64, v52, v53
	v_max3_f32 v64, v64, v54, v55
	v_max3_f32 v64, v64, v56, v57
	v_max3_f32 v64, v64, v58, v59
	v_max3_f32 v64, v64, v60, v61
	v_max3_f32 v64, v64, v62, v63
	v_max3_f32 v64, v64, v34, v35
	v_max3_f32 v64, v64, v36, v37
	v_max3_f32 v64, v64, v38, v39
	v_max3_f32 v64, v64, v40, v41
	v_max3_f32 v64, v64, v42, v43
	v_max3_f32 v64, v64, v44, v45
	v_max3_f32 v64, v64, v46, v47
	v_max3_f32 v64, v64, v48, v49
	v_mov_b32_e32 v65, v64
	s_nop 1
	v_permlane32_swap_b32_e32 v64, v65
	v_max_f32_e32 v65, v65, v65
	v_max_f32_e32 v64, v64, v64
	v_max_f32_e32 v64, v64, v65
	v_sub_f32_e32 v65, v64, v200
	v_cmp_ge_f32_e32 vcc, s0, v65
	s_cmp_lg_u64 vcc, exec
	s_cbranch_scc1 .LBB0_744
	v_mov_b32_e32 v64, v200

.LBB0_724:
	v_mov_b32_e32 v65, v64
	v_sub_f32_e32 v50, v50, v64
	v_sub_f32_e32 v51, v51, v64
	v_sub_f32_e32 v98, v138, v64
	v_sub_f32_e32 v99, v139, v64
	v_exp_f32_e32 v112, v50
	v_exp_f32_e32 v113, v51
	v_sub_f32_e32 v50, v52, v64
	v_sub_f32_e32 v51, v53, v64
	v_exp_f32_e32 v138, v98
	v_exp_f32_e32 v110, v50
	v_exp_f32_e32 v111, v51
	v_sub_f32_e32 v50, v54, v64
	v_sub_f32_e32 v51, v55, v64
	v_exp_f32_e32 v139, v99
	v_exp_f32_e32 v108, v50
	v_exp_f32_e32 v109, v51
	v_sub_f32_e32 v50, v56, v64
	v_sub_f32_e32 v51, v57, v64
	v_sub_f32_e32 v98, v34, v64
	v_sub_f32_e32 v99, v35, v65
	v_exp_f32_e32 v106, v50
	v_exp_f32_e32 v107, v51
	v_sub_f32_e32 v50, v58, v64
	v_sub_f32_e32 v51, v59, v64
	v_sub_f32_e32 v162, v36, v64
	v_sub_f32_e32 v163, v37, v65
	v_exp_f32_e32 v104, v50
	v_exp_f32_e32 v105, v51
	v_sub_f32_e32 v50, v60, v64
	v_sub_f32_e32 v51, v61, v64
	v_sub_f32_e32 v164, v38, v64
	v_sub_f32_e32 v165, v39, v65
	v_exp_f32_e32 v102, v50
	v_exp_f32_e32 v103, v51
	v_sub_f32_e32 v50, v62, v64
	v_sub_f32_e32 v51, v63, v64
	v_sub_f32_e32 v166, v40, v64
	v_sub_f32_e32 v167, v41, v65
	v_exp_f32_e32 v100, v50
	v_exp_f32_e32 v101, v51
	v_sub_f32_e32 v180, v42, v64
	v_sub_f32_e32 v181, v43, v65
	v_sub_f32_e32 v182, v44, v64
	v_sub_f32_e32 v183, v45, v65
	v_sub_f32_e32 v202, v46, v64
	v_sub_f32_e32 v203, v47, v65
	v_sub_f32_e32 v204, v48, v64
	v_sub_f32_e32 v205, v49, v65
	v_or_b32_e32 v154, 0x2000, v169
	s_waitcnt lgkmcnt(0)
	s_barrier
	ds_read_b128 v[34:37], v196 offset:16384
	ds_read_b128 v[50:53], v196 offset:20480
	ds_read_b128 v[142:145], v195 offset:16384
	ds_read_b128 v[158:161], v195 offset:20480
	s_waitcnt lgkmcnt(0)
	v_mfma_f32_32x32x16_bf16 v[34:49], v[34:37], v[74:77], 0
	v_mfma_f32_32x32x16_bf16 v[50:65], v[50:53], v[74:77], 0
	v_mfma_f32_32x32x16_bf16 v[50:65], v[158:161], v[66:69], v[50:65]
	v_mfma_f32_32x32x16_bf16 v[34:49], v[142:145], v[66:69], v[34:49]
	ds_read_b128 v[142:145], v194 offset:16384
	ds_read_b128 v[158:161], v194 offset:20480
	s_waitcnt lgkmcnt(0)
	v_mfma_f32_32x32x16_bf16 v[50:65], v[158:161], v[70:73], v[50:65]
	v_mfma_f32_32x32x16_bf16 v[34:49], v[142:145], v[70:73], v[34:49]
	ds_read_b128 v[142:145], v193 offset:16384
	ds_read_b128 v[158:161], v193 offset:20480
	s_waitcnt lgkmcnt(0)
	v_mfma_f32_32x32x16_bf16 v[50:65], v[158:161], v[78:81], v[50:65]
	v_exp_f32_e32 v158, v98
	v_exp_f32_e32 v159, v99
	v_add_f32_e32 v98, 0, v138
	v_add_f32_e32 v99, 0, v139
	v_exp_f32_e32 v160, v162
	v_add_f32_e32 v98, v112, v98
	v_add_f32_e32 v99, v113, v99
	v_exp_f32_e32 v161, v163
	v_add_f32_e32 v98, v110, v98
	v_add_f32_e32 v99, v111, v99
	v_exp_f32_e32 v162, v164
	v_add_f32_e32 v98, v108, v98
	v_add_f32_e32 v99, v109, v99
	v_exp_f32_e32 v163, v165
	v_add_f32_e32 v98, v106, v98
	v_add_f32_e32 v99, v107, v99
	v_exp_f32_e32 v164, v166
	v_add_f32_e32 v98, v104, v98
	v_add_f32_e32 v99, v105, v99
	v_exp_f32_e32 v165, v167
	v_add_f32_e32 v98, v102, v98
	v_add_f32_e32 v99, v103, v99
	v_exp_f32_e32 v166, v180
	v_add_f32_e32 v98, v100, v98
	v_add_f32_e32 v99, v101, v99
	v_exp_f32_e32 v167, v181
	v_add_f32_e32 v98, v158, v98
	v_add_f32_e32 v99, v159, v99
	v_exp_f32_e32 v180, v182
	v_exp_f32_e32 v181, v183
	v_add_f32_e32 v98, v160, v98
	v_add_f32_e32 v99, v161, v99
	v_exp_f32_e32 v182, v202
	v_exp_f32_e32 v183, v203
	v_add_f32_e32 v98, v162, v98
	v_add_f32_e32 v99, v163, v99
	v_mfma_f32_32x32x16_bf16 v[34:49], v[142:145], v[78:81], v[34:49]
	v_exp_f32_e32 v202, v204
	v_exp_f32_e32 v203, v205
	v_add_f32_e32 v98, v164, v98
	v_add_f32_e32 v99, v165, v99
	v_cvt_pk_bf16_f32 v145, v108, v109
	v_cvt_pk_bf16_f32 v108, v102, v103
	v_cvt_pk_bf16_f32 v109, v100, v101
	v_cvt_pk_bf16_f32 v100, v158, v159
	v_cvt_pk_bf16_f32 v101, v160, v161
	s_nop 0
	v_add_f32_e32 v98, v166, v98
	v_add_f32_e32 v99, v167, v99
	v_cvt_pk_bf16_f32 v102, v162, v163
	v_cvt_pk_bf16_f32 v103, v164, v165
	v_cvt_pk_bf16_f32 v142, v138, v139
	v_cvt_pk_bf16_f32 v143, v112, v113
	v_cvt_pk_bf16_f32 v144, v110, v111
	s_nop 0
	v_add_f32_e32 v98, v180, v98
	v_add_f32_e32 v99, v181, v99
	v_cvt_pk_bf16_f32 v106, v106, v107
	v_cvt_pk_bf16_f32 v107, v104, v105
	v_permlane32_swap_b32_e32 v100, v102
	v_add_f32_e32 v98, v182, v98
	v_add_f32_e32 v99, v183, v99
	v_permlane32_swap_b32_e32 v101, v103
	v_add_f32_e32 v98, v202, v98
	v_add_f32_e32 v99, v203, v99
	v_cvt_pk_bf16_f32 v110, v166, v167
	v_cvt_pk_bf16_f32 v111, v180, v181
	v_cvt_pk_bf16_f32 v112, v182, v183
	v_cvt_pk_bf16_f32 v113, v202, v203
	v_permlane32_swap_b32_e32 v142, v144
	v_pk_add_f32 v[98:99], v[98:99], v[98:99] op_sel:[0,1] op_sel_hi:[1,0]
	v_permlane32_swap_b32_e32 v143, v145
	v_mov_b32_e32 v99, v98
	s_nop 1
	v_permlane32_swap_b32_e32 v98, v99
	v_permlane32_swap_b32_e32 v106, v108
	v_permlane32_swap_b32_e32 v107, v109
	v_permlane32_swap_b32_e32 v110, v112
	v_permlane32_swap_b32_e32 v111, v113
	ds_read_b64_tr_b16 v[158:159], v154 offset:0
	ds_read_b64_tr_b16 v[160:161], v154 offset:0x400
	ds_read_b64_tr_b16 v[162:163], v154 offset:0x800
	ds_read_b64_tr_b16 v[164:165], v154 offset:0xc00
	ds_read_b64_tr_b16 v[202:203], v154 offset:0x1000
	ds_read_b64_tr_b16 v[204:205], v154 offset:0x1400
	ds_read_b64_tr_b16 v[206:207], v154 offset:0x1800
	ds_read_b64_tr_b16 v[208:209], v154 offset:0x1c00
	s_waitcnt lgkmcnt(0)
	s_nop 0
	v_mfma_f32_32x32x16_bf16 v[2:17], v[142:145], v[158:161], v[2:17]
	ds_read_b64_tr_b16 v[158:159], v154 offset:0x200
	ds_read_b64_tr_b16 v[160:161], v154 offset:0x600
	v_mfma_f32_32x32x16_bf16 v[2:17], v[106:109], v[162:165], v[2:17]
	ds_read_b64_tr_b16 v[162:163], v154 offset:0xa00
	ds_read_b64_tr_b16 v[164:165], v154 offset:0xe00
	v_mfma_f32_32x32x16_bf16 v[2:17], v[100:103], v[202:205], v[2:17]
	ds_read_b64_tr_b16 v[202:203], v154 offset:0x1200
	ds_read_b64_tr_b16 v[204:205], v154 offset:0x1600
	v_mfma_f32_32x32x16_bf16 v[2:17], v[110:113], v[206:209], v[2:17]
	ds_read_b64_tr_b16 v[206:207], v154 offset:0x1a00
	ds_read_b64_tr_b16 v[208:209], v154 offset:0x1e00
	s_waitcnt lgkmcnt(0)
	v_mfma_f32_32x32x16_bf16 v[18:33], v[142:145], v[158:161], v[18:33]
	v_mfma_f32_32x32x16_bf16 v[18:33], v[106:109], v[162:165], v[18:33]
	v_mfma_f32_32x32x16_bf16 v[18:33], v[100:103], v[202:205], v[18:33]
	v_add_u32_e32 v100, 0x9800, v201
	v_add_u32_e32 v102, 0x9880, v201
	ds_read2_b32 v[100:101], v100 offset1:1
	ds_read2_b32 v[102:103], v102 offset1:1
	s_waitcnt lgkmcnt(0)
	v_add_f32_e32 v100, v34, v100
	v_add_f32_e32 v101, v35, v101
	v_add_f32_e32 v34, v50, v102
	v_add_f32_e32 v35, v51, v103
	v_add_u32_e32 v50, 0x9808, v201
	v_add_u32_e32 v102, 0x9888, v201
	ds_read2_b32 v[50:51], v50 offset1:1
	ds_read2_b32 v[102:103], v102 offset1:1
	v_mfma_f32_32x32x16_bf16 v[18:33], v[110:113], v[206:209], v[18:33]
	s_waitcnt lgkmcnt(0)
	v_add_f32_e64 v50, v36, v50
	v_add_f32_e64 v51, v37, v51
	v_add_f32_e64 v36, v52, v102
	v_add_f32_e64 v37, v53, v103
	v_add_u32_e32 v52, 0x9820, v201
	v_add_u32_e32 v102, 0x98a0, v201
	ds_read2_b32 v[52:53], v52 offset1:1
	ds_read2_b32 v[102:103], v102 offset1:1
	s_waitcnt lgkmcnt(0)
	v_add_f32_e32 v52, v38, v52
	v_add_f32_e32 v53, v39, v53
	v_add_f32_e32 v38, v54, v102
	v_add_f32_e32 v39, v55, v103
	v_add_u32_e32 v54, 0x9828, v201
	v_add_u32_e32 v102, 0x98a8, v201
	ds_read2_b32 v[54:55], v54 offset1:1
	ds_read2_b32 v[102:103], v102 offset1:1
	s_waitcnt lgkmcnt(0)
	v_add_f32_e32 v54, v40, v54
	v_add_f32_e32 v55, v41, v55
	v_add_f32_e32 v40, v56, v102
	v_add_f32_e32 v41, v57, v103
	v_add_u32_e32 v56, 0x9840, v201
	v_add_u32_e32 v102, 0x98c0, v201
	ds_read2_b32 v[56:57], v56 offset1:1
	ds_read2_b32 v[102:103], v102 offset1:1
	s_waitcnt lgkmcnt(0)
	v_add_f32_e32 v56, v42, v56
	v_add_f32_e32 v57, v43, v57
	v_add_f32_e32 v42, v58, v102
	v_add_f32_e32 v43, v59, v103
	v_add_u32_e32 v58, 0x9848, v201
	v_add_u32_e32 v102, 0x98c8, v201
	ds_read2_b32 v[58:59], v58 offset1:1
	ds_read2_b32 v[102:103], v102 offset1:1
	s_waitcnt lgkmcnt(0)
	v_add_f32_e32 v58, v44, v58
	v_add_f32_e32 v59, v45, v59
	v_add_f32_e32 v44, v60, v102
	v_add_f32_e32 v45, v61, v103
	v_add_u32_e32 v60, 0x9860, v201
	v_add_u32_e32 v102, 0x98e0, v201
	ds_read2_b32 v[60:61], v60 offset1:1
	ds_read2_b32 v[102:103], v102 offset1:1
	s_waitcnt lgkmcnt(0)
	v_add_f32_e32 v60, v46, v60
	v_add_f32_e32 v61, v47, v61
	v_add_f32_e32 v46, v62, v102
	v_add_f32_e32 v47, v63, v103
	v_add_u32_e32 v62, 0x9868, v201
	v_add_u32_e32 v102, 0x98e8, v201
	ds_read2_b32 v[62:63], v62 offset1:1
	ds_read2_b32 v[102:103], v102 offset1:1
	s_waitcnt lgkmcnt(0)
	v_add_f32_e32 v62, v48, v62
	v_add_f32_e32 v63, v49, v63
	v_add_f32_e32 v48, v64, v102
	v_add_f32_e32 v49, v65, v103
	v_max_f32_e32 v64, v100, v101
	v_max3_f32 v64, v64, v50, v51
	v_max3_f32 v64, v64, v52, v53
	v_max3_f32 v64, v64, v54, v55
	v_max3_f32 v64, v64, v56, v57
	v_max3_f32 v64, v64, v58, v59
	v_max3_f32 v64, v64, v60, v61
	v_max3_f32 v64, v64, v62, v63
	v_max3_f32 v64, v64, v34, v35
	v_max3_f32 v64, v64, v36, v37
	v_max3_f32 v64, v64, v38, v39
	v_max3_f32 v64, v64, v40, v41
	v_max3_f32 v64, v64, v42, v43
	v_max3_f32 v64, v64, v44, v45
	v_max3_f32 v64, v64, v46, v47
	v_max3_f32 v64, v64, v48, v49
	v_mov_b32_e32 v65, v64
	s_nop 1
	v_permlane32_swap_b32_e32 v64, v65
	v_max_f32_e32 v65, v65, v65
	v_max_f32_e32 v64, v64, v64
	v_max_f32_e32 v64, v64, v65
	v_sub_f32_e32 v65, v64, v141
	v_cmp_ge_f32_e32 vcc, s0, v65
	s_cmp_lg_u64 vcc, exec
	s_cbranch_scc1 .LBB0_745
	v_mov_b32_e32 v64, v141

.LBB0_731:
	v_sub_f32_e32 v50, v50, v64
	v_sub_f32_e32 v51, v51, v64
	v_sub_f32_e32 v82, v100, v64
	v_sub_f32_e32 v83, v101, v64
	v_exp_f32_e32 v96, v50
	v_exp_f32_e32 v97, v51
	v_sub_f32_e32 v50, v52, v64
	v_sub_f32_e32 v51, v53, v64
	v_exp_f32_e32 v138, v82
	v_exp_f32_e32 v94, v50
	v_exp_f32_e32 v95, v51
	v_sub_f32_e32 v50, v54, v64
	v_sub_f32_e32 v51, v55, v64
	v_exp_f32_e32 v139, v83
	v_exp_f32_e32 v92, v50
	v_exp_f32_e32 v93, v51
	v_sub_f32_e32 v50, v56, v64
	v_sub_f32_e32 v51, v57, v64
	v_add_f32_e32 v1, v136, v1
	v_exp_f32_e32 v90, v50
	v_exp_f32_e32 v91, v51
	v_sub_f32_e32 v50, v58, v64
	v_sub_f32_e32 v51, v59, v64
	v_fmac_f32_e32 v1, 0, v191
	v_exp_f32_e32 v88, v50
	v_exp_f32_e32 v89, v51
	v_sub_f32_e32 v50, v60, v64
	v_sub_f32_e32 v51, v61, v64
	v_add_f32_e32 v136, v98, v99
	v_exp_f32_e32 v86, v50
	v_exp_f32_e32 v87, v51
	v_sub_f32_e32 v50, v62, v64
	v_sub_f32_e32 v51, v63, v64
	v_sub_f32_e32 v166, v34, v64
	v_exp_f32_e32 v84, v50
	v_exp_f32_e32 v85, v51
	v_sub_f32_e32 v167, v35, v64
	v_sub_f32_e32 v164, v36, v64
	v_sub_f32_e32 v165, v37, v64
	v_sub_f32_e32 v162, v38, v64
	v_sub_f32_e32 v163, v39, v64
	v_sub_f32_e32 v160, v40, v64
	v_sub_f32_e32 v161, v41, v64
	v_sub_f32_e32 v158, v42, v64
	v_sub_f32_e32 v159, v43, v64
	v_sub_f32_e32 v144, v44, v64
	v_sub_f32_e32 v145, v45, v64
	v_sub_f32_e32 v142, v46, v64
	v_sub_f32_e32 v143, v47, v64
	v_sub_f32_e32 v140, v48, v64
	v_sub_f32_e32 v141, v49, v64
	v_fmac_f32_e32 v136, v1, v137
	v_mov_b32_e32 v191, v65
	s_waitcnt lgkmcnt(0)
	s_barrier
.LBB0_732:
	s_or_b64 exec, exec, s[20:21]
	v_ashrrev_i32_e32 v127, 31, v126
	ds_read_b128 v[34:37], v196 offset:24576
	ds_read_b128 v[50:53], v196 offset:28672
	v_exp_f32_e32 v82, v160
	v_exp_f32_e32 v83, v161
	v_exp_f32_e32 v102, v142
	s_waitcnt lgkmcnt(1)
	v_mfma_f32_32x32x16_bf16 v[34:49], v[34:37], v[74:77], 0
	v_exp_f32_e32 v103, v143
	v_exp_f32_e32 v104, v140
	v_exp_f32_e32 v105, v141
	s_waitcnt lgkmcnt(0)
	v_mfma_f32_32x32x16_bf16 v[50:65], v[50:53], v[74:77], 0
	ds_read_b128 v[74:77], v195 offset:24576
	ds_read_b128 v[98:101], v195 offset:28672
	s_waitcnt lgkmcnt(1)
	v_mfma_f32_32x32x16_bf16 v[34:49], v[74:77], v[66:69], v[34:49]
	s_waitcnt lgkmcnt(0)
	v_mfma_f32_32x32x16_bf16 v[50:65], v[98:101], v[66:69], v[50:65]
	ds_read_b128 v[66:69], v194 offset:24576
	ds_read_b128 v[74:77], v194 offset:28672
	v_exp_f32_e32 v98, v158
	v_exp_f32_e32 v99, v159
	v_exp_f32_e32 v100, v144
	v_exp_f32_e32 v101, v145
	s_waitcnt lgkmcnt(1)
	v_mfma_f32_32x32x16_bf16 v[34:49], v[66:69], v[70:73], v[34:49]
	s_waitcnt lgkmcnt(0)
	v_mfma_f32_32x32x16_bf16 v[50:65], v[74:77], v[70:73], v[50:65]
	ds_read_b128 v[66:69], v193 offset:24576
	ds_read_b128 v[70:73], v193 offset:28672
	v_exp_f32_e32 v76, v166
	v_exp_f32_e32 v77, v167
	v_cvt_pk_bf16_f32 v74, v86, v87
	v_cvt_pk_bf16_f32 v75, v84, v85
	s_waitcnt lgkmcnt(1)
	v_mfma_f32_32x32x16_bf16 v[34:49], v[66:69], v[78:81], v[34:49]
	v_add_f32_e64 v66, v138, 0
	v_add_f32_e64 v67, v139, 0
	v_cvt_pk_bf16_f32 v68, v138, v139
	v_cvt_pk_bf16_f32 v69, v96, v97
	v_add_f32_e64 v66, v96, v66
	v_add_f32_e64 v67, v97, v67
	v_add_f32_e64 v66, v94, v66
	v_add_f32_e64 v67, v95, v67
	s_waitcnt lgkmcnt(0)
	v_mfma_f32_32x32x16_bf16 v[50:65], v[70:73], v[78:81], v[50:65]
	v_add_f32_e64 v66, v92, v66
	v_add_f32_e64 v67, v93, v67
	v_exp_f32_e32 v78, v164
	v_add_f32_e32 v66, v90, v66
	v_add_f32_e32 v67, v91, v67
	v_exp_f32_e32 v79, v165
	v_add_f32_e32 v66, v88, v66
	v_add_f32_e32 v67, v89, v67
	v_exp_f32_e32 v80, v162
	v_exp_f32_e32 v81, v163
	v_add_f32_e32 v66, v86, v66
	v_add_f32_e32 v67, v87, v67
	v_cvt_pk_bf16_f32 v70, v94, v95
	v_cvt_pk_bf16_f32 v71, v92, v93
	v_cvt_pk_bf16_f32 v72, v90, v91
	v_cvt_pk_bf16_f32 v73, v88, v89
	s_nop 0
	v_add_f32_e32 v66, v84, v66
	v_add_f32_e32 v67, v85, v67
	v_permlane32_swap_b32_e32 v68, v70
	v_add_f32_e32 v66, v76, v66
	v_add_f32_e32 v67, v77, v67
	v_permlane32_swap_b32_e32 v69, v71
	v_add_f32_e32 v66, v78, v66
	v_add_f32_e32 v67, v79, v67
	v_cvt_pk_bf16_f32 v76, v76, v77
	v_cvt_pk_bf16_f32 v77, v78, v79
	v_cvt_pk_bf16_f32 v78, v80, v81
	v_cvt_pk_bf16_f32 v79, v82, v83
	v_permlane32_swap_b32_e32 v72, v74
	v_add_f32_e32 v66, v80, v66
	v_add_f32_e32 v67, v81, v67
	v_cvt_pk_bf16_f32 v80, v98, v99
	v_cvt_pk_bf16_f32 v81, v100, v101
	v_permlane32_swap_b32_e32 v73, v75
	v_add_f32_e32 v66, v82, v66
	v_add_f32_e32 v67, v83, v67
	v_cvt_pk_bf16_f32 v82, v102, v103
	v_cvt_pk_bf16_f32 v83, v104, v105
	v_permlane32_swap_b32_e32 v76, v78
	v_add_f32_e32 v66, v98, v66
	v_add_f32_e32 v67, v99, v67
	v_permlane32_swap_b32_e32 v77, v79
	v_add_f32_e32 v66, v100, v66
	v_add_f32_e32 v67, v101, v67
	v_permlane32_swap_b32_e32 v80, v82
	v_add_f32_e32 v66, v102, v66
	v_add_f32_e32 v67, v103, v67
	v_permlane32_swap_b32_e32 v81, v83
	v_add_f32_e32 v66, v104, v66
	v_add_f32_e32 v67, v105, v67
	s_nop 0
	v_pk_add_f32 v[66:67], v[66:67], v[66:67] op_sel:[0,1] op_sel_hi:[1,0]
	s_nop 0
	v_mov_b32_e32 v1, v66
	s_nop 1
	v_permlane32_swap_b32_e32 v66, v1
	ds_read_b64_tr_b16 v[84:85], v169 offset:0
	ds_read_b64_tr_b16 v[86:87], v169 offset:0x400
	ds_read_b64_tr_b16 v[88:89], v169 offset:0x800
	ds_read_b64_tr_b16 v[90:91], v169 offset:0xc00
	ds_read_b64_tr_b16 v[92:93], v169 offset:0x1000
	ds_read_b64_tr_b16 v[94:95], v169 offset:0x1400
	ds_read_b64_tr_b16 v[96:97], v169 offset:0x1800
	ds_read_b64_tr_b16 v[98:99], v169 offset:0x1c00
	s_waitcnt lgkmcnt(0)
	s_nop 0
	v_mfma_f32_32x32x16_bf16 v[2:17], v[68:71], v[84:87], v[2:17]
	ds_read_b64_tr_b16 v[84:85], v169 offset:0x200
	ds_read_b64_tr_b16 v[86:87], v169 offset:0x600
	v_mfma_f32_32x32x16_bf16 v[2:17], v[72:75], v[88:91], v[2:17]
	ds_read_b64_tr_b16 v[88:89], v169 offset:0xa00
	ds_read_b64_tr_b16 v[90:91], v169 offset:0xe00
	v_mfma_f32_32x32x16_bf16 v[2:17], v[76:79], v[92:95], v[2:17]
	ds_read_b64_tr_b16 v[92:93], v169 offset:0x1200
	ds_read_b64_tr_b16 v[94:95], v169 offset:0x1600
	v_mfma_f32_32x32x16_bf16 v[2:17], v[80:83], v[96:99], v[2:17]
	ds_read_b64_tr_b16 v[96:97], v169 offset:0x1a00
	ds_read_b64_tr_b16 v[98:99], v169 offset:0x1e00
	s_waitcnt lgkmcnt(0)
	v_sub_u32_e32 v67, v149, v135
	v_mfma_f32_32x32x16_bf16 v[18:33], v[68:71], v[84:87], v[18:33]
	v_lshlrev_b32_e32 v67, 2, v67
	v_lshlrev_b32_e32 v68, 2, v192
	v_add3_u32 v67, v67, v68, v134
	v_add_u32_e32 v68, 0x9600, v67
	v_add_u32_e32 v70, 0x9680, v67
	ds_read2_b32 v[68:69], v68 offset1:1
	ds_read2_b32 v[70:71], v70 offset1:1
	v_mfma_f32_32x32x16_bf16 v[18:33], v[72:75], v[88:91], v[18:33]
	s_waitcnt lgkmcnt(1)
	v_add_f32_e64 v68, v34, v68
	v_add_f32_e64 v69, v35, v69
	s_waitcnt lgkmcnt(0)
	v_add_f32_e64 v34, v50, v70
	v_add_f32_e64 v35, v51, v71
	v_add_u32_e32 v50, 0x9608, v67
	v_add_u32_e32 v70, 0x9688, v67
	ds_read2_b32 v[50:51], v50 offset1:1
	ds_read2_b32 v[70:71], v70 offset1:1
	v_mfma_f32_32x32x16_bf16 v[18:33], v[76:79], v[92:95], v[18:33]
	s_waitcnt lgkmcnt(1)
	v_add_f32_e64 v50, v36, v50
	v_add_f32_e64 v51, v37, v51
	s_waitcnt lgkmcnt(0)
	v_add_f32_e64 v36, v52, v70
	v_add_f32_e64 v37, v53, v71
	v_add_u32_e32 v52, 0x9620, v67
	v_add_u32_e32 v70, 0x96a0, v67
	ds_read2_b32 v[52:53], v52 offset1:1
	ds_read2_b32 v[70:71], v70 offset1:1
	v_mfma_f32_32x32x16_bf16 v[18:33], v[80:83], v[96:99], v[18:33]
	s_waitcnt lgkmcnt(1)
	v_add_f32_e64 v52, v38, v52
	v_add_f32_e64 v53, v39, v53
	s_waitcnt lgkmcnt(0)
	v_add_f32_e64 v38, v54, v70
	v_add_f32_e64 v39, v55, v71
	v_add_u32_e32 v54, 0x9628, v67
	v_add_u32_e32 v70, 0x96a8, v67
	ds_read2_b32 v[54:55], v54 offset1:1
	ds_read2_b32 v[70:71], v70 offset1:1
	s_waitcnt lgkmcnt(1)
	v_add_f32_e32 v54, v40, v54
	v_add_f32_e32 v55, v41, v55
	s_waitcnt lgkmcnt(0)
	v_add_f32_e32 v40, v56, v70
	v_add_f32_e32 v41, v57, v71
	v_add_u32_e32 v56, 0x9640, v67
	v_add_u32_e32 v70, 0x96c0, v67
	ds_read2_b32 v[56:57], v56 offset1:1
	ds_read2_b32 v[70:71], v70 offset1:1
	s_waitcnt lgkmcnt(1)
	v_add_f32_e32 v56, v42, v56
	v_add_f32_e32 v57, v43, v57
	s_waitcnt lgkmcnt(0)
	v_add_f32_e32 v42, v58, v70
	v_add_f32_e32 v43, v59, v71
	v_add_u32_e32 v58, 0x9648, v67
	v_add_u32_e32 v70, 0x96c8, v67
	ds_read2_b32 v[58:59], v58 offset1:1
	ds_read2_b32 v[70:71], v70 offset1:1
	s_waitcnt lgkmcnt(1)
	v_add_f32_e32 v58, v44, v58
	v_add_f32_e32 v59, v45, v59
	s_waitcnt lgkmcnt(0)
	v_add_f32_e32 v44, v60, v70
	v_add_f32_e32 v45, v61, v71
	v_add_u32_e32 v60, 0x9660, v67
	v_add_u32_e32 v70, 0x96e0, v67
	ds_read2_b32 v[60:61], v60 offset1:1
	ds_read2_b32 v[70:71], v70 offset1:1
	s_waitcnt lgkmcnt(1)
	v_add_f32_e32 v60, v46, v60
	v_add_f32_e32 v61, v47, v61
	s_waitcnt lgkmcnt(0)
	v_add_f32_e32 v46, v62, v70
	v_add_f32_e32 v47, v63, v71
	v_add_u32_e32 v62, 0x9668, v67
	v_add_u32_e32 v67, 0x96e8, v67
	ds_read2_b32 v[62:63], v62 offset1:1
	ds_read2_b32 v[70:71], v67 offset1:1
	s_waitcnt lgkmcnt(1)
	v_add_f32_e32 v62, v48, v62
	v_add_f32_e32 v63, v49, v63
	s_waitcnt lgkmcnt(0)
	v_add_f32_e32 v48, v64, v70
	v_add_f32_e32 v49, v65, v71
	v_max_f32_e32 v64, v68, v69
	v_max3_f32 v64, v64, v50, v51
	v_max3_f32 v64, v64, v52, v53
	v_max3_f32 v64, v64, v54, v55
	v_max3_f32 v64, v64, v56, v57
	v_max3_f32 v64, v64, v58, v59
	v_max3_f32 v64, v64, v60, v61
	v_max3_f32 v64, v64, v62, v63
	v_max3_f32 v64, v64, v34, v35
	v_max3_f32 v64, v64, v36, v37
	v_max3_f32 v64, v64, v38, v39
	v_max3_f32 v64, v64, v40, v41
	v_max3_f32 v64, v64, v42, v43
	v_max3_f32 v64, v64, v44, v45
	v_max3_f32 v64, v64, v46, v47
	v_max3_f32 v64, v64, v48, v49
	v_mov_b32_e32 v65, v64
	s_nop 1
	v_permlane32_swap_b32_e32 v64, v65
	v_max_f32_e32 v65, v65, v65
	v_max_f32_e32 v64, v64, v64
	v_max_f32_e32 v64, v64, v65
	v_sub_f32_e32 v65, v64, v200
	v_cmp_ge_f32_e32 vcc, s0, v65
	s_cmp_lg_u64 vcc, exec
	s_cbranch_scc1 .LBB0_743
	v_mov_b32_e32 v64, v200

.LBB0_739:
	v_mov_b32_e32 v65, v64
	v_sub_f32_e32 v68, v68, v64
	v_sub_f32_e32 v69, v69, v64
	v_sub_f32_e32 v50, v50, v64
	v_sub_f32_e32 v51, v51, v64
	v_exp_f32_e32 v74, v68
	v_exp_f32_e32 v75, v69
	v_exp_f32_e32 v72, v50
	v_exp_f32_e32 v73, v51
	v_sub_f32_e32 v50, v52, v64
	v_sub_f32_e32 v51, v53, v64
	v_sub_f32_e32 v34, v34, v64
	v_sub_f32_e32 v35, v35, v65
	v_exp_f32_e32 v70, v50
	v_exp_f32_e32 v71, v51
	v_sub_f32_e32 v50, v54, v64
	v_sub_f32_e32 v51, v55, v64
	v_sub_f32_e32 v36, v36, v64
	v_sub_f32_e32 v37, v37, v65
	v_exp_f32_e32 v68, v50
	v_exp_f32_e32 v69, v51
	v_sub_f32_e32 v50, v56, v64
	v_sub_f32_e32 v51, v57, v64
	v_sub_f32_e32 v38, v38, v64
	v_sub_f32_e32 v39, v39, v65
	v_exp_f32_e32 v56, v50
	v_exp_f32_e32 v57, v51
	v_sub_f32_e32 v50, v58, v64
	v_sub_f32_e32 v51, v59, v64
	v_exp_f32_e32 v58, v34
	v_exp_f32_e32 v59, v35
	v_add_f32_e32 v34, 0, v74
	v_add_f32_e32 v35, 0, v75
	v_exp_f32_e32 v54, v50
	v_exp_f32_e32 v55, v51
	v_sub_f32_e32 v50, v60, v64
	v_sub_f32_e32 v51, v61, v64
	v_add_f32_e32 v34, v72, v34
	v_add_f32_e32 v35, v73, v35
	v_exp_f32_e32 v52, v50
	v_exp_f32_e32 v53, v51
	v_sub_f32_e32 v50, v62, v64
	v_sub_f32_e32 v51, v63, v64
	v_add_f32_e32 v34, v70, v34
	v_add_f32_e32 v35, v71, v35
	v_exp_f32_e32 v50, v50
	v_exp_f32_e32 v51, v51
	v_add_f32_e32 v34, v68, v34
	v_add_f32_e32 v35, v69, v35
	v_exp_f32_e32 v60, v36
	v_add_f32_e32 v34, v56, v34
	v_add_f32_e32 v35, v57, v35
	v_exp_f32_e32 v61, v37
	v_add_f32_e32 v34, v54, v34
	v_add_f32_e32 v35, v55, v35
	v_sub_f32_e32 v40, v40, v64
	v_sub_f32_e32 v41, v41, v65
	v_exp_f32_e32 v62, v38
	v_exp_f32_e32 v63, v39
	v_add_f32_e32 v34, v52, v34
	v_add_f32_e32 v35, v53, v35
	v_sub_f32_e32 v42, v42, v64
	v_sub_f32_e32 v43, v43, v65
	v_sub_f32_e32 v44, v44, v64
	v_sub_f32_e32 v45, v45, v65
	v_sub_f32_e32 v46, v46, v64
	v_sub_f32_e32 v47, v47, v65
	v_sub_f32_e32 v48, v48, v64
	v_sub_f32_e32 v49, v49, v65
	v_exp_f32_e32 v64, v40
	v_exp_f32_e32 v65, v41
	v_add_f32_e32 v34, v50, v34
	v_add_f32_e32 v35, v51, v35
	v_exp_f32_e32 v78, v42
	v_exp_f32_e32 v79, v43
	v_add_f32_e32 v34, v58, v34
	v_add_f32_e32 v35, v59, v35
	v_exp_f32_e32 v80, v44
	v_exp_f32_e32 v81, v45
	v_add_f32_e32 v34, v60, v34
	v_add_f32_e32 v35, v61, v35
	v_exp_f32_e32 v82, v46
	v_exp_f32_e32 v83, v47
	v_add_f32_e32 v34, v62, v34
	v_add_f32_e32 v35, v63, v35
	v_exp_f32_e32 v84, v48
	v_exp_f32_e32 v85, v49
	v_add_f32_e32 v34, v64, v34
	v_add_f32_e32 v35, v65, v35
	v_add_f32_e32 v66, v66, v1
	v_add_f32_e32 v34, v78, v34
	v_add_f32_e32 v35, v79, v35
	v_fmac_f32_e32 v66, v136, v191
	v_add_f32_e32 v34, v80, v34
	v_add_f32_e32 v35, v81, v35
	v_cvt_pk_bf16_f32 v36, v70, v71
	v_cvt_pk_bf16_f32 v37, v68, v69
	v_cvt_pk_bf16_f32 v38, v56, v57
	v_cvt_pk_bf16_f32 v39, v54, v55
	v_cvt_pk_bf16_f32 v40, v52, v53
	s_nop 0
	v_add_f32_e32 v34, v82, v34
	v_add_f32_e32 v35, v83, v35
	v_cvt_pk_bf16_f32 v41, v50, v51
	v_cvt_pk_bf16_f32 v42, v58, v59
	v_cvt_pk_bf16_f32 v43, v60, v61
	v_cvt_pk_bf16_f32 v44, v62, v63
	v_cvt_pk_bf16_f32 v45, v64, v65
	s_nop 0
	v_add_f32_e32 v34, v84, v34
	v_add_f32_e32 v35, v85, v35
	v_cvt_pk_bf16_f32 v46, v78, v79
	v_cvt_pk_bf16_f32 v47, v80, v81
	v_cvt_pk_bf16_f32 v48, v82, v83
	v_cvt_pk_bf16_f32 v49, v84, v85
	v_permlane32_swap_b32_e32 v38, v40
	v_pk_add_f32 v[34:35], v[34:35], v[34:35] op_sel:[0,1] op_sel_hi:[1,0]
	v_permlane32_swap_b32_e32 v39, v41
	v_mov_b32_e32 v1, v34
	s_nop 1
	v_permlane32_swap_b32_e32 v34, v1
	v_add_f32_e32 v1, v34, v1
	v_fmac_f32_e32 v1, v66, v76
	v_cvt_pk_bf16_f32 v34, v74, v75
	v_cvt_pk_bf16_f32 v35, v72, v73
	v_permlane32_swap_b32_e32 v42, v44
	v_permlane32_swap_b32_e32 v34, v36
	v_permlane32_swap_b32_e32 v35, v37
	v_permlane32_swap_b32_e32 v43, v45
	v_permlane32_swap_b32_e32 v46, v48
	v_permlane32_swap_b32_e32 v47, v49
	v_or_b32_e32 v66, 0x2000, v169
	ds_read_b64_tr_b16 v[50:51], v66 offset:0
	ds_read_b64_tr_b16 v[52:53], v66 offset:0x400
	ds_read_b64_tr_b16 v[54:55], v66 offset:0x800
	ds_read_b64_tr_b16 v[56:57], v66 offset:0xc00
	ds_read_b64_tr_b16 v[58:59], v66 offset:0x1000
	ds_read_b64_tr_b16 v[60:61], v66 offset:0x1400
	ds_read_b64_tr_b16 v[62:63], v66 offset:0x1800
	ds_read_b64_tr_b16 v[64:65], v66 offset:0x1c00
	s_waitcnt lgkmcnt(0)
	s_nop 0
	v_mfma_f32_32x32x16_bf16 v[2:17], v[34:37], v[50:53], v[2:17]
	ds_read_b64_tr_b16 v[50:51], v66 offset:0x200
	ds_read_b64_tr_b16 v[52:53], v66 offset:0x600
	v_mfma_f32_32x32x16_bf16 v[2:17], v[38:41], v[54:57], v[2:17]
	ds_read_b64_tr_b16 v[54:55], v66 offset:0xa00
	ds_read_b64_tr_b16 v[56:57], v66 offset:0xe00
	v_mfma_f32_32x32x16_bf16 v[2:17], v[42:45], v[58:61], v[2:17]
	ds_read_b64_tr_b16 v[58:59], v66 offset:0x1200
	ds_read_b64_tr_b16 v[60:61], v66 offset:0x1600
	v_mfma_f32_32x32x16_bf16 v[2:17], v[46:49], v[62:65], v[2:17]
	ds_read_b64_tr_b16 v[62:63], v66 offset:0x1a00
	ds_read_b64_tr_b16 v[64:65], v66 offset:0x1e00
	s_waitcnt lgkmcnt(0)
	v_mfma_f32_32x32x16_bf16 v[18:33], v[34:37], v[50:53], v[18:33]
	v_cmp_gt_u32_e32 vcc, 32, v129
	v_mfma_f32_32x32x16_bf16 v[18:33], v[38:41], v[54:57], v[18:33]
	v_mfma_f32_32x32x16_bf16 v[18:33], v[42:45], v[58:61], v[18:33]
	v_mfma_f32_32x32x16_bf16 v[18:33], v[46:49], v[62:65], v[18:33]
	s_and_saveexec_b64 s[4:5], vcc
	v_lshl_add_u32 v34, v135, 2, v168
	ds_write_b32 v34, v1 offset:32768
	s_or_b64 exec, exec, s[4:5]
	s_waitcnt lgkmcnt(0)
	s_and_saveexec_b64 s[8:9], vcc
	s_cbranch_execz .LBB0_713
	v_log_f32_e32 v1, v1
	v_lshl_add_u64 v[34:35], v[124:125], 4, v[122:123]
	v_lshlrev_b64 v[36:37], 8, v[126:127]
	v_lshl_add_u64 v[34:35], v[34:35], 0, v[36:37]
	v_add_f32_e32 v1, v67, v1
	flat_store_dword v[34:35], v1
	s_branch .LBB0_713

.LBB0_838:
	flat_load_dwordx4 v[22:25], v[16:17]
	flat_load_dwordx4 v[26:29], v[14:15]
	flat_load_dwordx4 v[30:33], v[12:13]
	v_add_u32_e32 v10, 32, v10
	s_mov_b64 s[4:5], 0x4000
	v_lshl_add_u64 v[12:13], v[12:13], 0, s[50:51]
	v_lshl_add_u64 v[14:15], v[14:15], 0, s[4:5]
	s_waitcnt vmcnt(0) lgkmcnt(0)
	v_lshlrev_b32_e32 v36, 16, v22
	v_lshlrev_b32_e32 v34, 16, v26
	v_lshlrev_b32_e32 v35, 16, v27
	v_lshlrev_b32_e32 v37, 16, v23
	v_and_b32_e32 v26, 0xffff0000, v26
	v_and_b32_e32 v22, 0xffff0000, v22
	v_and_b32_e32 v27, 0xffff0000, v27
	v_and_b32_e32 v23, 0xffff0000, v23
	v_add_f32_e32 v34, v36, v34
	v_add_f32_e32 v35, v37, v35
	v_lshlrev_b32_e32 v37, 16, v28
	v_lshlrev_b32_e32 v39, 16, v24
	v_lshlrev_b32_e32 v36, 16, v29
	v_lshlrev_b32_e32 v38, 16, v25
	v_add_f32_e32 v22, v22, v26
	v_add_f32_e32 v23, v23, v27
	v_pk_mul_f32 v[26:27], v[34:35], v[34:35]
	v_and_b32_e32 v41, 0xffff0000, v28
	v_and_b32_e32 v43, 0xffff0000, v24
	v_and_b32_e32 v40, 0xffff0000, v29
	v_and_b32_e32 v42, 0xffff0000, v25
	v_add_f32_e32 v24, v38, v36
	v_add_f32_e32 v25, v39, v37
	v_pk_fma_f32 v[26:27], v[22:23], v[22:23], v[26:27]
	v_add_f32_e32 v28, v42, v40
	v_add_f32_e32 v29, v43, v41
	v_pk_mul_f32 v[36:37], v[24:25], v[24:25]
	v_add_f32_e32 v11, v26, v27
	v_pk_fma_f32 v[36:37], v[28:29], v[28:29], v[36:37]
	v_lshlrev_b32_e32 v26, 16, v30
	v_add_f32_e32 v11, v37, v11
	v_add_f32_e32 v11, v36, v11
	ds_bpermute_b32 v21, v18, v11
	v_mul_f32_e32 v26, 0xbfb8aa3b, v26
	v_exp_f32_e32 v26, v26
	v_lshlrev_b32_e32 v27, 16, v31
	v_mul_f32_e32 v27, 0xbfb8aa3b, v27
	s_waitcnt lgkmcnt(0)
	v_add_f32_e32 v11, v11, v21
	ds_bpermute_b32 v21, v19, v11
	v_add_f32_e32 v26, 1.0, v26
	v_rcp_f32_e32 v26, v26
	v_exp_f32_e32 v27, v27
	s_waitcnt lgkmcnt(0)
	v_add_f32_e32 v11, v11, v21
	ds_bpermute_b32 v21, v20, v11
	v_add_f32_e32 v27, 1.0, v27
	v_rcp_f32_e32 v27, v27
	s_waitcnt lgkmcnt(0)
	v_add_f32_e32 v11, v11, v21
	v_fmamk_f32 v11, v11, 0x3c800000, v172
	v_cmp_gt_f32_e32 vcc, s58, v11
	v_mul_f32_e32 v21, 0x4b800000, v11
	s_nop 0
	v_cndmask_b32_e32 v11, v11, v21, vcc
	v_rsq_f32_e32 v11, v11
	s_nop 0
	v_mul_f32_e32 v21, 0x45800000, v11
	v_cndmask_b32_e32 v11, v11, v21, vcc
	v_mul_f32_e32 v21, v34, v11
	v_mul_f32_e32 v21, v2, v21
	v_mul_f32_e32 v21, v26, v21
	v_and_b32_e32 v26, 0xffff0000, v30
	v_mul_f32_e32 v26, 0xbfb8aa3b, v26
	v_exp_f32_e32 v26, v26
	v_mul_f32_e32 v22, v22, v11
	v_mul_f32_e32 v22, v3, v22
	v_mul_f32_e32 v23, v23, v11
	v_add_f32_e32 v26, 1.0, v26
	v_rcp_f32_e32 v26, v26
	v_mul_f32_e32 v23, v5, v23
	v_mul_f32_e32 v25, v25, v11
	v_mul_f32_e32 v25, v6, v25
	v_mul_f32_e32 v22, v26, v22
	v_mul_f32_e32 v26, v35, v11
	v_mul_f32_e32 v26, v4, v26
	v_mul_f32_e32 v26, v27, v26
	v_and_b32_e32 v27, 0xffff0000, v31
	v_mul_f32_e32 v27, 0xbfb8aa3b, v27
	v_exp_f32_e32 v27, v27
	v_mul_f32_e32 v24, v24, v11
	v_mul_f32_e32 v24, v8, v24
	v_cmp_ge_i32_e32 vcc, v10, v1
	v_add_f32_e32 v27, 1.0, v27
	v_rcp_f32_e32 v27, v27
	v_cvt_pk_bf16_f32 v22, v21, v22
	s_or_b64 s[12:13], vcc, s[12:13]
	v_mul_f32_e32 v23, v27, v23
	v_lshlrev_b32_e32 v27, 16, v32
	v_mul_f32_e32 v27, 0xbfb8aa3b, v27
	v_exp_f32_e32 v27, v27
	v_cvt_pk_bf16_f32 v23, v26, v23
	s_nop 0
	v_add_f32_e32 v27, 1.0, v27
	v_rcp_f32_e32 v27, v27
	s_nop 0
	v_mul_f32_e32 v25, v27, v25
	v_mul_f32_e32 v27, v29, v11
	v_and_b32_e32 v29, 0xffff0000, v32
	v_mul_f32_e32 v29, 0xbfb8aa3b, v29
	v_exp_f32_e32 v29, v29
	v_mul_f32_e32 v27, v7, v27
	v_mul_f32_e32 v11, v28, v11
	v_mul_f32_e32 v11, v9, v11
	v_add_f32_e32 v29, 1.0, v29
	v_rcp_f32_e32 v29, v29
	s_nop 0
	v_mul_f32_e32 v27, v29, v27
	v_lshlrev_b32_e32 v29, 16, v33
	v_mul_f32_e32 v29, 0xbfb8aa3b, v29
	v_exp_f32_e32 v29, v29
	s_nop 0
	v_add_f32_e32 v29, 1.0, v29
	v_rcp_f32_e32 v29, v29
	s_nop 0
	v_mul_f32_e32 v29, v29, v24
	v_and_b32_e32 v24, 0xffff0000, v33
	v_mul_f32_e32 v24, 0xbfb8aa3b, v24
	v_exp_f32_e32 v24, v24
	s_nop 0
	v_add_f32_e32 v24, 1.0, v24
	v_rcp_f32_e32 v24, v24
	s_nop 0
	v_mul_f32_e32 v11, v24, v11
	v_cvt_pk_bf16_f32 v24, v25, v27
	v_cvt_pk_bf16_f32 v25, v29, v11
	flat_store_dwordx4 v[16:17], v[22:25]
	v_lshl_add_u64 v[16:17], v[16:17], 0, s[48:49]
	s_andn2_b64 exec, exec, s[12:13]
	s_cbranch_execnz .LBB0_838
	s_branch .LBB0_585
